# v17: dil run-start spurious waits removed + item-head counts, hg1/hg2 lb prefetched one item ahead, hg2 gains at item head, rt1/rt2 heads leave output stores in flight
# baseline (speedup 1.0000x reference)
; #define LAS __attribute__((address_space(3)))
; #define SP_BEGIN() unsigned long long sp0_ = 0; if (PROBE_MASK >> 16) sp0_ = __builtin_amdgcn_s_memrealtime();
; __device__ __forceinline__ void da_blk_load(const Ctx& X, const bf16* H, const DaRun& I, int kb, DaBlk& R) {
;     const bool ok = kb >= 0 && kb < I.nbper; const size_t mb = (size_t)I.b * SEQ; const int kcol = I.qcol + 512, vcol = I.qcol + 1024;
; #pragma unroll
;     for (int p = 0; p < 2; ++p) { const int r = (X.tid >> 4) + 32 * p, c8 = X.tid & 15; R.kw[p] = (v4u){0u, 0u, 0u, 0u}; R.vw[p] = (v4u){0u, 0u, 0u, 0u};
;         if (ok) { const size_t mr = mb + (size_t)(I.rho * (SEQ / I.dil) + 64 * kb + r); R.kw[p] = *(const v4u*)hptr(H, mr, kcol + 8 * c8); R.vw[p] = *(const v4u*)hptr(H, mr, vcol + 8 * c8); } }
; }
; __device__ __forceinline__ void dil_run(const Ctx& X, bf16* H, int l, int run) {
;     const DaRun I = da_decode(run); const int b = I.b, g = I.g, slot = I.slot, dil = I.dil, rho = I.rho, qcol = I.qcol, Ls = SEQ / I.dil;
;     const lptr KN = X.lds + DA_KN, VT = X.lds + DA_VT, P = X.lds + DA_P; LAS float* bias = (LAS float*)(X.lds + DA_BIAS); LAS float* mx = (LAS float*)(X.lds + DA_MX); LAS float* lx = (LAS float*)(X.lds + DA_LX);
;     const float* qg = X.in(11) + l * 128; const float* kg = X.in(12) + l * 128; asm volatile("" : "+s"(qg), "+s"(kg));
;     const f32x4 kg0 = *(const f32x4*)(kg + 8 * (X.tid & 15)), kg1 = *(const f32x4*)(kg + 8 * (X.tid & 15) + 4);
;     LAS float* qgl = mx;
;     if (X.tid < 128) qgl[X.tid] = qg[X.tid];
;     const int fr = X.lane & 15, fq = X.lane >> 4, qb = X.wave & 3, kh = X.wave >> 2; const int qi = 16 * qb + fr;
;     const float mshift = ((const float*)(X.ws + WS_TAB) + 2 * 4 * 768 + 3 * 4 * 132)[l];
;     SP_BEGIN()
;     {
;         DaBlk B0, B1, B2; da_blk_load(X, H, I, I.nb0 - 1, B0); da_blk_load(X, H, I, I.nb0, B1); da_blk_load(X, H, I, I.nb0 + 1, B2);
;         if (X.tid < 256) bias[X.tid] = (X.tid >= 63 && X.tid <= 191) ? ((const float*)(X.ws + WS_TAB) + 2 * 4 * 768)[(g * 4 + slot) * 132 + X.tid - 63] - mshift : -1e30f;
;         da_blk_stage(X, kg0, kg1, I.nb0 - 1, B0); da_blk_stage(X, kg0, kg1, I.nb0, B1); da_blk_stage(X, kg0, kg1, I.nb0 + 1, B2);
;     }
;     v4u qw_[2][4]; da_q_load(X, H, I, I.nb0, qw_);
.LBB0_254:
	s_mov_b64 s[4:5], s[18:19]
	s_mov_b64 s[0:1], s[38:39]
	v_lshlrev_b32_e32 v158, 2, v110
	s_nop 0
	v_lshl_add_u64 v[6:7], s[4:5], 0, v[158:159]
	global_load_dwordx4 v[2:5], v[6:7], off
	s_nop 0
	global_load_dwordx4 v[6:9], v[6:7], off offset:16
	s_and_saveexec_b64 s[4:5], s[40:41]
	s_cbranch_execz .LBB0_256
	v_lshl_add_u64 v[10:11], v[108:109], 2, s[0:1]
	global_load_dword v251, v[10:11], off
.LBB0_256:
	s_or_b64 exec, exec, s[4:5]
	global_load_dword v155, v159, s[24:25]
	s_mul_hi_i32 s0, s63, 0x2aaaaaab
	s_lshr_b32 s1, s0, 31
	s_ashr_i32 s0, s0, 6
	s_add_i32 s12, s0, s1
	s_mul_i32 s0, s12, 0x180
	s_sub_i32 s0, s63, s0
	s_lshr_b32 s4, s0, 24
	s_and_b32 s4, s4, 0x7f
	s_add_i32 s4, s0, s4
	s_sext_i32_i16 s5, s4
	s_and_b32 s4, s4, 0xff80
	s_add_i32 s13, s0, 0x7f
	s_and_b32 s1, s0, 0xffffff80
	s_sub_i32 s0, s0, s4
	s_bfe_i32 s4, s0, 0x80000
	s_bfe_u32 s4, s4, 0x5000a
	s_add_i32 s4, s0, s4
	s_ashr_i32 s14, s5, 7
	s_bfe_i32 s5, s4, 0x80000
	s_sext_i32_i16 s52, s5
	s_and_b32 s4, s4, 0xffe0
	s_sub_i32 s15, s0, s4
	s_ashr_i32 s54, s52, 5
	s_cmpk_eq_i32 s1, 0x80
	s_cselect_b64 s[4:5], -1, 0
	s_and_b64 s[0:1], s[4:5], exec
	s_cselect_b32 s22, 2, 4
	s_cmpk_lt_u32 s13, 0xff
	s_cselect_b64 s[16:17], -1, 0
	s_and_b64 s[0:1], s[16:17], exec
	s_cselect_b32 s68, 0, s22
	s_lshr_b32 s13, 32, s68
	s_sext_i32_i8 s0, s15
	v_cvt_f32_ubyte0_e32 v11, s13
	v_cvt_f32_i32_e32 v10, s0
	v_rcp_iflag_f32_e32 v12, v11
	s_ashr_i32 s1, s0, 30
	s_lshr_b32 s69, 0x80, s68
	s_or_b32 s22, s1, 1
	v_mul_f32_e32 v12, v10, v12
	v_trunc_f32_e32 v12, v12
	v_fma_f32 v10, -v12, v11, v10
	v_cvt_i32_f32_e32 v12, v12
	v_cmp_ge_f32_e64 s[0:1], |v10|, v11
	s_and_b64 s[0:1], s[0:1], exec
	s_cselect_b32 s0, s22, 0
	v_readfirstlane_b32 s1, v12
	s_add_i32 s0, s1, s0
	s_sext_i32_i8 s70, s0
	s_mul_i32 s0, s0, s13
	s_sub_i32 s22, s15, s0
	s_sext_i32_i8 s48, s22
	s_and_b32 s0, s22, 1
	s_lshl_b32 s50, s48, 2
	s_cmp_eq_u32 s0, 0
	s_cselect_b64 s[0:1], -1, 0
	s_and_b64 s[30:31], s[0:1], exec
	s_cselect_b32 s49, 0, 3
	s_mul_i32 s13, s14, 0x600
	s_lshl_b32 s23, s54, 7
	s_or_b32 s15, s49, s50
	s_add_i32 s51, s13, s23
	s_addk_i32 s51, 0x1800
	s_add_i32 s55, s15, -1
	s_cmp_gt_i32 s15, 0
	s_cselect_b64 s[30:31], -1, 0
	s_cmp_le_i32 s15, s69
	s_cselect_b64 s[56:57], -1, 0
	s_and_b64 s[30:31], s[30:31], s[56:57]
	s_andn2_b64 vcc, exec, s[30:31]
	v_lshlrev_b32_e32 v158, 1, v110
	s_cbranch_vccnz .LBB0_258
	s_ashr_i32 s13, s12, 31
	s_lshl_b64 s[30:31], s[12:13], 21
	s_lshl_b32 s13, s55, 6
	s_add_i32 s23, s51, 0x400
	s_add_i32 s34, s51, 0x200
	s_and_b64 s[56:57], s[4:5], exec
	s_cselect_b32 s53, 11, 9
	s_and_b64 s[56:57], s[16:17], exec
	s_cselect_b32 s53, 13, s53
	s_lshl_b32 s53, s70, s53
	s_lshr_b32 s34, s34, 7
	s_add_i32 s13, s13, s53
	s_lshl_b64 s[56:57], s[34:35], 22
	s_add_u32 s56, s36, s56
	v_add_u32_e32 v10, s13, v129
	s_addc_u32 s57, s37, s57
	s_lshr_b32 s34, s23, 7
	v_ashrrev_i32_e32 v11, 31, v10
	s_lshl_b64 s[58:59], s[34:35], 22
	v_lshlrev_b64 v[12:13], 8, v[10:11]
	s_add_u32 s58, s36, s58
	v_add_u32_e32 v10, 32, v10
	v_lshl_add_u64 v[12:13], v[12:13], 0, s[30:31]
	s_addc_u32 s59, s37, s59
	v_ashrrev_i32_e32 v11, 31, v10
	v_lshl_add_u64 v[14:15], s[56:57], 0, v[12:13]
	v_lshl_add_u64 v[12:13], s[58:59], 0, v[12:13]
	v_lshlrev_b64 v[10:11], 8, v[10:11]
	v_lshl_add_u64 v[14:15], v[14:15], 0, v[158:159]
	v_lshl_add_u64 v[12:13], v[12:13], 0, v[158:159]
	v_lshl_add_u64 v[10:11], v[10:11], 0, s[30:31]
	global_load_dwordx4 v[54:57], v[14:15], off
	global_load_dwordx4 v[50:53], v[12:13], off
	v_lshl_add_u64 v[12:13], s[56:57], 0, v[10:11]
	v_lshl_add_u64 v[12:13], v[12:13], 0, v[158:159]
	v_lshl_add_u64 v[10:11], s[58:59], 0, v[10:11]
	v_lshl_add_u64 v[10:11], v[10:11], 0, v[158:159]
	global_load_dwordx4 v[46:49], v[12:13], off
	global_load_dwordx4 v[38:41], v[10:11], off
	s_branch .LBB0_259

; #define LAS __attribute__((address_space(3)))
; __device__ __forceinline__ float bf2f(unsigned h) { return __uint_as_float(h << 16); }
; __device__ __forceinline__ unsigned pk2(float lo, float hi) { return pg8::cvt_pk_bf16(lo, hi); }
; __device__ __forceinline__ void da_blk_stage(const Ctx& X, const f32x4 g0, const f32x4 g1, int kb, const DaBlk& R) {
;     const lptr KN = X.lds + DA_KN, VT = X.lds + DA_VT; const int slot = ((kb % 3) + 3) % 3;
; #pragma unroll
;     for (int p = 0; p < 2; ++p) { const int row = slot * 64 + (X.tid >> 4) + 32 * p, c8 = X.tid & 15; const v4u kw = R.kw[p], vw = R.vw[p];
;         float f[8]; f[0] = bf2f(kw.x & 0xffffu); f[1] = bf2f(kw.x >> 16); f[2] = bf2f(kw.y & 0xffffu); f[3] = bf2f(kw.y >> 16); f[4] = bf2f(kw.z & 0xffffu); f[5] = bf2f(kw.z >> 16); f[6] = bf2f(kw.w & 0xffffu); f[7] = bf2f(kw.w >> 16);
;         float s = 0.f;
; #pragma unroll
;         for (int e = 0; e < 8; ++e) s += f[e] * f[e];
;         s += __shfl_xor(s, 1); s += __shfl_xor(s, 2); s += __shfl_xor(s, 4); s += __shfl_xor(s, 8);
;         const float sc = __builtin_amdgcn_rsqf(s * (1.0f / 128.0f) + EPS);
;         v4u o; o.x = pk2(f[0] * sc * g0.x, f[1] * sc * g0.y); o.y = pk2(f[2] * sc * g0.z, f[3] * sc * g0.w); o.z = pk2(f[4] * sc * g1.x, f[5] * sc * g1.y); o.w = pk2(f[6] * sc * g1.z, f[7] * sc * g1.w);
;         *(LAS v4u*)(KN + row * 272 + c8 * 16) = o;
;         LAS unsigned short* d = (LAS unsigned short*)(VT + (8 * c8) * 400 + (row ^ (8 * (c8 & 7))) * 2);
;         d[0] = (unsigned short)vw.x; d[200] = (unsigned short)(vw.x >> 16); d[400] = (unsigned short)vw.y; d[600] = (unsigned short)(vw.y >> 16);
;         d[800] = (unsigned short)vw.z; d[1000] = (unsigned short)(vw.z >> 16); d[1200] = (unsigned short)vw.w; d[1400] = (unsigned short)(vw.w >> 16); }
; }
.LBB0_268:
	s_or_b64 exec, exec, s[22:23]
	s_waitcnt vmcnt(0)
	s_and_saveexec_b64 s[98:99], s[40:41]
	ds_write_b32 v111, v251
	s_or_b64 exec, exec, s[98:99]
	v_lshlrev_b32_e32 v70, 16, v54
	v_and_b32_e32 v71, 0xffff0000, v54
	v_lshlrev_b32_e32 v66, 16, v55
	v_and_b32_e32 v67, 0xffff0000, v55
	v_pk_mul_f32 v[54:55], v[70:71], v[70:71]
	v_pk_mul_f32 v[68:69], v[66:67], v[66:67]
	v_add_f32_e32 v54, v54, v55
	v_lshlrev_b32_e32 v64, 16, v56
	v_and_b32_e32 v65, 0xffff0000, v56
	v_add_f32_e32 v54, v68, v54
	v_and_b32_e32 v58, 64, v195
	v_lshlrev_b32_e32 v60, 16, v57
	v_and_b32_e32 v61, 0xffff0000, v57
	v_pk_mul_f32 v[56:57], v[64:65], v[64:65]
	v_add_f32_e32 v54, v69, v54
	v_xor_b32_e32 v59, 1, v195
	v_add_u32_e32 v58, 64, v58
	v_add_f32_e32 v54, v56, v54
	v_cmp_lt_i32_e32 vcc, v59, v58
	v_pk_mul_f32 v[62:63], v[60:61], v[60:61]
	v_add_f32_e32 v54, v57, v54
	v_cndmask_b32_e32 v59, v195, v59, vcc
	v_add_f32_e32 v54, v62, v54
	v_lshlrev_b32_e32 v156, 2, v59
	v_add_f32_e32 v54, v63, v54
	v_xor_b32_e32 v59, 2, v195
	v_cmp_lt_i32_e32 vcc, v59, v58
	s_lshr_b32 s52, s52, 5
	s_and_b64 s[0:1], s[0:1], exec
	v_cndmask_b32_e32 v59, v195, v59, vcc
	v_lshlrev_b32_e32 v157, 2, v59
	s_waitcnt lgkmcnt(0)
	s_nop 1
	v_add_f32_dpp v54, v54, v54 quad_perm:[1,0,3,2] row_mask:0xf bank_mask:0xf
	v_xor_b32_e32 v59, 4, v195
	v_cmp_lt_i32_e32 vcc, v59, v58
	s_cselect_b32 s22, 1, -1
	s_and_b64 s[0:1], s[4:5], exec
	v_cndmask_b32_e32 v59, v195, v59, vcc
	v_lshlrev_b32_e32 v158, 2, v59
	s_waitcnt lgkmcnt(0)
	s_nop 1
	v_add_f32_dpp v54, v54, v54 quad_perm:[2,3,0,1] row_mask:0xf bank_mask:0xf
	v_xor_b32_e32 v59, 8, v195
	v_cmp_lt_i32_e32 vcc, v59, v58
	s_movk_i32 s0, 0x800
	s_cselect_b32 s13, s0, 0x200
	v_cndmask_b32_e32 v59, v195, v59, vcc
	v_lshlrev_b32_e32 v161, 2, v59
	s_waitcnt lgkmcnt(0)
	s_nop 1
	v_add_f32_dpp v54, v54, v54 row_half_mirror row_mask:0xf bank_mask:0xf
	s_and_b64 s[0:1], s[16:17], exec
	s_mul_hi_i32 s0, s55, 0x55555556
	s_cselect_b32 s23, 0x2000, s13
	s_lshr_b32 s1, s0, 31
	s_waitcnt lgkmcnt(0)
	s_nop 1
	v_add_f32_dpp v54, v54, v54 row_mirror row_mask:0xf bank_mask:0xf
	v_fmamk_f32 v54, v54, 0x3c000000, v1
	s_add_i32 s0, s0, s1
	v_rsq_f32_e32 v62, v54
	s_mul_i32 s0, s0, 3
	s_sub_i32 s0, s55, s0
	s_lshl_b32 s1, s0, 6
	s_add_i32 s13, s1, 0xc0
	v_pk_mul_f32 v[54:55], v[62:63], v[70:71] op_sel_hi:[0,1]
	v_pk_mul_f32 v[56:57], v[62:63], v[66:67] op_sel_hi:[0,1]
	s_cmp_lt_i32 s0, 0
	v_pk_mul_f32 v[54:55], v[2:3], v[54:55]
	v_pk_mul_f32 v[56:57], v[4:5], v[56:57]
	s_cselect_b32 s0, s13, s1
	v_cvt_pk_bf16_f32 v54, v54, v55
	v_cvt_pk_bf16_f32 v55, v56, v57
	v_pk_mul_f32 v[56:57], v[62:63], v[64:65] op_sel_hi:[0,1]
	v_pk_mul_f32 v[60:61], v[62:63], v[60:61] op_sel_hi:[0,1]
	v_add_u32_e32 v59, s0, v129
	v_pk_mul_f32 v[56:57], v[6:7], v[56:57]
	v_pk_mul_f32 v[60:61], v[8:9], v[60:61]
	v_cvt_pk_bf16_f32 v56, v56, v57
	v_cvt_pk_bf16_f32 v57, v60, v61
	v_mad_u64_u32 v[60:61], s[0:1], v59, s27, v[112:113]
	v_lshlrev_b32_e32 v64, 16, v46
	v_and_b32_e32 v65, 0xffff0000, v46
	ds_write_b128 v60, v[54:57]
	v_xor_b32_e32 v54, v59, v132
	v_lshlrev_b32_e32 v56, 16, v47
	v_and_b32_e32 v57, 0xffff0000, v47
	v_pk_mul_f32 v[46:47], v[64:65], v[64:65]
	v_lshl_add_u32 v54, v54, 1, v131
	v_pk_mul_f32 v[62:63], v[56:57], v[56:57]
	v_add_f32_e32 v46, v46, v47
	ds_write_b16 v54, v50 offset:52224
	ds_write_b16_d16_hi v54, v50 offset:52624
	ds_write_b16 v54, v51 offset:53024
	ds_write_b16_d16_hi v54, v51 offset:53424
	ds_write_b16 v54, v52 offset:53824
	ds_write_b16_d16_hi v54, v52 offset:54224
	ds_write_b16 v54, v53 offset:54624
	ds_write_b16_d16_hi v54, v53 offset:55024
	v_lshlrev_b32_e32 v54, 16, v48
	v_and_b32_e32 v55, 0xffff0000, v48
	v_add_f32_e32 v46, v62, v46
	v_lshlrev_b32_e32 v50, 16, v49
	v_and_b32_e32 v51, 0xffff0000, v49
	v_pk_mul_f32 v[48:49], v[54:55], v[54:55]
	v_add_f32_e32 v46, v63, v46
	v_add_f32_e32 v46, v48, v46
	v_pk_mul_f32 v[52:53], v[50:51], v[50:51]
	v_add_f32_e32 v46, v49, v46
	v_add_f32_e32 v46, v52, v46
	v_add_f32_e32 v46, v53, v46
	v_add_u32_e32 v59, 32, v59
	s_mul_hi_i32 s0, s15, 0x55555556
	s_lshr_b32 s1, s0, 31
	s_add_i32 s0, s0, s1
	s_waitcnt lgkmcnt(0)
	s_nop 1
	v_add_f32_dpp v46, v46, v46 quad_perm:[1,0,3,2] row_mask:0xf bank_mask:0xf
	s_mul_i32 s0, s0, 3
	s_sub_i32 s0, s15, s0
	s_lshl_b32 s1, s0, 6
	s_add_i32 s13, s1, 0xc0
	s_waitcnt lgkmcnt(0)
	s_nop 1
	v_add_f32_dpp v46, v46, v46 quad_perm:[2,3,0,1] row_mask:0xf bank_mask:0xf
	s_cmp_lt_i32 s0, 0
	s_cselect_b32 s0, s13, s1
	v_mov_b32_e32 v119, v159
	s_mov_b32 s30, 0
	s_waitcnt lgkmcnt(0)
	s_nop 1
	v_add_f32_dpp v46, v46, v46 row_half_mirror row_mask:0xf bank_mask:0xf
	s_mov_b32 s31, 4
	s_waitcnt lgkmcnt(0)
	s_nop 1
	v_add_f32_dpp v46, v46, v46 row_mirror row_mask:0xf bank_mask:0xf
	v_fmamk_f32 v46, v46, 0x3c000000, v1
	v_rsq_f32_e32 v52, v46
	s_nop 0
	v_pk_mul_f32 v[46:47], v[52:53], v[64:65] op_sel_hi:[0,1]
	v_pk_mul_f32 v[48:49], v[52:53], v[56:57] op_sel_hi:[0,1]
	v_pk_mul_f32 v[46:47], v[2:3], v[46:47]
	v_pk_mul_f32 v[48:49], v[4:5], v[48:49]
	v_cvt_pk_bf16_f32 v46, v46, v47
	v_cvt_pk_bf16_f32 v47, v48, v49
	v_pk_mul_f32 v[48:49], v[52:53], v[54:55] op_sel_hi:[0,1]
	v_pk_mul_f32 v[50:51], v[52:53], v[50:51] op_sel_hi:[0,1]
	v_pk_mul_f32 v[48:49], v[6:7], v[48:49]
	v_pk_mul_f32 v[50:51], v[8:9], v[50:51]
	v_cvt_pk_bf16_f32 v48, v48, v49
	v_cvt_pk_bf16_f32 v49, v50, v51
	v_lshlrev_b32_e32 v52, 16, v42
	v_and_b32_e32 v53, 0xffff0000, v42
	ds_write_b128 v60, v[46:49] offset:8704
	v_xor_b32_e32 v46, v59, v132
	v_lshlrev_b32_e32 v48, 16, v43
	v_and_b32_e32 v49, 0xffff0000, v43
	v_pk_mul_f32 v[42:43], v[52:53], v[52:53]
	v_lshl_add_u32 v46, v46, 1, v131
	v_pk_mul_f32 v[50:51], v[48:49], v[48:49]
	v_add_f32_e32 v42, v42, v43
	ds_write_b16 v46, v38 offset:52224
	ds_write_b16_d16_hi v46, v38 offset:52624
	ds_write_b16 v46, v39 offset:53024
	ds_write_b16_d16_hi v46, v39 offset:53424
	ds_write_b16 v46, v40 offset:53824
	ds_write_b16_d16_hi v46, v40 offset:54224
	ds_write_b16 v46, v41 offset:54624
	ds_write_b16_d16_hi v46, v41 offset:55024
	v_lshlrev_b32_e32 v40, 16, v44
	v_and_b32_e32 v41, 0xffff0000, v44
	v_add_f32_e32 v42, v50, v42
	v_lshlrev_b32_e32 v46, 16, v45
	v_and_b32_e32 v47, 0xffff0000, v45
	v_pk_mul_f32 v[44:45], v[40:41], v[40:41]
	v_add_f32_e32 v42, v51, v42
	v_add_f32_e32 v42, v44, v42
	v_pk_mul_f32 v[38:39], v[46:47], v[46:47]
	v_add_f32_e32 v42, v45, v42
	v_add_f32_e32 v38, v38, v42
	v_add_f32_e32 v38, v39, v38
	v_add_u32_e32 v54, s0, v129
	s_waitcnt lgkmcnt(0)
; #define LAS __attribute__((address_space(3)))
; __device__ __forceinline__ float bf2f(unsigned h) { return __uint_as_float(h << 16); }
; __device__ __forceinline__ unsigned pk2(float lo, float hi) { return pg8::cvt_pk_bf16(lo, hi); }
; __device__ __forceinline__ void da_blk_stage(const Ctx& X, const f32x4 g0, const f32x4 g1, int kb, const DaBlk& R) {
;     const lptr KN = X.lds + DA_KN, VT = X.lds + DA_VT; const int slot = ((kb % 3) + 3) % 3;
; #pragma unroll
;     for (int p = 0; p < 2; ++p) { const int row = slot * 64 + (X.tid >> 4) + 32 * p, c8 = X.tid & 15; const v4u kw = R.kw[p], vw = R.vw[p];
;         float f[8]; f[0] = bf2f(kw.x & 0xffffu); f[1] = bf2f(kw.x >> 16); f[2] = bf2f(kw.y & 0xffffu); f[3] = bf2f(kw.y >> 16); f[4] = bf2f(kw.z & 0xffffu); f[5] = bf2f(kw.z >> 16); f[6] = bf2f(kw.w & 0xffffu); f[7] = bf2f(kw.w >> 16);
;         float s = 0.f;
; #pragma unroll
;         for (int e = 0; e < 8; ++e) s += f[e] * f[e];
;         s += __shfl_xor(s, 1); s += __shfl_xor(s, 2); s += __shfl_xor(s, 4); s += __shfl_xor(s, 8);
;         const float sc = __builtin_amdgcn_rsqf(s * (1.0f / 128.0f) + EPS);
;         v4u o; o.x = pk2(f[0] * sc * g0.x, f[1] * sc * g0.y); o.y = pk2(f[2] * sc * g0.z, f[3] * sc * g0.w); o.z = pk2(f[4] * sc * g1.x, f[5] * sc * g1.y); o.w = pk2(f[6] * sc * g1.z, f[7] * sc * g1.w);
;         *(LAS v4u*)(KN + row * 272 + c8 * 16) = o;
;         LAS unsigned short* d = (LAS unsigned short*)(VT + (8 * c8) * 400 + (row ^ (8 * (c8 & 7))) * 2);
;         d[0] = (unsigned short)vw.x; d[200] = (unsigned short)(vw.x >> 16); d[400] = (unsigned short)vw.y; d[600] = (unsigned short)(vw.y >> 16);
;         d[800] = (unsigned short)vw.z; d[1000] = (unsigned short)(vw.z >> 16); d[1200] = (unsigned short)vw.w; d[1400] = (unsigned short)(vw.w >> 16); }
; }
	s_nop 1
	v_add_f32_dpp v38, v38, v38 quad_perm:[1,0,3,2] row_mask:0xf bank_mask:0xf
	s_waitcnt lgkmcnt(0)
	s_nop 1
	v_add_f32_dpp v38, v38, v38 quad_perm:[2,3,0,1] row_mask:0xf bank_mask:0xf
	s_waitcnt lgkmcnt(0)
	s_nop 1
	v_add_f32_dpp v38, v38, v38 row_half_mirror row_mask:0xf bank_mask:0xf
	s_waitcnt lgkmcnt(0)
	s_nop 1
	v_add_f32_dpp v38, v38, v38 row_mirror row_mask:0xf bank_mask:0xf
	v_fmamk_f32 v38, v38, 0x3c000000, v1
	v_rsq_f32_e32 v42, v38
	s_nop 0
	v_pk_mul_f32 v[38:39], v[42:43], v[52:53] op_sel_hi:[0,1]
	v_pk_mul_f32 v[44:45], v[42:43], v[48:49] op_sel_hi:[0,1]
	v_pk_mul_f32 v[40:41], v[42:43], v[40:41] op_sel_hi:[0,1]
	v_pk_mul_f32 v[42:43], v[42:43], v[46:47] op_sel_hi:[0,1]
	v_pk_mul_f32 v[38:39], v[2:3], v[38:39]
	v_pk_mul_f32 v[44:45], v[4:5], v[44:45]
	v_pk_mul_f32 v[40:41], v[6:7], v[40:41]
	v_pk_mul_f32 v[42:43], v[8:9], v[42:43]
	v_cvt_pk_bf16_f32 v38, v38, v39
	v_cvt_pk_bf16_f32 v39, v44, v45
	v_cvt_pk_bf16_f32 v40, v40, v41
	v_cvt_pk_bf16_f32 v41, v42, v43
	v_mad_u64_u32 v[42:43], s[0:1], v54, s27, v[112:113]
	v_lshlrev_b32_e32 v46, 16, v30
	v_and_b32_e32 v47, 0xffff0000, v30
	ds_write_b128 v42, v[38:41]
	v_xor_b32_e32 v38, v54, v132
	v_lshlrev_b32_e32 v40, 16, v31
	v_and_b32_e32 v41, 0xffff0000, v31
	v_pk_mul_f32 v[30:31], v[46:47], v[46:47]
	v_lshl_add_u32 v38, v38, 1, v131
	v_pk_mul_f32 v[44:45], v[40:41], v[40:41]
	v_add_f32_e32 v30, v30, v31
	ds_write_b16 v38, v34 offset:52224
	ds_write_b16_d16_hi v38, v34 offset:52624
	ds_write_b16 v38, v35 offset:53024
	ds_write_b16_d16_hi v38, v35 offset:53424
	ds_write_b16 v38, v36 offset:53824
	ds_write_b16_d16_hi v38, v36 offset:54224
	ds_write_b16 v38, v37 offset:54624
	ds_write_b16_d16_hi v38, v37 offset:55024
	v_lshlrev_b32_e32 v38, 16, v32
	v_and_b32_e32 v39, 0xffff0000, v32
	v_add_f32_e32 v30, v44, v30
	v_lshlrev_b32_e32 v34, 16, v33
	v_and_b32_e32 v35, 0xffff0000, v33
	v_pk_mul_f32 v[32:33], v[38:39], v[38:39]
	v_add_f32_e32 v30, v45, v30
	v_add_f32_e32 v30, v32, v30
	v_pk_mul_f32 v[36:37], v[34:35], v[34:35]
	v_add_f32_e32 v30, v33, v30
	v_add_f32_e32 v30, v36, v30
	v_add_f32_e32 v30, v37, v30
	v_add_u32_e32 v43, 32, v54
	s_mul_hi_i32 s0, s53, 0x55555556
	s_lshr_b32 s1, s0, 31
	s_add_i32 s0, s0, s1
	s_waitcnt lgkmcnt(0)
	s_nop 1
	v_add_f32_dpp v30, v30, v30 quad_perm:[1,0,3,2] row_mask:0xf bank_mask:0xf
	s_mul_i32 s0, s0, 3
	s_sub_i32 s0, s53, s0
	s_lshl_b32 s1, s0, 6
	s_add_i32 s13, s1, 0xc0
	s_waitcnt lgkmcnt(0)
	s_nop 1
	v_add_f32_dpp v30, v30, v30 quad_perm:[2,3,0,1] row_mask:0xf bank_mask:0xf
	s_cmp_lt_i32 s0, 0
	s_cselect_b32 s0, s13, s1
	s_ashr_i32 s13, s12, 31
	s_waitcnt lgkmcnt(0)
	s_nop 1
	v_add_f32_dpp v30, v30, v30 row_half_mirror row_mask:0xf bank_mask:0xf
	s_waitcnt lgkmcnt(0)
	s_nop 1
	v_add_f32_dpp v30, v30, v30 row_mirror row_mask:0xf bank_mask:0xf
	v_fmamk_f32 v30, v30, 0x3c000000, v1
	v_rsq_f32_e32 v36, v30
	s_nop 0
	v_pk_mul_f32 v[30:31], v[36:37], v[46:47] op_sel_hi:[0,1]
	v_pk_mul_f32 v[32:33], v[36:37], v[40:41] op_sel_hi:[0,1]
	v_pk_mul_f32 v[30:31], v[2:3], v[30:31]
	v_pk_mul_f32 v[32:33], v[4:5], v[32:33]
	v_cvt_pk_bf16_f32 v30, v30, v31
	v_cvt_pk_bf16_f32 v31, v32, v33
	v_pk_mul_f32 v[32:33], v[36:37], v[38:39] op_sel_hi:[0,1]
	v_pk_mul_f32 v[34:35], v[36:37], v[34:35] op_sel_hi:[0,1]
	v_pk_mul_f32 v[32:33], v[6:7], v[32:33]
	v_pk_mul_f32 v[34:35], v[8:9], v[34:35]
	v_cvt_pk_bf16_f32 v32, v32, v33
	v_cvt_pk_bf16_f32 v33, v34, v35
	v_lshlrev_b32_e32 v36, 16, v26
	v_and_b32_e32 v37, 0xffff0000, v26
	ds_write_b128 v42, v[30:33] offset:8704
	v_xor_b32_e32 v30, v43, v132
	v_lshlrev_b32_e32 v32, 16, v27
	v_and_b32_e32 v33, 0xffff0000, v27
	v_pk_mul_f32 v[26:27], v[36:37], v[36:37]
	v_lshl_add_u32 v30, v30, 1, v131
	v_pk_mul_f32 v[34:35], v[32:33], v[32:33]
	v_add_f32_e32 v26, v26, v27
	ds_write_b16 v30, v22 offset:52224
	ds_write_b16_d16_hi v30, v22 offset:52624
	ds_write_b16 v30, v23 offset:53024
	ds_write_b16_d16_hi v30, v23 offset:53424
	ds_write_b16 v30, v24 offset:53824
	ds_write_b16_d16_hi v30, v24 offset:54224
	ds_write_b16 v30, v25 offset:54624
	ds_write_b16_d16_hi v30, v25 offset:55024
	v_lshlrev_b32_e32 v24, 16, v28
	v_and_b32_e32 v25, 0xffff0000, v28
	v_add_f32_e32 v26, v34, v26
	v_lshlrev_b32_e32 v30, 16, v29
	v_and_b32_e32 v31, 0xffff0000, v29
	v_pk_mul_f32 v[28:29], v[24:25], v[24:25]
	v_add_f32_e32 v26, v35, v26
	v_add_f32_e32 v26, v28, v26
	v_pk_mul_f32 v[22:23], v[30:31], v[30:31]
	v_add_f32_e32 v26, v29, v26
	v_add_f32_e32 v22, v22, v26
	v_add_f32_e32 v22, v23, v22
	v_add_u32_e32 v38, s0, v129
	s_and_b64 s[0:1], s[4:5], exec
	s_cselect_b32 s4, 11, 9
	s_and_b64 s[0:1], s[16:17], exec
	s_waitcnt lgkmcnt(0)
	s_nop 1
	v_add_f32_dpp v22, v22, v22 quad_perm:[1,0,3,2] row_mask:0xf bank_mask:0xf
	v_xor_b32_e32 v42, 16, v195
	v_cmp_lt_i32_e32 vcc, v42, v58
	s_waitcnt lgkmcnt(0)
	s_nop 1
	v_add_f32_dpp v22, v22, v22 quad_perm:[2,3,0,1] row_mask:0xf bank_mask:0xf
	v_cndmask_b32_e32 v42, v195, v42, vcc
	v_lshlrev_b32_e32 v166, 2, v42
	v_xor_b32_e32 v42, 32, v195
	v_cmp_lt_i32_e32 vcc, v42, v58
	s_waitcnt lgkmcnt(0)
	s_nop 1
	v_add_f32_dpp v22, v22, v22 row_half_mirror row_mask:0xf bank_mask:0xf
	v_cndmask_b32_e32 v42, v195, v42, vcc
	v_lshlrev_b32_e32 v167, 2, v42
	v_mov_b32_e32 v42, s52
	v_bfe_i32 v42, v42, 0, 8
	s_waitcnt lgkmcnt(0)
; #define LAS __attribute__((address_space(3)))
; #define BAR_LDS() do { asm volatile("s_waitcnt lgkmcnt(0)" ::: "memory"); __builtin_amdgcn_s_barrier(); asm volatile("" ::: "memory"); } while (0)
; __device__ __forceinline__ void da_blk_stage(const Ctx& X, const f32x4 g0, const f32x4 g1, int kb, const DaBlk& R) {
;     const lptr KN = X.lds + DA_KN, VT = X.lds + DA_VT; const int slot = ((kb % 3) + 3) % 3;
; #pragma unroll
;     for (int p = 0; p < 2; ++p) { const int row = slot * 64 + (X.tid >> 4) + 32 * p, c8 = X.tid & 15; const v4u kw = R.kw[p], vw = R.vw[p];
;         float f[8]; f[0] = bf2f(kw.x & 0xffffu); f[1] = bf2f(kw.x >> 16); f[2] = bf2f(kw.y & 0xffffu); f[3] = bf2f(kw.y >> 16); f[4] = bf2f(kw.z & 0xffffu); f[5] = bf2f(kw.z >> 16); f[6] = bf2f(kw.w & 0xffffu); f[7] = bf2f(kw.w >> 16);
;         float s = 0.f;
; #pragma unroll
;         for (int e = 0; e < 8; ++e) s += f[e] * f[e];
;         s += __shfl_xor(s, 1); s += __shfl_xor(s, 2); s += __shfl_xor(s, 4); s += __shfl_xor(s, 8);
;         const float sc = __builtin_amdgcn_rsqf(s * (1.0f / 128.0f) + EPS);
;         v4u o; o.x = pk2(f[0] * sc * g0.x, f[1] * sc * g0.y); o.y = pk2(f[2] * sc * g0.z, f[3] * sc * g0.w); o.z = pk2(f[4] * sc * g1.x, f[5] * sc * g1.y); o.w = pk2(f[6] * sc * g1.z, f[7] * sc * g1.w);
;         *(LAS v4u*)(KN + row * 272 + c8 * 16) = o;
;         LAS unsigned short* d = (LAS unsigned short*)(VT + (8 * c8) * 400 + (row ^ (8 * (c8 & 7))) * 2);
;         d[0] = (unsigned short)vw.x; d[200] = (unsigned short)(vw.x >> 16); d[400] = (unsigned short)vw.y; d[600] = (unsigned short)(vw.y >> 16);
;         d[800] = (unsigned short)vw.z; d[1000] = (unsigned short)(vw.z >> 16); d[1200] = (unsigned short)vw.w; d[1400] = (unsigned short)(vw.w >> 16); }
; }
; __device__ __forceinline__ void da_q_load(const Ctx& X, const bf16* H, const DaRun& I, int nb, v4u (&qw)[2][4]) {
;     const int fr = X.lane & 15, fq = X.lane >> 4, qh = X.wave & 1;
; #pragma unroll
;     for (int u = 0; u < 2; ++u) { const size_t m = (size_t)I.b * SEQ + (size_t)(I.rho * (SEQ / I.dil) + 64 * nb + 32 * qh + 16 * u + fr);
; #pragma unroll
;         for (int ks = 0; ks < 4; ++ks) qw[u][ks] = *(const v4u*)hptr(H, m, I.qcol + 32 * ks + 8 * fq); }
; }
; __device__ __forceinline__ void dil_run(const Ctx& X, bf16* H, int l, int run) {
;     ...
;     v4u qw_[2][4]; da_q_load(X, H, I, I.nb0, qw_);
;     BAR_LDS();
	s_nop 1
	v_add_f32_dpp v22, v22, v22 row_mirror row_mask:0xf bank_mask:0xf
	v_fmamk_f32 v22, v22, 0x3c000000, v1
	v_rsq_f32_e32 v26, v22
	v_ashrrev_i32_e32 v43, 31, v42
	v_lshlrev_b64 v[42:43], 2, v[42:43]
	v_lshl_add_u64 v[124:125], s[28:29], 0, v[42:43]
	v_pk_mul_f32 v[22:23], v[26:27], v[36:37] op_sel_hi:[0,1]
	v_pk_mul_f32 v[28:29], v[26:27], v[32:33] op_sel_hi:[0,1]
	v_pk_mul_f32 v[24:25], v[26:27], v[24:25] op_sel_hi:[0,1]
	v_pk_mul_f32 v[26:27], v[26:27], v[30:31] op_sel_hi:[0,1]
	v_pk_mul_f32 v[22:23], v[2:3], v[22:23]
	v_pk_mul_f32 v[28:29], v[4:5], v[28:29]
	v_pk_mul_f32 v[24:25], v[6:7], v[24:25]
	v_pk_mul_f32 v[26:27], v[8:9], v[26:27]
	v_cvt_pk_bf16_f32 v22, v22, v23
	v_cvt_pk_bf16_f32 v23, v28, v29
	v_cvt_pk_bf16_f32 v24, v24, v25
	v_cvt_pk_bf16_f32 v25, v26, v27
	v_mad_u64_u32 v[26:27], s[0:1], v38, s27, v[112:113]
	v_lshlrev_b32_e32 v30, 16, v10
	v_and_b32_e32 v31, 0xffff0000, v10
	ds_write_b128 v26, v[22:25]
	v_xor_b32_e32 v22, v38, v132
	v_lshlrev_b32_e32 v24, 16, v11
	v_and_b32_e32 v25, 0xffff0000, v11
	v_pk_mul_f32 v[10:11], v[30:31], v[30:31]
	v_lshl_add_u32 v22, v22, 1, v131
	v_pk_mul_f32 v[28:29], v[24:25], v[24:25]
	v_add_f32_e32 v10, v10, v11
	ds_write_b16 v22, v18 offset:52224
	ds_write_b16_d16_hi v22, v18 offset:52624
	ds_write_b16 v22, v19 offset:53024
	ds_write_b16_d16_hi v22, v19 offset:53424
	ds_write_b16 v22, v20 offset:53824
	ds_write_b16_d16_hi v22, v20 offset:54224
	ds_write_b16 v22, v21 offset:54624
	ds_write_b16_d16_hi v22, v21 offset:55024
	v_lshlrev_b32_e32 v22, 16, v12
	v_and_b32_e32 v23, 0xffff0000, v12
	v_add_f32_e32 v10, v28, v10
	v_lshlrev_b32_e32 v18, 16, v13
	v_and_b32_e32 v19, 0xffff0000, v13
	v_pk_mul_f32 v[12:13], v[22:23], v[22:23]
	v_add_f32_e32 v10, v29, v10
	v_add_f32_e32 v10, v12, v10
	v_pk_mul_f32 v[20:21], v[18:19], v[18:19]
	v_add_f32_e32 v10, v13, v10
	v_add_f32_e32 v10, v20, v10
	v_add_f32_e32 v10, v21, v10
	v_add_u32_e32 v27, 32, v38
	s_cselect_b32 s0, 13, s4
	s_lshl_b32 s53, s70, s0
	s_lshl_b64 s[4:5], s[12:13], 21
	s_waitcnt lgkmcnt(0)
	s_nop 1
	v_add_f32_dpp v10, v10, v10 quad_perm:[1,0,3,2] row_mask:0xf bank_mask:0xf
	s_add_u32 s0, s36, s4
	s_addc_u32 s1, s37, s5
	s_lshr_b32 s34, s51, 7
	s_lshl_b64 s[16:17], s[34:35], 22
	s_waitcnt lgkmcnt(0)
	s_nop 1
	v_add_f32_dpp v10, v10, v10 quad_perm:[2,3,0,1] row_mask:0xf bank_mask:0xf
	s_add_i32 s34, s51, 0x200
	s_lshr_b32 s34, s34, 7
	s_lshl_b64 s[54:55], s[34:35], 22
	s_lshl_b32 s71, s22, 1
	s_waitcnt lgkmcnt(0)
	s_nop 1
	v_add_f32_dpp v10, v10, v10 row_half_mirror row_mask:0xf bank_mask:0xf
	s_lshl_b64 s[58:59], s[12:13], 13
	v_add_u32_e32 v42, s53, v129
	v_lshl_add_u64 v[120:121], v[116:117], 0, s[54:55]
	s_waitcnt lgkmcnt(0)
	s_nop 1
	v_add_f32_dpp v10, v10, v10 row_mirror row_mask:0xf bank_mask:0xf
	v_fmamk_f32 v10, v10, 0x3c000000, v1
	v_rsq_f32_e32 v20, v10
	s_nop 0
	v_pk_mul_f32 v[10:11], v[20:21], v[30:31] op_sel_hi:[0,1]
	v_pk_mul_f32 v[12:13], v[20:21], v[24:25] op_sel_hi:[0,1]
	v_pk_mul_f32 v[10:11], v[2:3], v[10:11]
	v_pk_mul_f32 v[12:13], v[4:5], v[12:13]
	v_cvt_pk_bf16_f32 v10, v10, v11
	v_cvt_pk_bf16_f32 v11, v12, v13
	v_pk_mul_f32 v[12:13], v[20:21], v[22:23] op_sel_hi:[0,1]
	v_pk_mul_f32 v[18:19], v[20:21], v[18:19] op_sel_hi:[0,1]
	v_pk_mul_f32 v[12:13], v[6:7], v[12:13]
	v_pk_mul_f32 v[18:19], v[8:9], v[18:19]
	v_cvt_pk_bf16_f32 v12, v12, v13
	v_cvt_pk_bf16_f32 v13, v18, v19
	ds_write_b128 v26, v[10:13] offset:8704
	v_xor_b32_e32 v10, v27, v132
	v_lshl_add_u32 v10, v10, 1, v131
	ds_write_b16 v10, v14 offset:52224
	ds_write_b16_d16_hi v10, v14 offset:52624
	ds_write_b16 v10, v15 offset:53024
	ds_write_b16_d16_hi v10, v15 offset:53424
	ds_write_b16 v10, v16 offset:53824
	ds_write_b16_d16_hi v10, v16 offset:54224
	ds_write_b16 v10, v17 offset:54624
	ds_write_b16_d16_hi v10, v17 offset:55024
	v_lshl_or_b32 v10, s15, 6, v133
	v_add_u32_e32 v26, s53, v10
	v_ashrrev_i32_e32 v27, 31, v26
	v_lshlrev_b64 v[10:11], 8, v[26:27]
	v_add_u32_e32 v26, 16, v26
	v_ashrrev_i32_e32 v27, 31, v26
	v_lshlrev_b64 v[26:27], 8, v[26:27]
	v_lshl_add_u64 v[10:11], s[0:1], 0, v[10:11]
	v_lshl_add_u64 v[26:27], s[0:1], 0, v[26:27]
	v_lshl_add_u64 v[10:11], v[10:11], 0, s[16:17]
	v_lshl_add_u64 v[26:27], v[26:27], 0, s[16:17]
	v_lshl_add_u64 v[22:23], v[10:11], 0, v[118:119]
	v_lshl_add_u64 v[38:39], v[26:27], 0, v[118:119]
	global_load_dwordx4 v[10:13], v[22:23], off
	global_load_dwordx4 v[14:17], v[22:23], off offset:64
	global_load_dwordx4 v[18:21], v[22:23], off offset:128
	s_nop 0
	global_load_dwordx4 v[22:25], v[22:23], off offset:192
	s_nop 0
	global_load_dwordx4 v[26:29], v[38:39], off
	global_load_dwordx4 v[30:33], v[38:39], off offset:64
	global_load_dwordx4 v[34:37], v[38:39], off offset:128
	s_nop 0
	global_load_dwordx4 v[38:41], v[38:39], off offset:192
	s_add_i32 s15, s51, 0x400
	s_lshr_b32 s34, s15, 7
	s_ashr_i32 s15, s14, 31
	s_lshl_b64 s[56:57], s[34:35], 22
	s_add_i32 s34, s69, -1
	s_lshl_b64 s[14:15], s[14:15], 14
	s_add_u32 s12, s14, s58
	s_addc_u32 s13, s15, s59
	s_lshl_b32 s14, s51, 7
	s_and_b32 s14, s14, 0x1fc000
	s_add_u32 s14, s58, s14
	s_addc_u32 s15, s59, 0
	s_add_u32 s0, s0, s16
	s_addc_u32 s1, s1, s17
	s_add_i32 s75, s49, s50
	v_lshl_add_u64 v[126:127], s[0:1], 0, v[118:119]
	s_add_i32 s0, s75, s22
	s_lshl_b32 s0, s0, 6
	s_add_i32 s0, s0, s53
	v_or_b32_e32 v119, s0, v133
	s_add_i32 s0, s75, s71
	v_lshl_add_u32 v168, s0, 6, v42
	s_lshl_b32 s0, s48, 8
	s_lshl_b32 s1, s49, 6
	s_waitcnt lgkmcnt(0)
	s_barrier
	s_or_b32 s77, s0, s1
	s_add_i32 s0, s77, s53
	v_lshl_add_u64 v[122:123], v[116:117], 0, s[56:57]
	s_lshl_b32 s76, s22, 6
	v_or_b32_e32 v169, s77, v128
	v_add_u32_e32 v170, s0, v148
	v_add_u32_e32 v171, s77, v42
	v_add_u32_e32 v172, s77, v134
	s_add_i32 s78, s77, s21
	s_waitcnt vmcnt(0)
	s_branch .LBB0_270

; #define LAS __attribute__((address_space(3)))
; __device__ __forceinline__ float bf2f(unsigned h) { return __uint_as_float(h << 16); }
; __device__ __forceinline__ unsigned pk2(float lo, float hi) { return pg8::cvt_pk_bf16(lo, hi); }
; __device__ __forceinline__ void dil_run(const Ctx& X, bf16* H, int l, int run) {
;     ...
;         for (int u = 0; u < 2; ++u) {
;             float s = 0.f;
; #pragma unroll
;             for (int ks = 0; ks < 4; ++ks) { const v4u qw = qw_[u][ks];
;                 const float a0 = bf2f(qw.x & 0xffffu), a1 = bf2f(qw.x >> 16), a2 = bf2f(qw.y & 0xffffu), a3 = bf2f(qw.y >> 16), a4 = bf2f(qw.z & 0xffffu), a5 = bf2f(qw.z >> 16), a6 = bf2f(qw.w & 0xffffu), a7 = bf2f(qw.w >> 16);
;                 s += (a0 * a0 + a1 * a1) + (a2 * a2 + a3 * a3) + (a4 * a4 + a5 * a5) + (a6 * a6 + a7 * a7); }
;             s += __shfl_xor(s, 16); s += __shfl_xor(s, 32);
;             const float sc = (0.08838834764831845f * 1.4426950408889634f) * __builtin_amdgcn_rsqf(s * (1.0f / 128.0f) + EPS);
; #pragma unroll
;             for (int ks = 0; ks < 4; ++ks) { const v4u qw = qw_[u][ks]; const f32x4 g0 = *(const LAS f32x4*)(qgl + 32 * ks + 8 * fq), g1 = *(const LAS f32x4*)(qgl + 32 * ks + 8 * fq + 4);
;                 v4u o; o.x = pk2(bf2f(qw.x & 0xffffu) * sc * g0.x, bf2f(qw.x >> 16) * sc * g0.y); o.y = pk2(bf2f(qw.y & 0xffffu) * sc * g0.z, bf2f(qw.y >> 16) * sc * g0.w);
;                 o.z = pk2(bf2f(qw.z & 0xffffu) * sc * g1.x, bf2f(qw.z >> 16) * sc * g1.y); o.w = pk2(bf2f(qw.w & 0xffffu) * sc * g1.z, bf2f(qw.w >> 16) * sc * g1.w);
;                 qf[u][ks] = __builtin_bit_cast(bf16x8, o); }
.LBB0_270:
	s_waitcnt vmcnt(8)
	v_and_b32_e32 v177, 0xffff0000, v17
	v_and_b32_e32 v179, 0xffff0000, v16
	v_lshlrev_b32_e32 v176, 16, v17
	v_lshlrev_b32_e32 v178, 16, v16
	v_mov_b32_e32 v182, v177
	v_mov_b32_e32 v183, v179
	v_mov_b32_e32 v180, v176
	v_mov_b32_e32 v181, v178
	v_pk_mul_f32 v[182:183], v[182:183], v[182:183]
	v_and_b32_e32 v185, 0xffff0000, v14
	v_pk_fma_f32 v[180:181], v[180:181], v[180:181], v[182:183]
	v_and_b32_e32 v183, 0xffff0000, v15
	v_lshlrev_b32_e32 v182, 16, v15
	v_lshlrev_b32_e32 v184, 16, v14
	v_mov_b32_e32 v188, v185
	v_mov_b32_e32 v189, v183
	v_mov_b32_e32 v186, v184
	v_mov_b32_e32 v187, v182
	v_pk_mul_f32 v[188:189], v[188:189], v[188:189]
	v_and_b32_e32 v201, 0xffff0000, v10
	v_pk_fma_f32 v[186:187], v[186:187], v[186:187], v[188:189]
	v_and_b32_e32 v189, 0xffff0000, v12
	v_pk_add_f32 v[186:187], v[186:187], v[186:187] op_sel:[0,1] op_sel_hi:[1,0]
	v_lshlrev_b32_e32 v188, 16, v12
	v_pk_add_f32 v[186:187], v[180:181], v[186:187] op_sel:[1,0] op_sel_hi:[0,1]
	v_pk_add_f32 v[180:181], v[180:181], v[186:187]
	v_and_b32_e32 v187, 0xffff0000, v13
	v_lshlrev_b32_e32 v186, 16, v13
	v_mov_b32_e32 v192, v187
	v_mov_b32_e32 v193, v189
	v_mov_b32_e32 v190, v186
	v_mov_b32_e32 v191, v188
	v_pk_mul_f32 v[192:193], v[192:193], v[192:193]
	v_lshlrev_b32_e32 v200, 16, v10
	v_pk_fma_f32 v[190:191], v[190:191], v[190:191], v[192:193]
	v_and_b32_e32 v193, 0xffff0000, v11
	v_lshlrev_b32_e32 v192, 16, v11
	v_mov_b32_e32 v204, v201
	v_mov_b32_e32 v205, v193
	s_waitcnt vmcnt(7)
	v_lshlrev_b32_e32 v174, 16, v19
	v_mov_b32_e32 v202, v200
	v_mov_b32_e32 v203, v192
	v_pk_mul_f32 v[204:205], v[204:205], v[204:205]
	v_and_b32_e32 v175, 0xffff0000, v19
	v_mul_f32_e32 v62, v174, v174
	v_pk_fma_f32 v[202:203], v[202:203], v[202:203], v[204:205]
	s_waitcnt vmcnt(6)
	v_and_b32_e32 v73, 0xffff0000, v24
	v_and_b32_e32 v165, 0xffff0000, v21
	v_pk_fma_f32 v[62:63], v[174:175], v[174:175], v[62:63] op_sel_hi:[1,1,0]
	v_lshlrev_b32_e32 v66, 16, v18
	v_pk_add_f32 v[202:203], v[202:203], v[202:203] op_sel:[0,1] op_sel_hi:[1,0]
	v_lshlrev_b32_e32 v72, 16, v24
	v_lshlrev_b32_e32 v162, 16, v23
	v_and_b32_e32 v163, 0xffff0000, v23
	v_and_b32_e32 v71, 0xffff0000, v22
	v_lshlrev_b32_e32 v164, 16, v21
	v_and_b32_e32 v69, 0xffff0000, v20
	v_and_b32_e32 v67, 0xffff0000, v18
	v_mul_f32_e32 v62, v66, v66
	v_pk_add_f32 v[202:203], v[190:191], v[202:203] op_sel:[1,0] op_sel_hi:[0,1]
	v_mov_b32_e32 v204, v73
	v_mov_b32_e32 v205, v165
	v_pk_mul_f32 v[60:61], v[162:163], v[162:163]
	v_lshlrev_b32_e32 v70, 16, v22
	v_lshlrev_b32_e32 v68, 16, v20
	v_pk_fma_f32 v[64:65], v[66:67], v[66:67], v[62:63] op_sel_hi:[1,1,0]
	v_pk_add_f32 v[190:191], v[190:191], v[202:203]
	v_mov_b32_e32 v202, v72
	v_mov_b32_e32 v203, v164
	v_pk_mul_f32 v[204:205], v[204:205], v[204:205]
	v_mov_b32_e32 v206, v71
	v_mov_b32_e32 v207, v69
	v_lshlrev_b32_e32 v74, 16, v25
	v_and_b32_e32 v75, 0xffff0000, v25
	v_pk_fma_f32 v[202:203], v[202:203], v[202:203], v[204:205]
	v_mov_b32_e32 v204, v70
	v_mov_b32_e32 v205, v68
	v_pk_mul_f32 v[206:207], v[206:207], v[206:207]
	v_mov_b32_e32 v64, v60
	v_mov_b32_e32 v62, v61
	v_pk_mul_f32 v[58:59], v[74:75], v[74:75]
	v_pk_fma_f32 v[204:205], v[204:205], v[204:205], v[206:207]
	v_pk_add_f32 v[60:61], v[64:65], v[62:63]
	v_mov_b32_e32 v62, v58
	v_pk_add_f32 v[60:61], v[204:205], v[60:61]
	v_mov_b32_e32 v63, v180
	v_pk_mov_b32 v[58:59], v[58:59], v[190:191] op_sel:[1,0]
	v_pk_add_f32 v[60:61], v[202:203], v[60:61]
	v_pk_add_f32 v[58:59], v[62:63], v[58:59]
	s_waitcnt vmcnt(4)
	v_and_b32_e32 v207, 0xffff0000, v30
	v_pk_add_f32 v[58:59], v[60:61], v[58:59]
	v_lshlrev_b32_e32 v206, 16, v30
	v_add_f32_e32 v58, v58, v59
	v_mov_b32_e32 v59, v58
	s_nop 1
	v_permlane16_swap_b32_e32 v59, v58
	v_mov_b32_e32 v210, v207
	v_mov_b32_e32 v208, v206
	ds_read_b128 v[104:107], v149
	ds_read_b128 v[76:79], v149 offset:16
	ds_read_b128 v[100:103], v149 offset:128
	ds_read_b128 v[80:83], v149 offset:144
	ds_read_b128 v[96:99], v149 offset:256
	ds_read_b128 v[84:87], v149 offset:272
	ds_read_b128 v[92:95], v149 offset:384
	ds_read_b128 v[88:91], v149 offset:400
	v_and_b32_e32 v217, 0xffff0000, v26
	s_waitcnt lgkmcnt(8)
	v_add_f32_e32 v58, v58, v59
	v_mov_b32_e32 v59, v58
	s_nop 1
	v_permlane32_swap_b32_e32 v59, v58
	v_lshlrev_b32_e32 v216, 16, v26
	v_mov_b32_e32 v220, v217
	v_mov_b32_e32 v218, v216
	s_waitcnt lgkmcnt(0)
	v_add_f32_e32 v58, v58, v59
	v_fmamk_f32 v58, v58, 0x3c000000, v1
	v_rsq_f32_e32 v58, v58
	s_nop 0
	v_mul_f32_e32 v180, 0x3e0293ee, v58
	v_pk_mul_f32 v[58:59], v[180:181], v[200:201] op_sel_hi:[0,1]
	v_pk_mul_f32 v[60:61], v[180:181], v[192:193] op_sel_hi:[0,1]
	v_and_b32_e32 v193, 0xffff0000, v33
	v_and_b32_e32 v201, 0xffff0000, v32
	v_lshlrev_b32_e32 v192, 16, v33
	v_lshlrev_b32_e32 v200, 16, v32
	v_mov_b32_e32 v204, v193
	v_mov_b32_e32 v205, v201
	v_mov_b32_e32 v202, v192
	v_mov_b32_e32 v203, v200
	v_pk_mul_f32 v[204:205], v[204:205], v[204:205]
	v_pk_mul_f32 v[58:59], v[104:105], v[58:59]
	v_pk_fma_f32 v[202:203], v[202:203], v[202:203], v[204:205]
	v_and_b32_e32 v205, 0xffff0000, v31
	v_lshlrev_b32_e32 v204, 16, v31
	v_mov_b32_e32 v211, v205
	v_mov_b32_e32 v209, v204
	v_pk_mul_f32 v[210:211], v[210:211], v[210:211]
	v_pk_mul_f32 v[60:61], v[106:107], v[60:61]
	v_pk_fma_f32 v[208:209], v[208:209], v[208:209], v[210:211]
	v_and_b32_e32 v211, 0xffff0000, v28
	v_pk_add_f32 v[208:209], v[208:209], v[208:209] op_sel:[0,1] op_sel_hi:[1,0]
	v_lshlrev_b32_e32 v210, 16, v28
	v_pk_add_f32 v[208:209], v[202:203], v[208:209] op_sel:[1,0] op_sel_hi:[0,1]
	v_pk_add_f32 v[202:203], v[202:203], v[208:209]
	v_and_b32_e32 v209, 0xffff0000, v29
	v_lshlrev_b32_e32 v208, 16, v29
	v_mov_b32_e32 v214, v209
	v_mov_b32_e32 v215, v211
	v_mov_b32_e32 v212, v208
	v_mov_b32_e32 v213, v210
	v_pk_mul_f32 v[214:215], v[214:215], v[214:215]
	v_cvt_pk_bf16_f32 v58, v58, v59
	v_cvt_pk_bf16_f32 v59, v60, v61
	v_pk_mul_f32 v[60:61], v[180:181], v[188:189] op_sel_hi:[0,1]
	v_pk_mul_f32 v[62:63], v[180:181], v[186:187] op_sel_hi:[0,1]
	v_pk_fma_f32 v[212:213], v[212:213], v[212:213], v[214:215]
	v_and_b32_e32 v215, 0xffff0000, v27
	v_pk_mul_f32 v[60:61], v[76:77], v[60:61]
	v_pk_mul_f32 v[62:63], v[78:79], v[62:63]
	v_lshlrev_b32_e32 v214, 16, v27
	v_mov_b32_e32 v221, v215
	v_cvt_pk_bf16_f32 v60, v60, v61
	v_cvt_pk_bf16_f32 v61, v62, v63
	v_pk_mul_f32 v[62:63], v[180:181], v[184:185] op_sel_hi:[0,1]
	v_pk_mul_f32 v[64:65], v[180:181], v[182:183] op_sel_hi:[0,1]
	v_pk_mul_f32 v[68:69], v[180:181], v[68:69] op_sel_hi:[0,1]
	v_pk_mul_f32 v[164:165], v[180:181], v[164:165] op_sel_hi:[0,1]
	s_waitcnt vmcnt(3)
; #define LAS __attribute__((address_space(3)))
; __device__ __forceinline__ float bf2f(unsigned h) { return __uint_as_float(h << 16); }
; __device__ __forceinline__ unsigned pk2(float lo, float hi) { return pg8::cvt_pk_bf16(lo, hi); }
; __device__ __forceinline__ void dil_run(const Ctx& X, bf16* H, int l, int run) {
;     ...
;         for (int u = 0; u < 2; ++u) {
;             float s = 0.f;
; #pragma unroll
;             for (int ks = 0; ks < 4; ++ks) { const v4u qw = qw_[u][ks];
;                 const float a0 = bf2f(qw.x & 0xffffu), a1 = bf2f(qw.x >> 16), a2 = bf2f(qw.y & 0xffffu), a3 = bf2f(qw.y >> 16), a4 = bf2f(qw.z & 0xffffu), a5 = bf2f(qw.z >> 16), a6 = bf2f(qw.w & 0xffffu), a7 = bf2f(qw.w >> 16);
;                 s += (a0 * a0 + a1 * a1) + (a2 * a2 + a3 * a3) + (a4 * a4 + a5 * a5) + (a6 * a6 + a7 * a7); }
;             s += __shfl_xor(s, 16); s += __shfl_xor(s, 32);
;             const float sc = (0.08838834764831845f * 1.4426950408889634f) * __builtin_amdgcn_rsqf(s * (1.0f / 128.0f) + EPS);
; #pragma unroll
;             for (int ks = 0; ks < 4; ++ks) { const v4u qw = qw_[u][ks]; const f32x4 g0 = *(const LAS f32x4*)(qgl + 32 * ks + 8 * fq), g1 = *(const LAS f32x4*)(qgl + 32 * ks + 8 * fq + 4);
;                 v4u o; o.x = pk2(bf2f(qw.x & 0xffffu) * sc * g0.x, bf2f(qw.x >> 16) * sc * g0.y); o.y = pk2(bf2f(qw.y & 0xffffu) * sc * g0.z, bf2f(qw.y >> 16) * sc * g0.w);
;                 o.z = pk2(bf2f(qw.z & 0xffffu) * sc * g1.x, bf2f(qw.z >> 16) * sc * g1.y); o.w = pk2(bf2f(qw.w & 0xffffu) * sc * g1.z, bf2f(qw.w >> 16) * sc * g1.w);
;                 qf[u][ks] = __builtin_bit_cast(bf16x8, o); }
;         }
;         asm volatile("" : "+v"(qf[0][0]), "+v"(qf[0][1]), "+v"(qf[0][2]), "+v"(qf[0][3]), "+v"(qf[1][0]), "+v"(qf[1][1]), "+v"(qf[1][2]), "+v"(qf[1][3]));
;         __builtin_amdgcn_sched_barrier(0);
;         DaBlk Bn; if (i < 3) { da_blk_load(X, H, I, nb + 2 * I.dn, Bn); da_q_load(X, H, I, nb + I.dn, qw_); }
;         __builtin_amdgcn_sched_barrier(0);
	v_lshlrev_b32_e32 v184, 16, v35
	v_mov_b32_e32 v219, v214
	v_pk_mul_f32 v[220:221], v[220:221], v[220:221]
	v_pk_mul_f32 v[62:63], v[100:101], v[62:63]
	v_pk_mul_f32 v[64:65], v[102:103], v[64:65]
	v_pk_mul_f32 v[66:67], v[180:181], v[66:67] op_sel_hi:[0,1]
	v_pk_mul_f32 v[174:175], v[180:181], v[174:175] op_sel_hi:[0,1]
	v_pk_mul_f32 v[68:69], v[84:85], v[68:69]
	v_pk_mul_f32 v[164:165], v[86:87], v[164:165]
	v_and_b32_e32 v185, 0xffff0000, v35
	v_mul_f32_e32 v186, v184, v184
	v_pk_fma_f32 v[218:219], v[218:219], v[218:219], v[220:221]
	v_cvt_pk_bf16_f32 v62, v62, v63
	v_cvt_pk_bf16_f32 v63, v64, v65
	v_pk_mul_f32 v[64:65], v[180:181], v[178:179] op_sel_hi:[0,1]
	v_pk_mul_f32 v[176:177], v[180:181], v[176:177] op_sel_hi:[0,1]
	v_pk_mul_f32 v[66:67], v[96:97], v[66:67]
	v_pk_mul_f32 v[174:175], v[98:99], v[174:175]
	v_cvt_pk_bf16_f32 v68, v68, v69
	v_cvt_pk_bf16_f32 v69, v164, v165
	v_pk_mul_f32 v[70:71], v[180:181], v[70:71] op_sel_hi:[0,1]
	v_pk_mul_f32 v[162:163], v[180:181], v[162:163] op_sel_hi:[0,1]
	v_pk_mul_f32 v[72:73], v[180:181], v[72:73] op_sel_hi:[0,1]
	v_pk_mul_f32 v[74:75], v[180:181], v[74:75] op_sel_hi:[0,1]
	s_waitcnt vmcnt(2)
	v_and_b32_e32 v165, 0xffff0000, v40
	v_and_b32_e32 v181, 0xffff0000, v37
	v_pk_fma_f32 v[186:187], v[184:185], v[184:185], v[186:187] op_sel_hi:[1,1,0]
	v_lshlrev_b32_e32 v188, 16, v34
	v_pk_add_f32 v[218:219], v[218:219], v[218:219] op_sel:[0,1] op_sel_hi:[1,0]
	v_pk_mul_f32 v[64:65], v[80:81], v[64:65]
	v_pk_mul_f32 v[176:177], v[82:83], v[176:177]
	v_cvt_pk_bf16_f32 v66, v66, v67
	v_cvt_pk_bf16_f32 v67, v174, v175
	v_lshlrev_b32_e32 v164, 16, v40
	v_lshlrev_b32_e32 v174, 16, v39
	v_and_b32_e32 v175, 0xffff0000, v39
	v_and_b32_e32 v179, 0xffff0000, v38
	v_lshlrev_b32_e32 v180, 16, v37
	v_and_b32_e32 v183, 0xffff0000, v36
	v_and_b32_e32 v189, 0xffff0000, v34
	v_mul_f32_e32 v186, v188, v188
	v_pk_add_f32 v[218:219], v[212:213], v[218:219] op_sel:[1,0] op_sel_hi:[0,1]
	v_mov_b32_e32 v220, v165
	v_mov_b32_e32 v221, v181
	v_cvt_pk_bf16_f32 v64, v64, v65
	v_cvt_pk_bf16_f32 v65, v176, v177
	v_pk_mul_f32 v[70:71], v[92:93], v[70:71]
	v_pk_mul_f32 v[162:163], v[94:95], v[162:163]
	v_pk_mul_f32 v[176:177], v[174:175], v[174:175]
	v_lshlrev_b32_e32 v178, 16, v38
	v_lshlrev_b32_e32 v182, 16, v36
	v_pk_fma_f32 v[190:191], v[188:189], v[188:189], v[186:187] op_sel_hi:[1,1,0]
	v_pk_add_f32 v[212:213], v[212:213], v[218:219]
	v_mov_b32_e32 v218, v164
	v_mov_b32_e32 v219, v180
	v_pk_mul_f32 v[220:221], v[220:221], v[220:221]
	v_mov_b32_e32 v222, v179
	v_mov_b32_e32 v223, v183
	v_cvt_pk_bf16_f32 v70, v70, v71
	v_cvt_pk_bf16_f32 v71, v162, v163
	v_pk_mul_f32 v[72:73], v[88:89], v[72:73]
	v_pk_mul_f32 v[74:75], v[90:91], v[74:75]
	v_lshlrev_b32_e32 v162, 16, v41
	v_and_b32_e32 v163, 0xffff0000, v41
	v_pk_fma_f32 v[218:219], v[218:219], v[218:219], v[220:221]
	v_mov_b32_e32 v220, v178
	v_mov_b32_e32 v221, v182
	v_pk_mul_f32 v[222:223], v[222:223], v[222:223]
	v_mov_b32_e32 v190, v176
	v_mov_b32_e32 v186, v177
	v_cvt_pk_bf16_f32 v72, v72, v73
	v_cvt_pk_bf16_f32 v73, v74, v75
	v_pk_mul_f32 v[74:75], v[162:163], v[162:163]
	v_pk_fma_f32 v[220:221], v[220:221], v[220:221], v[222:223]
	v_pk_add_f32 v[176:177], v[190:191], v[186:187]
	v_mov_b32_e32 v186, v74
	v_pk_add_f32 v[176:177], v[220:221], v[176:177]
	v_mov_b32_e32 v187, v202
	v_pk_mov_b32 v[74:75], v[74:75], v[212:213] op_sel:[1,0]
	v_pk_add_f32 v[176:177], v[218:219], v[176:177]
	v_pk_add_f32 v[74:75], v[186:187], v[74:75]
	s_nop 0
	v_pk_add_f32 v[74:75], v[176:177], v[74:75]
	s_nop 0
	v_add_f32_e32 v74, v74, v75
	v_mov_b32_e32 v75, v74
	s_nop 1
	v_permlane16_swap_b32_e32 v75, v74
	s_waitcnt lgkmcnt(0)
	v_add_f32_e32 v74, v74, v75
	v_mov_b32_e32 v75, v74
	s_nop 1
	v_permlane32_swap_b32_e32 v75, v74
	s_waitcnt lgkmcnt(0)
	v_add_f32_e32 v74, v74, v75
	v_fmamk_f32 v74, v74, 0x3c000000, v1
	v_rsq_f32_e32 v74, v74
	s_nop 0
	v_mul_f32_e32 v176, 0x3e0293ee, v74
	v_pk_mul_f32 v[74:75], v[176:177], v[216:217] op_sel_hi:[0,1]
	v_pk_mul_f32 v[74:75], v[104:105], v[74:75]
	v_pk_mul_f32 v[104:105], v[176:177], v[214:215] op_sel_hi:[0,1]
	v_pk_mul_f32 v[104:105], v[106:107], v[104:105]
	v_cvt_pk_bf16_f32 v74, v74, v75
	v_cvt_pk_bf16_f32 v75, v104, v105
	v_pk_mul_f32 v[104:105], v[176:177], v[210:211] op_sel_hi:[0,1]
	v_pk_mul_f32 v[76:77], v[76:77], v[104:105]
	v_pk_mul_f32 v[104:105], v[176:177], v[208:209] op_sel_hi:[0,1]
	v_pk_mul_f32 v[78:79], v[78:79], v[104:105]
	v_cvt_pk_bf16_f32 v76, v76, v77
	v_cvt_pk_bf16_f32 v77, v78, v79
	v_pk_mul_f32 v[78:79], v[176:177], v[206:207] op_sel_hi:[0,1]
	v_pk_mul_f32 v[78:79], v[100:101], v[78:79]
	v_pk_mul_f32 v[100:101], v[176:177], v[204:205] op_sel_hi:[0,1]
	v_pk_mul_f32 v[100:101], v[102:103], v[100:101]
	v_cvt_pk_bf16_f32 v78, v78, v79
	v_cvt_pk_bf16_f32 v79, v100, v101
	v_pk_mul_f32 v[100:101], v[176:177], v[200:201] op_sel_hi:[0,1]
	v_pk_mul_f32 v[80:81], v[80:81], v[100:101]
	v_pk_mul_f32 v[100:101], v[176:177], v[192:193] op_sel_hi:[0,1]
	v_pk_mul_f32 v[82:83], v[82:83], v[100:101]
	v_cvt_pk_bf16_f32 v80, v80, v81
	v_cvt_pk_bf16_f32 v81, v82, v83
	v_pk_mul_f32 v[82:83], v[176:177], v[188:189] op_sel_hi:[0,1]
	v_pk_mul_f32 v[82:83], v[96:97], v[82:83]
	v_pk_mul_f32 v[96:97], v[176:177], v[184:185] op_sel_hi:[0,1]
	v_pk_mul_f32 v[96:97], v[98:99], v[96:97]
	v_cvt_pk_bf16_f32 v82, v82, v83
	v_cvt_pk_bf16_f32 v83, v96, v97
	v_pk_mul_f32 v[96:97], v[176:177], v[182:183] op_sel_hi:[0,1]
	v_pk_mul_f32 v[84:85], v[84:85], v[96:97]
	v_pk_mul_f32 v[96:97], v[176:177], v[180:181] op_sel_hi:[0,1]
	v_pk_mul_f32 v[86:87], v[86:87], v[96:97]
	v_cvt_pk_bf16_f32 v84, v84, v85
	v_cvt_pk_bf16_f32 v85, v86, v87
	v_pk_mul_f32 v[86:87], v[176:177], v[178:179] op_sel_hi:[0,1]
	v_pk_mul_f32 v[86:87], v[92:93], v[86:87]
	v_pk_mul_f32 v[92:93], v[176:177], v[174:175] op_sel_hi:[0,1]
	v_pk_mul_f32 v[92:93], v[94:95], v[92:93]
	v_cvt_pk_bf16_f32 v86, v86, v87
	v_cvt_pk_bf16_f32 v87, v92, v93
	v_pk_mul_f32 v[92:93], v[176:177], v[164:165] op_sel_hi:[0,1]
	v_pk_mul_f32 v[88:89], v[88:89], v[92:93]
	v_pk_mul_f32 v[92:93], v[176:177], v[162:163] op_sel_hi:[0,1]
	v_pk_mul_f32 v[90:91], v[90:91], v[92:93]
	v_cvt_pk_bf16_f32 v88, v88, v89
	v_cvt_pk_bf16_f32 v89, v90, v91
	s_cmp_lg_u32 s31, 1
	s_cselect_b64 s[0:1], -1, 0
	s_cmp_eq_u32 s31, 1
	s_cbranch_scc1 .LBB0_275
; __device__ __forceinline__ void da_blk_load(const Ctx& X, const bf16* H, const DaRun& I, int kb, DaBlk& R) {
;     const bool ok = kb >= 0 && kb < I.nbper; const size_t mb = (size_t)I.b * SEQ; const int kcol = I.qcol + 512, vcol = I.qcol + 1024;
; #pragma unroll
;     for (int p = 0; p < 2; ++p) { const int r = (X.tid >> 4) + 32 * p, c8 = X.tid & 15; R.kw[p] = (v4u){0u, 0u, 0u, 0u}; R.vw[p] = (v4u){0u, 0u, 0u, 0u};
;         if (ok) { const size_t mr = mb + (size_t)(I.rho * (SEQ / I.dil) + 64 * kb + r); R.kw[p] = *(const v4u*)hptr(H, mr, kcol + 8 * c8); R.vw[p] = *(const v4u*)hptr(H, mr, vcol + 8 * c8); } }
; }
; __device__ __forceinline__ void dil_run(const Ctx& X, bf16* H, int l, int run) {
;     ...
;         DaBlk Bn; if (i < 3) { da_blk_load(X, H, I, nb + 2 * I.dn, Bn); da_q_load(X, H, I, nb + I.dn, qw_); }
	s_add_i32 s48, s71, s75
	s_cmp_gt_i32 s48, -1
	s_cselect_b64 s[16:17], -1, 0
	s_cmp_lt_i32 s48, s69
	s_cselect_b64 s[48:49], -1, 0
	s_and_b64 s[16:17], s[16:17], s[48:49]
	s_andn2_b64 vcc, exec, s[16:17]
	s_cbranch_vccnz .LBB0_273
	v_add_u32_e32 v10, s30, v168
	v_ashrrev_i32_e32 v11, 31, v10
	v_lshlrev_b64 v[12:13], 8, v[10:11]
	v_add_u32_e32 v10, 32, v10
	v_ashrrev_i32_e32 v11, 31, v10
	v_lshl_add_u64 v[12:13], v[12:13], 0, s[4:5]
	v_lshlrev_b64 v[10:11], 8, v[10:11]
	v_lshl_add_u64 v[14:15], v[120:121], 0, v[12:13]
	v_lshl_add_u64 v[12:13], v[122:123], 0, v[12:13]
	v_lshl_add_u64 v[10:11], v[10:11], 0, s[4:5]
	global_load_dwordx4 v[42:45], v[14:15], off
	global_load_dwordx4 v[46:49], v[12:13], off
	v_lshl_add_u64 v[12:13], v[120:121], 0, v[10:11]
	v_lshl_add_u64 v[10:11], v[122:123], 0, v[10:11]
	global_load_dwordx4 v[50:53], v[12:13], off
	global_load_dwordx4 v[54:57], v[10:11], off
	s_branch .LBB0_274

; template <bool RET> __device__ __forceinline__ void loc_load(const Ctx& X, const bf16* H, int r, LocRegs<RET>& R) {
;     const int b = r / 768, head = (r / 128) % 6, n = r % 128; const size_t m0 = (size_t)(b * SEQ + n * CH);
;     raw_load<128>(X, H, m0, (RET ? C_RV : C_HGV) + head * 128, R.rv);
;     if (!RET) { raw_load<128>(X, H, m0, C_ZF + head * 128, R.rzf); raw_load<128>(X, H, m0, C_ZB + head * 128, R.rzb); }
;     else { raw_load<64>(X, H, m0, C_RQ + head * 64, R.rq); raw_load<64>(X, H, m0, C_RK + head * 64, R.rk);
;         const float* rc = (const float*)(X.ws + WS_ROPE) + (size_t)n * CH * 32; R.c4 = *(const f32x4*)(rc + X.tid * 4); R.s4 = *(const f32x4*)(rc + SEQ * 32 + X.tid * 4); }
; }
; template <int DK, bool RET>
; __device__ __forceinline__ void gla_local_item(const Ctx& X, bf16* H, int l, int r, LocRegs<RET>& R, bool has_next) {
;     static_assert(DK == 128 && !RET, "HGRN2 only (retention has its own path)");
;     const int b = r / 768, head = (r / 128) % 6, n = r % 128;
;     const float* LB = (const float*)(X.ws + WS_TAB);
;     unsigned char* St = (unsigned char*)(X.ws + WS_SHG); float* dd = (float*)(X.ws + WS_DHG);
;     const int kp = X.tid & 63;
;     f32x2v lb0 = *(const f32x2v*)(LB + (0 * 4 + l) * 768 + head * 128 + 2 * kp), lb1 = *(const f32x2v*)(LB + (1 * 4 + l) * 768 + head * 128 + 2 * kp);
;     vt_store(X, X.lds + L1_VT, R.rv); raw_store<128>(X, X.lds + L1_RAW, R.rzf); raw_store<128>(X, X.lds + L1_RAW + 16384, R.rzb);
;     asm volatile("" : "+v"(lb0), "+v"(lb1)); __builtin_amdgcn_sched_barrier(0);
;     if (has_next) loc_load<RET>(X, H, r + X.G, R);
.LBB0_295:
	v_readlane_b32 s4, v254, 15
	v_mov_b32_e32 v90, v0
	v_readlane_b32 s0, v253, 0
	v_readlane_b32 s5, v254, 16
	v_readlane_b32 s1, v253, 1
	s_andn2_b64 vcc, exec, s[4:5]
	v_readfirstlane_b32 s12, v90
	s_cbranch_vccnz .LBB0_308
	v_ashrrev_i32_e32 v2, 31, v90
	v_lshrrev_b32_e32 v2, 28, v2
	v_add_u32_e32 v2, v90, v2
	s_waitcnt vmcnt(0)
	v_ashrrev_i32_e32 v42, 4, v2
	v_and_b32_e32 v2, 0x1ffffff0, v2
	v_sub_u32_e32 v2, v90, v2
	v_add_u32_e32 v27, 0x200, v90
	v_lshlrev_b32_e32 v91, 3, v2
	v_ashrrev_i32_e32 v2, 31, v27
	v_lshrrev_b32_e32 v2, 28, v2
	v_add_u32_e32 v2, v27, v2
	v_ashrrev_i32_e32 v44, 4, v2
	v_and_b32_e32 v2, 0x1ffffff0, v2
	v_readlane_b32 s14, v254, 9
	s_load_dwordx2 s[0:1], s[0:1], 0x78
	v_sub_u32_e32 v2, v27, v2
	v_ashrrev_i32_e32 v45, 31, v44
	v_readlane_b32 s15, v254, 10
	v_lshlrev_b32_e32 v92, 3, v2
	v_readlane_b32 s13, v254, 14
	v_lshl_add_u64 v[4:5], v[44:45], 0, s[14:15]
	v_lshlrev_b64 v[18:19], 8, v[4:5]
	v_add_u32_e32 v2, s13, v92
	v_add_u32_e32 v4, s13, v91
	v_readlane_b32 s13, v254, 12
	s_waitcnt lgkmcnt(0)
	s_add_u32 s4, s0, 0x25800000
	v_lshrrev_b32_e32 v158, 7, v2
	v_add_u32_e32 v10, s13, v92
	v_add_u32_e32 v12, s13, v91
	v_readlane_b32 s13, v254, 11
	v_lshrrev_b32_e32 v10, 7, v10
	v_mov_b32_e32 v11, v159
	v_add_u32_e32 v24, s13, v92
	v_lshrrev_b32_e32 v24, 7, v24
	v_mov_b32_e32 v25, v159
	s_addc_u32 s5, s1, 0
	v_lshlrev_b64 v[2:3], 22, v[158:159]
	v_lshlrev_b64 v[10:11], 22, v[10:11]
	v_lshlrev_b64 v[24:25], 22, v[24:25]
	v_and_b32_e32 v28, 0x78, v92
	v_lshl_add_u64 v[2:3], s[4:5], 0, v[2:3]
	v_lshl_add_u64 v[10:11], s[4:5], 0, v[10:11]
	v_lshl_add_u64 v[24:25], s[4:5], 0, v[24:25]
	v_lshl_add_u64 v[2:3], v[2:3], 0, v[18:19]
	v_lshlrev_b32_e32 v158, 1, v28
	v_lshl_add_u64 v[10:11], v[10:11], 0, v[18:19]
	v_lshl_add_u64 v[18:19], v[24:25], 0, v[18:19]
	v_add_u32_e32 v24, s13, v91
	v_ashrrev_i32_e32 v43, 31, v42
	v_lshl_add_u64 v[2:3], v[2:3], 0, v[158:159]
	v_lshrrev_b32_e32 v4, 7, v4
	v_mov_b32_e32 v5, v159
	v_lshl_add_u64 v[10:11], v[10:11], 0, v[158:159]
	v_lshrrev_b32_e32 v12, 7, v12
	v_mov_b32_e32 v13, v159
	v_lshl_add_u64 v[18:19], v[18:19], 0, v[158:159]
	v_lshrrev_b32_e32 v158, 7, v24
	v_lshlrev_b64 v[4:5], 22, v[4:5]
	v_lshl_add_u64 v[6:7], v[42:43], 0, s[14:15]
	v_lshlrev_b64 v[12:13], 22, v[12:13]
	v_lshlrev_b64 v[24:25], 22, v[158:159]
	v_and_b32_e32 v26, 0x78, v91
	v_lshl_add_u64 v[4:5], s[4:5], 0, v[4:5]
	v_lshlrev_b64 v[20:21], 8, v[6:7]
	v_lshl_add_u64 v[12:13], s[4:5], 0, v[12:13]
	v_lshl_add_u64 v[24:25], s[4:5], 0, v[24:25]
	v_lshl_add_u64 v[4:5], v[4:5], 0, v[20:21]
	v_lshlrev_b32_e32 v22, 1, v26
	v_mov_b32_e32 v23, v159
	v_lshl_add_u64 v[12:13], v[12:13], 0, v[20:21]
	v_lshl_add_u64 v[20:21], v[24:25], 0, v[20:21]
	v_lshl_add_u64 v[6:7], v[4:5], 0, v[22:23]
	v_lshl_add_u64 v[14:15], v[12:13], 0, v[22:23]
	v_lshl_add_u64 v[22:23], v[20:21], 0, v[22:23]
	global_load_dwordx4 v[2:5], v[2:3], off
	s_nop 0
	global_load_dwordx4 v[6:9], v[6:7], off
	s_nop 0
	global_load_dwordx4 v[10:13], v[10:11], off
	s_nop 0
	global_load_dwordx4 v[14:17], v[14:15], off
	s_nop 0
	global_load_dwordx4 v[18:21], v[18:19], off
	s_nop 0
	global_load_dwordx4 v[22:25], v[22:23], off
	s_mul_i32 s34, s86, 0x300
	s_lshl_b64 s[14:15], s[34:35], 2
	s_add_u32 s14, s0, s14
	v_lshlrev_b32_e32 v29, 3, v90
	s_addc_u32 s15, s1, s15
	v_and_b32_e32 v158, 0x1f8, v29
	v_lshl_add_u64 v[30:31], s[14:15], 0, v[158:159]
	s_mov_b64 s[14:15], 0x400000
	v_lshl_add_u64 v[46:47], v[30:31], 0, s[14:15]
	s_mov_b64 s[14:15], 0x403000
	v_lshl_add_u64 v[48:49], v[30:31], 0, s[14:15]
	v_ashrrev_i32_e32 v31, 4, v90
	v_bitop3_b32 v31, v29, v31, 56 bitop3:0x6c
	v_lshlrev_b32_e32 v33, 1, v31
	v_ashrrev_i32_e32 v31, 4, v27
	v_and_b32_e32 v30, 15, v90
	v_bitop3_b32 v29, v31, v29, 56 bitop3:0x78
	v_bfe_u32 v31, v90, 4, 2
	s_add_u32 s18, s0, 0x600000
	v_lshlrev_b32_e32 v35, 3, v31
	v_or_b32_e32 v50, 32, v30
	s_addc_u32 s19, s1, 0
	v_bitop3_b32 v50, v50, v35, 40 bitop3:0x6c
	s_add_u32 s21, s0, 0x3a800000
	v_lshlrev_b32_e32 v57, 1, v50
	v_or_b32_e32 v50, 48, v30
	s_movk_i32 s13, 0x480
	s_addc_u32 s22, s1, 0
	s_ashr_i32 s0, s12, 2
	v_bitop3_b32 v50, v50, v35, 56 bitop3:0x6c
	v_mad_u32_u24 v32, v30, s13, 0
	s_and_b32 s1, s0, -16
	v_bfi_b32 v34, -16, s0, v90
	s_movk_i32 s12, 0x90
	s_movk_i32 s0, 0xfc10
	v_lshlrev_b32_e32 v95, 1, v50
	v_mov_b32_e32 v50, 0x3f00
	v_mul_u32_u24_e32 v36, 0x90, v30
	v_mad_i32_i24 v94, v30, s0, v32
	v_and_b32_e32 v37, 8, v90
	v_or_b32_e32 v40, 16, v30
	v_bitop3_b32 v41, v30, 24, 16 bitop3:0xc8
	v_bitop3_b32 v51, v30, 40, 32 bitop3:0xc8
	v_bitop3_b32 v52, v30, 56, 48 bitop3:0xc8
	v_mad_u32_u24 v96, v30, s12, v50
	v_or_b32_e32 v30, 32, v35
	v_lshlrev_b32_e32 v59, 1, v30
	v_bitop3_b32 v30, v35, v37, 32 bitop3:0x36
	v_lshlrev_b32_e32 v37, 1, v30
	v_bitop3_b32 v30, v35, v41, 32 bitop3:0x36
	v_lshlrev_b32_e32 v41, 1, v30
	v_bitop3_b32 v30, v35, v51, 32 bitop3:0x36
	v_lshlrev_b32_e32 v60, 1, v30
	v_bitop3_b32 v30, v35, v52, 32 bitop3:0x36
	s_add_i32 s0, 0, 0x12000
	v_lshlrev_b32_e32 v98, 1, v30
	s_add_i32 s1, s0, s1
	v_ashrrev_i32_e32 v30, 3, v90
	v_lshl_add_u32 v99, v31, 2, s1
	v_mul_lo_u32 v31, v30, s12
	v_bitop3_b32 v39, v35, v90, 8 bitop3:0x78
	v_bitop3_b32 v40, v40, v35, 24 bitop3:0x6c
	v_add_u32_e32 v35, s0, v31
	v_ashrrev_i32_e32 v31, 31, v30
	v_lshlrev_b64 v[52:53], 7, v[30:31]
	v_ashrrev_i32_e32 v30, 3, v27
	v_lshlrev_b32_e32 v93, 4, v90
	v_mul_lo_u32 v34, v34, s12
	v_mul_lo_u32 v27, v30, s12
	v_lshlrev_b32_e32 v29, 1, v29
	v_add_u32_e32 v34, 0, v34
	v_and_b32_e32 v38, 48, v90
	v_lshlrev_b32_e32 v39, 1, v39
	v_lshlrev_b32_e32 v40, 1, v40
	v_and_b32_e32 v50, 0x70, v93
	v_add_u32_e32 v27, s0, v27
	v_ashrrev_i32_e32 v31, 31, v30
	s_add_i32 s0, s2, s62
	v_add_u32_e32 v97, 0, v96
	v_mov_b32_e32 v51, v159
	v_lshlrev_b64 v[54:55], 7, v[30:31]
	s_lshl_b32 s23, s0, 6
	s_lshl_b32 s24, s62, 6
	v_add_u32_e32 v100, v32, v33
	v_add_u32_e32 v101, v32, v29
	v_lshlrev_b32_e32 v56, 1, v26
	v_lshlrev_b32_e32 v58, 1, v28
	v_add_u32_e32 v102, v34, v38
	v_add_u32_e32 v103, v94, v39
	v_add_u32_e32 v104, v94, v40
	v_add_u32_e32 v105, v94, v57
	v_add_u32_e32 v106, v34, v59
	v_add_u32_e32 v107, v94, v37
	v_add_u32_e32 v108, v94, v41
	v_add_u32_e32 v109, v94, v60
	v_add_u32_e32 v110, v99, v36
	v_add_u32_e32 v111, v35, v50
	v_add_u32_e32 v112, v27, v50
	s_mov_b32 s0, s2
	s_ashr_i32 s100, s0, 7
	s_mul_hi_i32 s101, s100, 0x2aaaaaab
	s_mul_i32 s101, s101, 6
	s_sub_i32 s100, s100, s101
	s_lshl_b32 s100, s100, 9
	s_mov_b32 s101, 0
	v_lshl_add_u64 v[222:223], v[48:49], 0, s[100:101]
	v_lshl_add_u64 v[224:225], v[46:47], 0, s[100:101]
	global_load_dwordx2 v[222:223], v[222:223], off
	global_load_dwordx2 v[224:225], v[224:225], off
	s_waitcnt vmcnt(0)
	s_branch .LBB0_298

; template <bool RET> __device__ __forceinline__ void loc_load(const Ctx& X, const bf16* H, int r, LocRegs<RET>& R) {
;     const int b = r / 768, head = (r / 128) % 6, n = r % 128; const size_t m0 = (size_t)(b * SEQ + n * CH);
;     raw_load<128>(X, H, m0, (RET ? C_RV : C_HGV) + head * 128, R.rv);
;     if (!RET) { raw_load<128>(X, H, m0, C_ZF + head * 128, R.rzf); raw_load<128>(X, H, m0, C_ZB + head * 128, R.rzb); }
;     else { raw_load<64>(X, H, m0, C_RQ + head * 64, R.rq); raw_load<64>(X, H, m0, C_RK + head * 64, R.rk);
;         const float* rc = (const float*)(X.ws + WS_ROPE) + (size_t)n * CH * 32; R.c4 = *(const f32x4*)(rc + X.tid * 4); R.s4 = *(const f32x4*)(rc + SEQ * 32 + X.tid * 4); }
; }
; template <int DK, bool RET>
; __device__ __forceinline__ void gla_local_item(const Ctx& X, bf16* H, int l, int r, LocRegs<RET>& R, bool has_next) {
;     static_assert(DK == 128 && !RET, "HGRN2 only (retention has its own path)");
;     const int b = r / 768, head = (r / 128) % 6, n = r % 128;
;     const float* LB = (const float*)(X.ws + WS_TAB);
;     unsigned char* St = (unsigned char*)(X.ws + WS_SHG); float* dd = (float*)(X.ws + WS_DHG);
;     const int kp = X.tid & 63;
;     f32x2v lb0 = *(const f32x2v*)(LB + (0 * 4 + l) * 768 + head * 128 + 2 * kp), lb1 = *(const f32x2v*)(LB + (1 * 4 + l) * 768 + head * 128 + 2 * kp);
;     vt_store(X, X.lds + L1_VT, R.rv); raw_store<128>(X, X.lds + L1_RAW, R.rzf); raw_store<128>(X, X.lds + L1_RAW + 16384, R.rzb);
;     asm volatile("" : "+v"(lb0), "+v"(lb1)); __builtin_amdgcn_sched_barrier(0);
;     if (has_next) loc_load<RET>(X, H, r + X.G, R);
.LBB0_298:
	s_add_i32 s25, s0, s62
	s_cmpk_gt_i32 s25, 0x5ff
	s_cselect_b64 s[12:13], -1, 0
	s_ashr_i32 s1, s0, 31
	s_lshr_b32 s1, s1, 25
	s_add_i32 s1, s0, s1
	s_ashr_i32 s14, s1, 7
	s_mul_hi_i32 s1, s14, 0x2aaaaaab
	s_lshr_b32 s15, s1, 31
	s_add_i32 s1, s1, s15
	s_mul_i32 s1, s1, 6
	s_sub_i32 s1, s14, s1
	s_lshl_b32 s16, s1, 7
	s_ashr_i32 s17, s16, 31
	s_lshl_b64 s[16:17], s[16:17], 2
	v_add_u32_e32 v28, 0, v93
	s_waitcnt vmcnt(2)
	ds_write_b16 v100, v22
	ds_write_b16_d16_hi v100, v22 offset:144
	ds_write_b16 v100, v23 offset:288
	ds_write_b16_d16_hi v100, v23 offset:432
	ds_write_b16 v100, v24 offset:576
	ds_write_b16_d16_hi v100, v24 offset:720
	ds_write_b16 v100, v25 offset:864
	ds_write_b16_d16_hi v100, v25 offset:1008
	ds_write_b16 v101, v18
	ds_write_b16_d16_hi v101, v18 offset:144
	ds_write_b16 v101, v19 offset:288
	ds_write_b16_d16_hi v101, v19 offset:432
	ds_write_b16 v101, v20 offset:576
	ds_write_b16_d16_hi v101, v20 offset:720
	ds_write_b16 v101, v21 offset:864
	ds_write_b16_d16_hi v101, v21 offset:1008
	ds_write_b128 v28, v[14:17] offset:40960
	ds_write_b128 v28, v[10:13] offset:49152
	ds_write_b128 v28, v[6:9] offset:57344
	v_add_u32_e32 v28, 0x10000, v28
	ds_write_b128 v28, v[2:5]
	v_mov_b32_e32 v60, v222
	v_mov_b32_e32 v61, v223
	v_mov_b32_e32 v26, v224
	v_mov_b32_e32 v27, v225
	s_and_b64 vcc, exec, s[12:13]
	s_cbranch_vccnz .LBB0_300
	s_mul_hi_i32 s15, s25, 0x2aaaaaab
	s_lshr_b32 s16, s15, 31
	s_lshr_b32 s15, s15, 7
	s_add_i32 s15, s15, s16
	s_ashr_i32 s16, s25, 31
	s_lshr_b32 s16, s16, 25
	s_add_i32 s16, s25, s16
	s_ashr_i32 s16, s16, 7
	s_mul_hi_i32 s17, s16, 0x2aaaaaab
	s_lshr_b32 s28, s17, 31
	s_add_i32 s17, s17, s28
	s_mul_i32 s17, s17, 6
	s_sub_i32 s28, s16, s17
	s_lshl_b32 s15, s15, 13
	s_lshl_b32 s16, s16, 13
	s_sub_i32 s15, s15, s16
	s_add_i32 s16, s23, s15
	s_lshl_b32 s15, s28, 7
	s_lshl_b32 s100, s15, 2
	s_mov_b32 s101, 0
	v_lshl_add_u64 v[222:223], v[48:49], 0, s[100:101]
	v_lshl_add_u64 v[224:225], v[46:47], 0, s[100:101]
	global_load_dwordx2 v[222:223], v[222:223], off
	global_load_dwordx2 v[224:225], v[224:225], off
	s_add_i32 s28, s15, 0x300
	v_add_u32_e32 v4, s28, v91
	s_ashr_i32 s17, s16, 31
	v_lshrrev_b32_e32 v158, 7, v4
	v_add_u32_e32 v8, s28, v92
	v_lshl_add_u64 v[2:3], s[16:17], 0, v[42:43]
	v_lshlrev_b64 v[4:5], 22, v[158:159]
	v_lshrrev_b32_e32 v158, 7, v8
	v_lshl_add_u64 v[4:5], s[4:5], 0, v[4:5]
	v_lshlrev_b64 v[2:3], 8, v[2:3]
	v_lshl_add_u64 v[6:7], s[16:17], 0, v[44:45]
	v_lshlrev_b64 v[8:9], 22, v[158:159]
	v_lshl_add_u64 v[4:5], v[4:5], 0, v[2:3]
	v_mov_b32_e32 v57, v159
	v_lshl_add_u64 v[8:9], s[4:5], 0, v[8:9]
	v_lshlrev_b64 v[6:7], 8, v[6:7]
	v_lshl_add_u64 v[4:5], v[4:5], 0, v[56:57]
	v_lshl_add_u64 v[8:9], v[8:9], 0, v[6:7]
	v_mov_b32_e32 v59, v159
	s_add_i32 s16, s15, 0x600
	v_lshl_add_u64 v[8:9], v[8:9], 0, v[58:59]
	global_load_dwordx4 v[22:25], v[4:5], off
	global_load_dwordx4 v[18:21], v[8:9], off
	v_add_u32_e32 v4, s16, v91
	v_lshrrev_b32_e32 v158, 7, v4
	v_add_u32_e32 v8, s16, v92
	v_lshlrev_b64 v[4:5], 22, v[158:159]
	v_lshrrev_b32_e32 v158, 7, v8
	v_lshl_add_u64 v[4:5], s[4:5], 0, v[4:5]
	v_lshlrev_b64 v[8:9], 22, v[158:159]
	v_lshl_add_u64 v[4:5], v[4:5], 0, v[2:3]
	v_lshl_add_u64 v[8:9], s[4:5], 0, v[8:9]
	v_lshl_add_u64 v[4:5], v[4:5], 0, v[56:57]
	v_lshl_add_u64 v[8:9], v[8:9], 0, v[6:7]
	s_addk_i32 s15, 0x900
	v_lshl_add_u64 v[8:9], v[8:9], 0, v[58:59]
	global_load_dwordx4 v[14:17], v[4:5], off
	global_load_dwordx4 v[10:13], v[8:9], off
	v_add_u32_e32 v4, s15, v91
	v_lshrrev_b32_e32 v158, 7, v4
	v_lshlrev_b64 v[4:5], 22, v[158:159]
	v_lshl_add_u64 v[4:5], s[4:5], 0, v[4:5]
	v_lshl_add_u64 v[2:3], v[4:5], 0, v[2:3]
	v_add_u32_e32 v4, s15, v92
	v_lshrrev_b32_e32 v158, 7, v4
	v_lshlrev_b64 v[4:5], 22, v[158:159]
	v_lshl_add_u64 v[4:5], s[4:5], 0, v[4:5]
	v_lshl_add_u64 v[4:5], v[4:5], 0, v[6:7]
	v_lshl_add_u64 v[2:3], v[2:3], 0, v[56:57]
	v_lshl_add_u64 v[4:5], v[4:5], 0, v[58:59]
	global_load_dwordx4 v[6:9], v[2:3], off
	s_nop 0
	global_load_dwordx4 v[2:5], v[4:5], off

; #define LAS __attribute__((address_space(3)))
; template <bool RET> __device__ __forceinline__ void loc_load(const Ctx& X, const bf16* H, int r, LocRegs<RET>& R) {
;     const int b = r / 768, head = (r / 128) % 6, n = r % 128; const size_t m0 = (size_t)(b * SEQ + n * CH);
;     raw_load<128>(X, H, m0, (RET ? C_RV : C_HGV) + head * 128, R.rv);
;     if (!RET) { raw_load<128>(X, H, m0, C_ZF + head * 128, R.rzf); raw_load<128>(X, H, m0, C_ZB + head * 128, R.rzb); }
;     else { raw_load<64>(X, H, m0, C_RQ + head * 64, R.rq); raw_load<64>(X, H, m0, C_RK + head * 64, R.rk);
;         const float* rc = (const float*)(X.ws + WS_ROPE) + (size_t)n * CH * 32; R.c4 = *(const f32x4*)(rc + X.tid * 4); R.s4 = *(const f32x4*)(rc + SEQ * 32 + X.tid * 4); }
; }
; __device__ __forceinline__ void ret_local_item(const Ctx& X, bf16* H, int it, LocRegs<true>& R, bool has_next) {
;     const int b = it / 384, head = (it / 64) % 6, n = it % 64;
;     bf16* St = (bf16*)(X.ws + WS_SRT); float* dd = (float*)(X.ws + WS_DRT);
;     const lptr VT = X.lds + R1_VT, KC0 = X.lds + R1_KC0, KC1 = X.lds + R1_KC1, rawq = X.lds + R1_RAW, rawk = X.lds + R1_RAW + 8192; LAS float* cs = (LAS float*)(X.lds + R1_RAW + 16384); LAS float* sn = (LAS float*)(X.lds + R1_RAW + 24576);
;     const float l2f = __log2f(1.0f - exp2f(-5.0f - (float)head)), l2b = __log2f(1.0f - exp2f(-5.0f - (float)(5 - head)));
;     const int chain = (b * 6 + head) * 2;
;     const int fr = X.lane & 15, fq = X.lane >> 4, rt = X.wave & 3, ct0 = (X.wave >> 2) * 4;
;     const int k = X.tid & 63, rq = X.tid >> 6, k2 = k & 31; const bool active = X.tid < 256;
;     f32x4 accf[4], accb[4];
; #pragma unroll
;     for (int t = 0; t < 4; ++t) { accf[t] = (f32x4){0.f, 0.f, 0.f, 0.f}; accb[t] = accf[t]; }
; #pragma unroll 1
;     for (int h = 0; h < 2; ++h) {
;         const int r = 2 * it + h; const size_t m0 = (size_t)(b * SEQ + (2 * n + h) * 64);
;         vt_store(X, VT, R.rv); raw_store<64>(X, rawq, R.rq); raw_store<64>(X, rawk, R.rk); *(LAS f32x4*)(cs + X.tid * 4) = R.c4; *(LAS f32x4*)(sn + X.tid * 4) = R.s4;
;         __builtin_amdgcn_sched_barrier(0);
;         { const int nr = h == 0 ? r + 1 : 2 * (it + X.G); if (h == 0 || has_next) loc_load<true>(X, H, nr, R); }
.LBB0_308:
	v_readlane_b32 s4, v254, 22
	s_waitcnt vmcnt(0)
	v_mov_b32_e32 v26, v0
	v_readlane_b32 s0, v253, 0
	v_readlane_b32 s5, v254, 23
	v_readlane_b32 s1, v253, 1
	s_andn2_b64 vcc, exec, s[4:5]
	v_readfirstlane_b32 s12, v26
	s_mov_b64 s[60:61], s[90:91]
	s_cbranch_vccnz .LBB0_323
	v_ashrrev_i32_e32 v27, 31, v26
	v_lshrrev_b32_e32 v2, 28, v27
	s_load_dwordx2 s[0:1], s[0:1], 0x78
	v_add_u32_e32 v2, v26, v2
	v_ashrrev_i32_e32 v58, 4, v2
	v_and_b32_e32 v2, 0x1ffffff0, v2
	v_sub_u32_e32 v2, v26, v2
	v_add_u32_e32 v29, 0x200, v26
	v_lshlrev_b32_e32 v120, 3, v2
	v_ashrrev_i32_e32 v2, 31, v29
	v_lshrrev_b32_e32 v2, 28, v2
	s_waitcnt lgkmcnt(0)
	s_add_u32 s4, s0, 0x25800000
	v_add_u32_e32 v2, v29, v2
	s_addc_u32 s5, s1, 0
	v_ashrrev_i32_e32 v60, 4, v2
	v_and_b32_e32 v2, 0x1ffffff0, v2
	v_sub_u32_e32 v2, v29, v2
	s_add_u32 s21, s0, 0x200000
	v_lshlrev_b32_e32 v121, 3, v2
	v_lshrrev_b32_e32 v2, 29, v27
	s_addc_u32 s28, s1, 0
	v_readlane_b32 s14, v254, 20
	v_add_u32_e32 v10, v26, v2
	v_lshlrev_b32_e32 v64, 2, v26
	v_readlane_b32 s15, v254, 21
	s_add_u32 s14, s21, s14
	v_ashrrev_i32_e32 v62, 3, v10
	v_ashrrev_i32_e32 v65, 31, v64
	s_addc_u32 s15, s28, s15
	v_and_b32_e32 v10, 0x1ffffff8, v10
	v_lshl_add_u64 v[2:3], v[64:65], 2, s[14:15]
	s_mov_b32 s13, 0x100000
	v_sub_u32_e32 v10, v26, v10
	v_add_co_u32_e32 v4, vcc, s13, v2
	v_lshlrev_b32_e32 v31, 3, v10
	v_readlane_b32 s13, v254, 31
	v_readlane_b32 s14, v254, 17
	v_ashrrev_i32_e32 v63, 31, v62
	v_add_u32_e32 v14, s13, v31
	v_lshrrev_b32_e32 v158, 7, v14
	v_readlane_b32 s15, v254, 18
	v_lshlrev_b64 v[10:11], 22, v[158:159]
	v_lshl_add_u64 v[10:11], s[4:5], 0, v[10:11]
	v_lshl_add_u64 v[12:13], v[62:63], 0, s[14:15]
	v_lshlrev_b64 v[12:13], 8, v[12:13]
	v_and_b32_e32 v14, 0x78, v14
	v_readlane_b32 s13, v254, 28
	v_lshl_add_u64 v[10:11], v[10:11], 0, v[12:13]
	v_lshlrev_b32_e32 v158, 1, v14
	v_add_u32_e32 v16, s13, v31
	v_lshl_add_u64 v[10:11], v[10:11], 0, v[158:159]
	v_lshrrev_b32_e32 v158, 7, v16
	v_lshlrev_b64 v[14:15], 22, v[158:159]
	v_lshl_add_u64 v[14:15], s[4:5], 0, v[14:15]
	v_lshl_add_u64 v[12:13], v[14:15], 0, v[12:13]
	v_and_b32_e32 v14, 0x78, v16
	v_readlane_b32 s13, v254, 19
	v_lshlrev_b32_e32 v158, 1, v14
	v_ashrrev_i32_e32 v61, 31, v60
	v_add_u32_e32 v18, s13, v121
	v_lshl_add_u64 v[12:13], v[12:13], 0, v[158:159]
	v_lshrrev_b32_e32 v158, 7, v18
	v_lshlrev_b64 v[18:19], 22, v[158:159]
	v_lshl_add_u64 v[20:21], v[60:61], 0, s[14:15]
	v_and_b32_e32 v30, 0x78, v121
	v_lshl_add_u64 v[18:19], s[4:5], 0, v[18:19]
	v_lshlrev_b64 v[20:21], 8, v[20:21]
	v_lshl_add_u64 v[18:19], v[18:19], 0, v[20:21]
	v_lshlrev_b32_e32 v158, 1, v30
	v_add_u32_e32 v20, s13, v120
	v_ashrrev_i32_e32 v59, 31, v58
	v_lshl_add_u64 v[18:19], v[18:19], 0, v[158:159]
	v_lshrrev_b32_e32 v158, 7, v20
	v_lshlrev_b64 v[20:21], 22, v[158:159]
	v_lshl_add_u64 v[22:23], v[58:59], 0, s[14:15]
	v_and_b32_e32 v28, 0x78, v120
	v_lshl_add_u64 v[20:21], s[4:5], 0, v[20:21]
	v_lshlrev_b64 v[22:23], 8, v[22:23]
	v_lshl_add_u64 v[20:21], v[20:21], 0, v[22:23]
	v_lshlrev_b32_e32 v158, 1, v28
	v_addc_co_u32_e32 v5, vcc, 0, v3, vcc
	v_lshl_add_u64 v[20:21], v[20:21], 0, v[158:159]
	global_load_dwordx4 v[6:9], v[4:5], off
	s_nop 0
	global_load_dwordx4 v[2:5], v[2:3], off
	s_nop 0
	global_load_dwordx4 v[14:17], v[10:11], off
	s_nop 0
	global_load_dwordx4 v[10:13], v[12:13], off
	s_nop 0
	global_load_dwordx4 v[22:25], v[18:19], off
	s_nop 0
	global_load_dwordx4 v[18:21], v[20:21], off
	v_ashrrev_i32_e32 v35, 6, v26
	v_lshlrev_b32_e32 v122, 4, v35
	v_and_b32_e32 v34, 31, v26
	v_or_b32_e32 v132, 5, v122
	v_lshlrev_b32_e32 v36, 1, v34
	v_lshlrev_b32_e32 v34, 2, v34
	v_lshlrev_b32_e32 v57, 7, v132
	v_or_b32_e32 v66, v57, v34
	v_or_b32_e32 v134, 6, v122
	v_add_u32_e32 v133, 0, v66
	v_lshlrev_b32_e32 v66, 7, v134
	v_or_b32_e32 v67, v66, v34
	v_or_b32_e32 v136, 7, v122
	v_add_u32_e32 v135, 0, v67
	v_lshlrev_b32_e32 v67, 7, v136
	v_or_b32_e32 v70, v67, v34
	v_or_b32_e32 v138, 8, v122
	v_add_u32_e32 v137, 0, v70
	v_lshlrev_b32_e32 v70, 7, v138
	v_or_b32_e32 v71, v70, v34
	v_or_b32_e32 v140, 9, v122
	s_ashr_i32 s12, s12, 6
	v_add_u32_e32 v139, 0, v71
	v_lshlrev_b32_e32 v71, 7, v140
	v_and_b32_e32 v32, 63, v26
	v_and_b32_e32 v33, 15, v26
	s_and_b32 s13, s12, 3
	s_movk_i32 s15, 0x90
	s_lshl_b32 s12, s12, 4
	v_or_b32_e32 v72, v71, v34
	v_or_b32_e32 v142, 10, v122
	v_cmp_gt_u32_e64 s[42:43], 32, v32
	v_lshlrev_b32_e32 v37, 1, v32
	v_mad_u32_u24 v38, v32, s15, 0
	v_lshl_or_b32 v32, s13, 4, v33
	s_and_b32 s14, s12, 0xffffffc0
	v_add_u32_e32 v141, 0, v72
	v_lshlrev_b32_e32 v72, 7, v142
	v_lshlrev_b32_e32 v39, 5, v35
	v_mad_u32_u24 v42, v32, s15, 0
	v_or_b32_e32 v32, s14, v33
	v_lshlrev_b32_e32 v35, 11, v35
	v_or_b32_e32 v124, 1, v122
	v_or_b32_e32 v126, 2, v122
	v_or_b32_e32 v128, 3, v122
	v_or_b32_e32 v130, 4, v122
	v_or_b32_e32 v74, v72, v34
	v_or_b32_e32 v144, 11, v122
	v_or_b32_e32 v146, 12, v122
	v_or_b32_e32 v148, 13, v122
	v_or_b32_e32 v150, 14, v122
	v_or_b32_e32 v152, 15, v122
	v_lshrrev_b32_e32 v40, 1, v26
	v_mul_lo_u32 v46, v32, s15
	v_or_b32_e32 v48, v35, v34
	v_lshlrev_b32_e32 v49, 7, v124
	v_lshlrev_b32_e32 v51, 7, v126
	v_lshlrev_b32_e32 v53, 7, v128
	v_lshlrev_b32_e32 v55, 7, v130
	v_add_u32_e32 v143, 0, v74
	v_lshlrev_b32_e32 v74, 7, v144
	v_lshlrev_b32_e32 v79, 7, v146
	v_lshlrev_b32_e32 v81, 7, v148
	v_lshlrev_b32_e32 v83, 7, v150
	v_lshlrev_b32_e32 v85, 7, v152
	v_or_b32_e32 v32, 16, v32
	v_and_b32_e32 v41, 24, v40
	v_and_b32_e32 v43, 8, v26
	v_add_u32_e32 v123, 0, v48
	v_or_b32_e32 v48, v35, v36
	v_or_b32_e32 v50, v49, v34
; #define LAS __attribute__((address_space(3)))
; __device__ __forceinline__ void ret_local_item(const Ctx& X, bf16* H, int it, LocRegs<true>& R, bool has_next) {
;     const int b = it / 384, head = (it / 64) % 6, n = it % 64;
;     bf16* St = (bf16*)(X.ws + WS_SRT); float* dd = (float*)(X.ws + WS_DRT);
;     const lptr VT = X.lds + R1_VT, KC0 = X.lds + R1_KC0, KC1 = X.lds + R1_KC1, rawq = X.lds + R1_RAW, rawk = X.lds + R1_RAW + 8192; LAS float* cs = (LAS float*)(X.lds + R1_RAW + 16384); LAS float* sn = (LAS float*)(X.lds + R1_RAW + 24576);
;     const float l2f = __log2f(1.0f - exp2f(-5.0f - (float)head)), l2b = __log2f(1.0f - exp2f(-5.0f - (float)(5 - head)));
;     const int chain = (b * 6 + head) * 2;
;     const int fr = X.lane & 15, fq = X.lane >> 4, rt = X.wave & 3, ct0 = (X.wave >> 2) * 4;
;     const int k = X.tid & 63, rq = X.tid >> 6, k2 = k & 31; const bool active = X.tid < 256;
;     f32x4 accf[4], accb[4];
; #pragma unroll
;     for (int t = 0; t < 4; ++t) { accf[t] = (f32x4){0.f, 0.f, 0.f, 0.f}; accb[t] = accf[t]; }
; #pragma unroll 1
;     for (int h = 0; h < 2; ++h) {
;         const int r = 2 * it + h; const size_t m0 = (size_t)(b * SEQ + (2 * n + h) * 64);
;         vt_store(X, VT, R.rv); raw_store<64>(X, rawq, R.rq); raw_store<64>(X, rawk, R.rk); *(LAS f32x4*)(cs + X.tid * 4) = R.c4; *(LAS f32x4*)(sn + X.tid * 4) = R.s4;
;         __builtin_amdgcn_sched_barrier(0);
;         { const int nr = h == 0 ? r + 1 : 2 * (it + X.G); if (h == 0 || has_next) loc_load<true>(X, H, nr, R); }
	v_or_b32_e32 v52, v51, v34
	v_or_b32_e32 v54, v53, v34
	v_or_b32_e32 v56, v55, v34
	v_or_b32_e32 v78, v74, v34
	v_or_b32_e32 v80, v79, v34
	v_or_b32_e32 v82, v81, v34
	v_or_b32_e32 v84, v83, v34
	v_or_b32_e32 v34, v85, v34
	v_or_b32_e32 v86, v35, v37
	v_bitop3_b32 v35, v32, v40, 24 bitop3:0x28
	v_or_b32_e32 v44, 32, v41
	v_add_u32_e32 v153, 0, v34
	v_bitop3_b32 v34, v40, v43, 24 bitop3:0x6c
	v_lshlrev_b32_e32 v40, 1, v35
	v_or_b32_e32 v35, 32, v33
	v_bitop3_b32 v45, v41, v43, 32 bitop3:0x36
	v_or_b32_e32 v69, v66, v36
	v_or_b32_e32 v87, v66, v37
	v_lshlrev_b32_e32 v43, 1, v34
	v_mul_lo_u32 v34, v32, s15
	v_bitop3_b32 v66, v35, v41, 40 bitop3:0x6c
	v_bitop3_b32 v32, v32, v44, 24 bitop3:0x6c
	v_lshlrev_b32_e32 v95, 1, v66
	v_or3_b32 v66, s12, v33, 48
	v_lshlrev_b32_e32 v99, 1, v32
	v_bitop3_b32 v32, v35, v44, 40 bitop3:0x6c
	v_lshlrev_b32_e32 v100, 1, v32
	v_bitop3_b32 v32, v66, v44, 56 bitop3:0x6c
	v_lshlrev_b32_e32 v98, 1, v44
	v_lshlrev_b32_e32 v44, 1, v32
	v_lshlrev_b32_e32 v32, 3, v26
	v_ashrrev_i32_e32 v35, 4, v26
	v_bitop3_b32 v35, v32, v35, 56 bitop3:0x6c
	v_or_b32_e32 v77, v72, v36
	v_or_b32_e32 v91, v72, v37
	v_lshlrev_b32_e32 v72, 1, v35
	v_ashrrev_i32_e32 v35, 4, v29
	v_readlane_b32 s14, v252, 2
	v_readlane_b32 s16, v252, 3
	v_or_b32_e32 v73, v67, v36
	v_or_b32_e32 v75, v70, v36
	v_or_b32_e32 v76, v71, v36
	v_or_b32_e32 v88, v67, v37
	v_or_b32_e32 v89, v70, v37
	v_or_b32_e32 v90, v71, v37
	v_add_u32_e32 v93, 0, v34
	v_add_u32_e32 v70, 0x900, v34
	v_mul_lo_u32 v71, v66, s15
	v_bitop3_b32 v67, v66, v41, 56 bitop3:0x6c
	v_and_b32_e32 v154, 56, v32
	v_bitop3_b32 v32, v35, v32, 56 bitop3:0x78
	v_ashrrev_i32_e32 v66, 3, v26
	v_add_u32_e32 v102, s14, v34
	v_add_u32_e32 v103, s16, v34
	s_add_u32 s29, s0, 0x800000
	v_ashrrev_i32_e32 v34, 3, v29
	v_add_u32_e32 v145, 0, v78
	v_or_b32_e32 v78, v74, v36
	v_or_b32_e32 v92, v74, v37
	s_movk_i32 s12, 0x480
	v_lshlrev_b32_e32 v74, 1, v32
	s_addc_u32 s30, s1, 0
	v_and_b32_e32 v32, 7, v26
	v_mul_lo_u32 v108, v66, s15
	v_mul_lo_u32 v29, v34, s15
	v_ashrrev_i32_e32 v35, 31, v34
	v_lshlrev_b32_e32 v45, 1, v45
	v_add_u32_e32 v47, 0, v46
	v_add_u32_e32 v125, 0, v50
	v_or_b32_e32 v50, v49, v36
	v_add_u32_e32 v127, 0, v52
	v_or_b32_e32 v52, v51, v36
	v_add_u32_e32 v129, 0, v54
	v_or_b32_e32 v54, v53, v36
	v_add_u32_e32 v131, 0, v56
	v_or_b32_e32 v56, v55, v36
	v_or_b32_e32 v68, v57, v36
	v_add_u32_e32 v147, 0, v80
	v_or_b32_e32 v80, v79, v36
	v_add_u32_e32 v149, 0, v82
	v_or_b32_e32 v82, v81, v36
	v_add_u32_e32 v151, 0, v84
	v_or_b32_e32 v84, v83, v36
	v_or_b32_e32 v36, v85, v36
	v_or_b32_e32 v49, v49, v37
	v_or_b32_e32 v51, v51, v37
	v_or_b32_e32 v53, v53, v37
	v_or_b32_e32 v55, v55, v37
	v_or_b32_e32 v57, v57, v37
	v_or_b32_e32 v79, v79, v37
	v_or_b32_e32 v81, v81, v37
	v_or_b32_e32 v83, v83, v37
	v_or_b32_e32 v37, v85, v37
	v_lshlrev_b32_e32 v85, 1, v41
	v_add_u32_e32 v94, 0, v70
	v_add_u32_e32 v96, 0, v71
	v_lshlrev_b32_e32 v97, 1, v67
	v_mad_u32_u24 v33, v33, s12, 0
	v_lshlrev_b32_e32 v101, 4, v26
	v_add_u32_e32 v155, 0xf00, v31
	v_add_u32_e32 v156, 0x1080, v31
	v_lshl_or_b32 v31, s13, 5, v41
	v_add_u32_e32 v41, s14, v46
	v_add_u32_e32 v46, s16, v46
	v_add_u32_e32 v104, s14, v70
	v_add_u32_e32 v105, s16, v70
	v_add_u32_e32 v106, s14, v71
	v_add_u32_e32 v107, s16, v71
	s_add_u32 s12, s0, 4.0
	v_add_u32_e32 v109, s14, v108
	v_lshlrev_b32_e32 v110, 4, v32
	v_lshlrev_b32_e32 v32, 3, v32
	v_add_u32_e32 v111, s14, v29
	v_lshlrev_b64 v[70:71], 7, v[34:35]
	v_add_u32_e32 v34, s16, v108
	v_add_u32_e32 v29, s16, v29
	v_cmp_gt_i32_e64 s[40:41], s20, v26
	v_ashrrev_i32_e32 v67, 31, v66
	v_cmp_lt_i32_e64 s[44:45], 63, v26
	s_addc_u32 s13, s1, 0
	v_add_u32_e32 v157, v33, v72
	v_add_u32_e32 v161, v33, v74
	v_lshlrev_b32_e32 v72, 1, v28
	v_lshlrev_b32_e32 v74, 1, v30
	v_add_u32_e32 v166, 0, v48
	v_add_u32_e32 v167, 0, v50
	v_add_u32_e32 v168, 0, v52
	v_add_u32_e32 v169, 0, v54
	v_add_u32_e32 v170, 0, v56
	v_add_u32_e32 v171, 0, v68
	v_add_u32_e32 v172, 0, v69
	v_add_u32_e32 v173, 0, v73
	v_add_u32_e32 v174, 0, v75
	v_add_u32_e32 v175, 0, v76
	v_add_u32_e32 v176, 0, v77
	v_add_u32_e32 v177, 0, v78
	v_add_u32_e32 v178, 0, v80
	v_add_u32_e32 v179, 0, v82
	v_add_u32_e32 v180, 0, v84
	v_add_u32_e32 v181, 0, v36
	v_add_u32_e32 v182, 0, v86
	v_add_u32_e32 v183, 0, v49
	v_add_u32_e32 v184, 0, v51
	v_add_u32_e32 v185, 0, v53
	v_add_u32_e32 v186, 0, v55
	v_add_u32_e32 v187, 0, v57
	v_add_u32_e32 v188, 0, v87
	v_add_u32_e32 v189, 0, v88
	v_add_u32_e32 v190, 0, v89
	v_add_u32_e32 v191, 0, v90
	v_add_u32_e32 v192, 0, v91
	v_add_u32_e32 v193, 0, v92
	v_add_u32_e32 v199, 0, v79
	v_add_u32_e32 v200, 0, v81
	v_add_u32_e32 v201, 0, v83
	v_add_u32_e32 v202, 0, v37
	v_add_u32_e32 v203, v38, v39
	v_add_u32_e32 v204, v42, v85
	v_add_u32_e32 v205, v47, v43
	v_add_u32_e32 v206, v93, v40
	v_add_u32_e32 v207, v94, v95
	v_add_u32_e32 v208, v96, v97
	v_add_u32_e32 v209, v42, v98
	v_add_u32_e32 v210, v47, v45
	v_add_u32_e32 v211, v93, v99
	v_add_u32_e32 v212, v94, v100
	v_add_u32_e32 v213, v96, v44
	v_add_u32_e32 v214, v41, v31
	v_add_u32_e32 v215, v46, v31
	v_add_u32_e32 v216, v102, v31
	v_add_u32_e32 v217, v103, v31
	v_add_u32_e32 v218, v104, v31
	v_add_u32_e32 v219, v105, v31
	v_add_u32_e32 v220, v106, v31
	v_add_u32_e32 v221, v107, v31
	v_lshlrev_b64 v[76:77], 2, v[26:27]
	v_add_u32_e32 v222, v109, v110
	v_lshlrev_b32_e32 v78, 1, v32
	v_add_u32_e32 v223, v111, v110
	v_add_u32_e32 v224, v34, v110
	v_add_u32_e32 v225, v29, v110
	v_add_u32_e32 v226, 0, v101
	s_mov_b32 s31, s2
	s_waitcnt vmcnt(0)
	s_branch .LBB0_311

; #define LAS __attribute__((address_space(3)))
; template <bool RET> __device__ __forceinline__ void loc_load(const Ctx& X, const bf16* H, int r, LocRegs<RET>& R) {
;     const int b = r / 768, head = (r / 128) % 6, n = r % 128; const size_t m0 = (size_t)(b * SEQ + n * CH);
;     raw_load<128>(X, H, m0, (RET ? C_RV : C_HGV) + head * 128, R.rv);
;     if (!RET) { raw_load<128>(X, H, m0, C_ZF + head * 128, R.rzf); raw_load<128>(X, H, m0, C_ZB + head * 128, R.rzb); }
;     else { raw_load<64>(X, H, m0, C_RQ + head * 64, R.rq); raw_load<64>(X, H, m0, C_RK + head * 64, R.rk);
;         const float* rc = (const float*)(X.ws + WS_ROPE) + (size_t)n * CH * 32; R.c4 = *(const f32x4*)(rc + X.tid * 4); R.s4 = *(const f32x4*)(rc + SEQ * 32 + X.tid * 4); }
; }
; __device__ __forceinline__ void ret_local_item(const Ctx& X, bf16* H, int it, LocRegs<true>& R, bool has_next) {
;     ...
;         const int r = 2 * it + h; const size_t m0 = (size_t)(b * SEQ + (2 * n + h) * 64);
;         vt_store(X, VT, R.rv); raw_store<64>(X, rawq, R.rq); raw_store<64>(X, rawk, R.rk); *(LAS f32x4*)(cs + X.tid * 4) = R.c4; *(LAS f32x4*)(sn + X.tid * 4) = R.s4;
;         __builtin_amdgcn_sched_barrier(0);
;         { const int nr = h == 0 ? r + 1 : 2 * (it + X.G); if (h == 0 || has_next) loc_load<true>(X, H, nr, R); }
.LBB0_313:
	s_waitcnt vmcnt(2)
	ds_write_b16 v157, v18
	ds_write_b16_d16_hi v157, v18 offset:144
	ds_write_b16 v157, v19 offset:288
	ds_write_b16_d16_hi v157, v19 offset:432
	ds_write_b16 v157, v20 offset:576
	ds_write_b16_d16_hi v157, v20 offset:720
	ds_write_b16 v157, v21 offset:864
	ds_write_b16_d16_hi v157, v21 offset:1008
	ds_write_b16 v161, v22
	ds_write_b16_d16_hi v161, v22 offset:144
	ds_write_b16 v161, v23 offset:288
	ds_write_b16_d16_hi v161, v23 offset:432
	ds_write_b16 v161, v24 offset:576
	ds_write_b16_d16_hi v161, v24 offset:720
	ds_write_b16 v161, v25 offset:864
	ds_write_b16_d16_hi v161, v25 offset:1008
	ds_write_b128 v226, v[10:13] offset:36864
	ds_write_b128 v226, v[14:17] offset:45056
	ds_write_b128 v226, v[2:5] offset:53248
	ds_write_b128 v226, v[6:9] offset:61440
	s_or_b64 s[0:1], s[18:19], s[24:25]
	s_andn2_b64 vcc, exec, s[0:1]
	s_cbranch_vccnz .LBB0_315
	s_and_b64 s[0:1], s[24:25], exec
	s_cselect_b32 s0, s38, s39
	s_mul_hi_i32 s1, s0, 0x2aaaaaab
	s_lshr_b32 s47, s1, 31
	s_lshr_b32 s1, s1, 7
	s_add_i32 s1, s1, s47
	s_ashr_i32 s47, s0, 31
	s_lshr_b32 s47, s47, 25
	s_add_i32 s47, s0, s47
	s_ashr_i32 s48, s47, 7
	s_mul_hi_i32 s49, s48, 0x2aaaaaab
	s_lshr_b32 s50, s49, 31
	s_add_i32 s49, s49, s50
	s_and_b32 s47, s47, 0xffffff80
	s_mul_i32 s49, s49, 6
	s_sub_i32 s0, s0, s47
	s_sub_i32 s50, s48, s49
	s_lshl_b32 s1, s1, 13
	s_lshl_b32 s47, s0, 6
	s_add_i32 s48, s1, s47
	s_lshl_b32 s1, s50, 7
	s_addk_i32 s1, 0x1200
	v_add_u32_e32 v4, s1, v120
	s_ashr_i32 s49, s48, 31
	v_lshrrev_b32_e32 v158, 7, v4
	v_lshl_add_u64 v[2:3], s[48:49], 0, v[58:59]
	v_lshlrev_b64 v[4:5], 22, v[158:159]
	v_add_u32_e32 v6, s1, v121
	v_lshl_add_u64 v[4:5], s[4:5], 0, v[4:5]
	v_lshlrev_b64 v[2:3], 8, v[2:3]
	v_lshrrev_b32_e32 v158, 7, v6
	v_lshl_add_u64 v[2:3], v[4:5], 0, v[2:3]
	v_lshl_add_u64 v[4:5], s[48:49], 0, v[60:61]
	v_lshlrev_b64 v[6:7], 22, v[158:159]
	v_lshl_add_u64 v[6:7], s[4:5], 0, v[6:7]
	v_lshlrev_b64 v[4:5], 8, v[4:5]
	s_lshl_b32 s1, s50, 6
	v_mov_b32_e32 v73, v159
	v_lshl_add_u64 v[4:5], v[6:7], 0, v[4:5]
	v_mov_b32_e32 v75, v159
	v_add_u32_e32 v6, s1, v155
	v_lshl_add_u64 v[2:3], v[2:3], 0, v[72:73]
	v_lshl_add_u64 v[4:5], v[4:5], 0, v[74:75]
	v_lshrrev_b32_e32 v158, 7, v6
	global_load_dwordx4 v[18:21], v[2:3], off
	global_load_dwordx4 v[22:25], v[4:5], off
	v_lshl_add_u64 v[2:3], s[48:49], 0, v[62:63]
	v_lshlrev_b64 v[4:5], 22, v[158:159]
	v_lshl_add_u64 v[4:5], s[4:5], 0, v[4:5]
	v_lshlrev_b64 v[2:3], 8, v[2:3]
	v_and_b32_e32 v6, 0x78, v6
	v_lshl_add_u64 v[4:5], v[4:5], 0, v[2:3]
	v_lshlrev_b32_e32 v158, 1, v6
	v_add_u32_e32 v8, s1, v156
	v_lshl_add_u64 v[4:5], v[4:5], 0, v[158:159]
	v_lshrrev_b32_e32 v158, 7, v8
	v_lshlrev_b64 v[6:7], 22, v[158:159]
	v_lshl_add_u64 v[6:7], s[4:5], 0, v[6:7]
	s_ashr_i32 s1, s0, 31
	v_lshl_add_u64 v[2:3], v[6:7], 0, v[2:3]
	v_and_b32_e32 v6, 0x78, v8
	s_lshl_b64 s[0:1], s[0:1], 13
	v_lshlrev_b32_e32 v158, 1, v6
	s_add_u32 s0, s21, s0
	v_lshl_add_u64 v[2:3], v[2:3], 0, v[158:159]
	s_addc_u32 s1, s28, s1
	global_load_dwordx4 v[10:13], v[4:5], off
	global_load_dwordx4 v[14:17], v[2:3], off
	v_lshl_add_u64 v[2:3], v[64:65], 2, s[0:1]
	v_add_co_u32_e32 v6, vcc, 0x100000, v2
	s_nop 1
	v_addc_co_u32_e32 v7, vcc, 0, v3, vcc
	global_load_dwordx4 v[2:5], v[2:3], off
	s_nop 0
	global_load_dwordx4 v[6:9], v[6:7], off

; #define SP_BEGIN() unsigned long long sp0_ = 0; if (PROBE_MASK >> 16) sp0_ = __builtin_amdgcn_s_memrealtime();
; template <bool RET> __device__ __forceinline__ void out_load(const Ctx& X, const bf16* H, int r, OutRegs<RET>& R) {
;     const int b = r / 768, head = (r / 128) % 6, n = r % 128; const size_t m0 = (size_t)(b * SEQ + n * CH);
;     const int fr = X.lane & 15, fq = X.lane >> 4, tb = X.wave & 3, vh = X.wave >> 2; const size_t m = m0 + 16 * tb + fr; const int gcol = (RET ? C_RG : C_HGG) + head * 128;
;     raw_load<128>(X, H, m0, (RET ? C_RV : C_HGV) + head * 128, R.rv);
;     if (!RET) { raw_load<128>(X, H, m0, C_ZF + head * 128, R.rzf); raw_load<128>(X, H, m0, C_HGQ + head * 128, R.rq); }
;     else { raw_load<64>(X, H, m0, C_RQ + head * 64, R.rq6); raw_load<64>(X, H, m0, C_RK + head * 64, R.rk6); }
; #pragma unroll
;     for (int t = 0; t < 4; ++t) if (RET) R.gw[t] = *(const v2u*)hptr(H, m, gcol + 64 * vh + 16 * t + 4 * fq);
; }
; template <int DK, bool RET>
; __device__ __forceinline__ void gla_out_item(const Ctx& X, const bf16* H, bf16* Y, int l, int r, OutRegs<RET>& R, bool has_next) {
;     typedef L3<DK, RET> L;
;     const int b = r / 768, head = (r / 128) % 6, n = r % 128;
;     const float* LB = (const float*)(X.ws + WS_TAB);
;     const unsigned char* St = (const unsigned char*)(X.ws + WS_SHG);
;     const int fr = X.lane & 15, fq = X.lane >> 4, tb = X.wave & 3, vh = X.wave >> 2;
;     const size_t m = (size_t)(b * SEQ + n * CH + 16 * tb + fr);
;     const int ycol = (RET ? 768 : 0) + head * 128;
;     SP_BEGIN()
;     const int kp = X.tid & 63; f32x2v lb0 = (f32x2v){0.f, 0.f}, lb1 = lb0;
;     v2u gw[4];
;     if (!RET) {
;         lb0 = *(const f32x2v*)(LB + (0 * 4 + l) * 768 + head * 128 + 2 * kp); lb1 = *(const f32x2v*)(LB + (1 * 4 + l) * 768 + head * 128 + 2 * kp);
;         vt_store(X, X.lds + L::VT, R.rv); raw_store<128>(X, X.lds + L::RAW, R.rzf); raw_store<128>(X, X.lds + L::RAW + 16384, R.rq);
.LBB0_474:
	s_andn2_b64 vcc, exec, s[0:1]
	s_cbranch_vccnz .LBB0_651
	v_readlane_b32 s18, v253, 0
	v_readlane_b32 s0, v253, 6
	v_mov_b32_e32 v42, v0
	v_readlane_b32 s19, v253, 1
	v_readlane_b32 s1, v253, 7
	s_waitcnt lgkmcnt(0)
	s_load_dword s87, s[0:1], 0x0
	v_readlane_b32 s0, v254, 15
	v_readlane_b32 s1, v254, 16
	v_readfirstlane_b32 s4, v42
	s_andn2_b64 vcc, exec, s[0:1]
	s_mul_i32 s34, s86, 0x300
	s_cbranch_vccnz .LBB0_566
	v_ashrrev_i32_e32 v43, 31, v42
	s_waitcnt vmcnt(0)
	v_lshrrev_b32_e32 v2, 28, v43
	v_add_u32_e32 v2, v42, v2
	v_ashrrev_i32_e32 v44, 4, v2
	v_and_b32_e32 v2, 0x1ffffff0, v2
	v_add_u32_e32 v28, 0x200, v42
	v_sub_u32_e32 v2, v42, v2
	v_ashrrev_i32_e32 v29, 31, v28
	s_waitcnt lgkmcnt(0)
	v_lshlrev_b32_e32 v47, 3, v2
	v_lshrrev_b32_e32 v2, 28, v29
	s_load_dwordx2 s[0:1], s[18:19], 0x78
	v_add_u32_e32 v2, v28, v2
	v_ashrrev_i32_e32 v48, 4, v2
	v_and_b32_e32 v2, 0x1ffffff0, v2
	v_readlane_b32 s12, v254, 9
	v_sub_u32_e32 v2, v28, v2
	v_ashrrev_i32_e32 v49, 31, v48
	v_readlane_b32 s13, v254, 10
	v_lshlrev_b32_e32 v112, 3, v2
	v_readlane_b32 s5, v254, 13
	v_lshl_add_u64 v[4:5], v[48:49], 0, s[12:13]
	v_lshlrev_b64 v[18:19], 8, v[4:5]
	v_add_u32_e32 v2, s5, v112
	v_add_u32_e32 v4, s5, v47
	v_readlane_b32 s5, v254, 12
	s_waitcnt lgkmcnt(0)
	s_add_u32 s75, s0, 0x21800000
	s_addc_u32 s76, s1, 0
	v_add_u32_e32 v10, s5, v112
	v_add_u32_e32 v12, s5, v47
	v_readlane_b32 s5, v254, 11
	v_ashrrev_i32_e32 v2, 7, v2
	s_add_u32 s24, s0, 0x25800000
	v_add_u32_e32 v24, s5, v112
	v_ashrrev_i32_e32 v3, 31, v2
	v_lshrrev_b32_e32 v10, 7, v10
	v_mov_b32_e32 v11, v159
	v_lshrrev_b32_e32 v24, 7, v24
	v_mov_b32_e32 v25, v159
	s_addc_u32 s25, s1, 0
	v_lshlrev_b64 v[2:3], 22, v[2:3]
	v_lshlrev_b64 v[10:11], 22, v[10:11]
	v_lshlrev_b64 v[24:25], 22, v[24:25]
	v_and_b32_e32 v26, 0x78, v112
	v_lshl_add_u64 v[2:3], s[24:25], 0, v[2:3]
	v_lshl_add_u64 v[10:11], s[24:25], 0, v[10:11]
	v_lshl_add_u64 v[24:25], s[24:25], 0, v[24:25]
	v_lshl_add_u64 v[2:3], v[2:3], 0, v[18:19]
	v_lshlrev_b32_e32 v158, 1, v26
	v_ashrrev_i32_e32 v4, 7, v4
	v_lshl_add_u64 v[10:11], v[10:11], 0, v[18:19]
	v_lshl_add_u64 v[18:19], v[24:25], 0, v[18:19]
	v_add_u32_e32 v24, s5, v47
	v_ashrrev_i32_e32 v45, 31, v44
	v_lshl_add_u64 v[2:3], v[2:3], 0, v[158:159]
	v_ashrrev_i32_e32 v5, 31, v4
	v_lshl_add_u64 v[10:11], v[10:11], 0, v[158:159]
	v_lshrrev_b32_e32 v12, 7, v12
	v_mov_b32_e32 v13, v159
	v_lshl_add_u64 v[18:19], v[18:19], 0, v[158:159]
	v_lshrrev_b32_e32 v158, 7, v24
	v_lshlrev_b64 v[4:5], 22, v[4:5]
	v_lshl_add_u64 v[6:7], v[44:45], 0, s[12:13]
	v_lshlrev_b64 v[12:13], 22, v[12:13]
	v_lshlrev_b64 v[24:25], 22, v[158:159]
	v_and_b32_e32 v46, 0x78, v47
	v_lshl_add_u64 v[4:5], s[24:25], 0, v[4:5]
	v_lshlrev_b64 v[20:21], 8, v[6:7]
	v_lshl_add_u64 v[12:13], s[24:25], 0, v[12:13]
	v_lshl_add_u64 v[24:25], s[24:25], 0, v[24:25]
	v_lshl_add_u64 v[4:5], v[4:5], 0, v[20:21]
	v_lshlrev_b32_e32 v22, 1, v46
	v_mov_b32_e32 v23, v159
	v_lshl_add_u64 v[12:13], v[12:13], 0, v[20:21]
	v_lshl_add_u64 v[20:21], v[24:25], 0, v[20:21]
	v_lshl_add_u64 v[6:7], v[4:5], 0, v[22:23]
	v_lshl_add_u64 v[14:15], v[12:13], 0, v[22:23]
	v_lshl_add_u64 v[22:23], v[20:21], 0, v[22:23]
	global_load_dwordx4 v[2:5], v[2:3], off
	s_nop 0
	global_load_dwordx4 v[6:9], v[6:7], off
	s_nop 0
	global_load_dwordx4 v[10:13], v[10:11], off
	s_nop 0
	global_load_dwordx4 v[14:17], v[14:15], off
	s_nop 0
	global_load_dwordx4 v[18:21], v[18:19], off
	s_nop 0
	global_load_dwordx4 v[22:25], v[22:23], off
	s_ashr_i32 s5, s4, 6
	s_add_u32 s77, s0, 0x3a800000
	s_addc_u32 s78, s1, 0
	s_lshl_b32 s12, s5, 4
	s_lshl_b64 s[28:29], s[34:35], 2
	s_add_u32 s0, s0, s28
	v_lshlrev_b32_e32 v34, 3, v42
	s_addc_u32 s1, s1, s29
	v_and_b32_e32 v158, 0x1f8, v34
	v_lshl_add_u64 v[30:31], s[0:1], 0, v[158:159]
	s_mov_b64 s[0:1], 0x400000
	v_lshl_add_u64 v[50:51], v[30:31], 0, s[0:1]
	s_mov_b64 s[0:1], 0x403000
	v_and_b32_e32 v33, 15, v42
	v_lshl_add_u64 v[52:53], v[30:31], 0, s[0:1]
	s_movk_i32 s0, 0x480
	v_mad_u32_u24 v30, v33, s0, 0
	s_lshl_b32 s0, s5, 1
	s_ashr_i32 s13, s4, 7
	s_and_b32 s0, s0, 2
	s_cmp_le_i32 s0, s13
	s_cselect_b64 s[36:37], -1, 0
	s_xor_b32 s1, s0, s13
	s_cmp_lt_u32 s1, 2
	v_readlane_b32 s22, v252, 6
	v_readlane_b32 s23, v252, 7
	s_cselect_b32 s1, s22, s23
	s_lshl_b32 s14, s0, 4
	s_cmp_eq_u32 s13, s0
	v_mov_b32_e32 v39, s1
	s_cselect_b64 s[40:41], -1, 0
	s_lshl_b32 s1, s0, 5
	v_readlane_b32 s17, v252, 8
	s_add_i32 s1, s17, s1
	s_or_b32 s15, s0, 1
	s_cmp_lt_i32 s0, s13
	v_ashrrev_i32_e32 v35, 4, v28
	v_lshlrev_b64 v[56:57], 4, v[28:29]
	v_lshrrev_b32_e32 v28, 3, v28
	s_cselect_b64 s[38:39], -1, 0
	s_cmp_ge_i32 s0, s13
	v_bfe_u32 v29, v42, 4, 2
	v_readlane_b32 s60, v252, 5
	v_mul_lo_u32 v28, v28, s27
	s_cselect_b64 s[66:67], -1, 0
	s_lshl_b32 s16, s15, 4
	v_add_u32_e32 v37, s60, v28
	v_lshlrev_b32_e32 v28, 3, v29
	v_lshl_or_b32 v41, s13, 4, v33
	s_cmp_eq_u32 s13, s15
	v_mul_lo_u32 v58, v41, s27
	v_add_u32_e32 v63, s1, v28
	s_cselect_b64 s[48:49], -1, 0
	s_and_b32 s5, s5, 3
	s_lshl_b32 s1, s15, 5
	v_add_u32_e32 v61, 0, v58
	s_add_i32 s1, s17, s1
	v_lshl_or_b32 v60, s5, 4, v33
	v_mov_b32_e32 v58, s17
	s_movk_i32 s20, 0x90
	s_and_b32 s17, s12, 0xffffffc0
	v_mad_u32_u24 v118, v60, s20, v58
	v_or_b32_e32 v58, s17, v33
	v_mul_lo_u32 v62, v58, s20
	v_add_u32_e32 v64, s1, v28
	v_add_u32_e32 v65, 0, v62
	v_and_b32_e32 v62, 8, v42
	v_or_b32_e32 v67, 16, v33
	v_or_b32_e32 v70, 32, v33
	v_or_b32_e32 v73, 48, v33
	s_sub_i32 s1, 3, s13
	v_bitop3_b32 v66, v28, v42, 8 bitop3:0x78
	v_bitop3_b32 v69, v67, v28, 24 bitop3:0x6c
	v_bitop3_b32 v72, v70, v28, 40 bitop3:0x6c
	v_bitop3_b32 v75, v73, v28, 56 bitop3:0x6c
	v_or_b32_e32 v76, 32, v28
; #define SP_BEGIN() unsigned long long sp0_ = 0; if (PROBE_MASK >> 16) sp0_ = __builtin_amdgcn_s_memrealtime();
; template <int DK, bool RET>
; __device__ __forceinline__ void gla_out_item(const Ctx& X, const bf16* H, bf16* Y, int l, int r, OutRegs<RET>& R, bool has_next) {
;     typedef L3<DK, RET> L;
;     const int b = r / 768, head = (r / 128) % 6, n = r % 128;
;     const float* LB = (const float*)(X.ws + WS_TAB);
;     const unsigned char* St = (const unsigned char*)(X.ws + WS_SHG);
;     const int fr = X.lane & 15, fq = X.lane >> 4, tb = X.wave & 3, vh = X.wave >> 2;
;     const size_t m = (size_t)(b * SEQ + n * CH + 16 * tb + fr);
;     const int ycol = (RET ? 768 : 0) + head * 128;
;     SP_BEGIN()
;     const int kp = X.tid & 63; f32x2v lb0 = (f32x2v){0.f, 0.f}, lb1 = lb0;
;     v2u gw[4];
;     if (!RET) {
;         lb0 = *(const f32x2v*)(LB + (0 * 4 + l) * 768 + head * 128 + 2 * kp); lb1 = *(const f32x2v*)(LB + (1 * 4 + l) * 768 + head * 128 + 2 * kp);
;         vt_store(X, X.lds + L::VT, R.rv); raw_store<128>(X, X.lds + L::RAW, R.rzf); raw_store<128>(X, X.lds + L::RAW + 16384, R.rq);
;     ...
;     const float* gn = X.in(RET ? 10 : 9) + l * 768 + head * 128;
	v_bitop3_b32 v28, v28, v62, 32 bitop3:0x36
	s_xor_b32 s0, s1, s0
	v_lshlrev_b32_e32 v78, 1, v28
	v_bitop3_b32 v28, v67, v76, 24 bitop3:0x6c
	s_xor_b32 s0, s0, 2
	v_lshlrev_b32_e32 v67, 1, v28
	v_bitop3_b32 v28, v70, v76, 40 bitop3:0x6c
	s_cmp_lt_u32 s0, 2
	v_lshlrev_b32_e32 v70, 1, v28
	v_bitop3_b32 v28, v73, v76, 56 bitop3:0x6c
	s_cselect_b64 s[58:59], -1, 0
	v_lshlrev_b32_e32 v73, 1, v28
	v_or_b32_e32 v28, 0xffffffe0, v33
	s_and_b64 s[0:1], s[58:59], exec
	v_or_b32_e32 v38, s14, v33
	v_add_u32_e32 v62, s14, v28
	s_cselect_b32 s14, s22, s23
	s_cmp_le_i32 s13, s15
	s_cselect_b64 s[30:31], -1, 0
	s_cmp_lt_u32 s5, 2
	s_cselect_b64 s[50:51], -1, 0
	s_and_b64 s[0:1], s[50:51], exec
	v_readlane_b32 s1, v252, 9
	v_mad_u32_u24 v40, v38, s27, v39
	v_cndmask_b32_e64 v38, v62, v38, s[58:59]
	v_subrev_u32_e32 v62, 32, v60
	s_cselect_b32 s0, 0, s1
	v_lshlrev_b32_e32 v77, 1, v76
	v_cndmask_b32_e64 v62, v62, v60, s[50:51]
	v_mov_b32_e32 v76, s0
	v_ashrrev_i32_e32 v31, 4, v42
	v_lshlrev_b32_e32 v29, 2, v29
	v_or_b32_e32 v59, s16, v33
	v_mad_i32_i24 v62, v62, s27, v76
	v_mul_lo_u32 v76, v58, s27
	v_lshrrev_b32_e32 v58, 2, v42
	v_add_u32_e32 v28, s16, v28
	v_and_b32_e32 v27, 63, v42
	v_readlane_b32 s21, v252, 4
	v_bitop3_b32 v31, v34, v31, 56 bitop3:0x6c
	v_bitop3_b32 v34, v35, v34, 56 bitop3:0x78
	v_lshrrev_b32_e32 v35, 3, v42
	v_sub_u32_e32 v29, v33, v29
	v_and_or_b32 v58, v58, 12, s17
	v_mov_b32_e32 v80, s14
	v_cndmask_b32_e64 v28, v28, v59, s[58:59]
	s_cselect_b32 s0, s1, 0
	s_andn2_b32 s4, s4, 63
	v_lshl_add_u32 v32, v27, 2, s21
	v_and_or_b32 v113, s12, 48, v33
	v_lshlrev_b64 v[54:55], 4, v[42:43]
	v_mul_lo_u32 v35, v35, s27
	v_lshlrev_b32_e32 v36, 5, v42
	v_and_b32_e32 v43, 48, v42
	v_cmp_gt_i32_e64 s[42:43], 0, v29
	v_cmp_gt_i32_e64 s[44:45], 1, v29
	v_cmp_gt_i32_e64 s[46:47], 2, v29
	v_cmp_gt_i32_e32 vcc, 3, v29
	v_add_u32_e32 v119, 0xc00, v58
	v_cmp_lt_i32_e64 s[50:51], 0, v29
	v_cmp_lt_i32_e64 s[52:53], 1, v29
	v_cmp_lt_i32_e64 s[54:55], 2, v29
	v_cmp_lt_i32_e64 s[56:57], 3, v29
	v_mad_i32_i24 v29, v28, s27, v80
	v_mov_b32_e32 v28, s0
	v_cmp_gt_u32_e64 s[58:59], 16, v27
	s_add_i32 s0, s21, s4
	v_bitop3_b32 v27, s12, 64, v33 bitop3:0x36
	v_lshlrev_b32_e32 v123, 1, v58
	v_lshlrev_b32_e32 v31, 1, v31
	v_lshlrev_b32_e32 v34, 1, v34
	v_add_u32_e32 v35, s60, v35
	v_and_b32_e32 v36, 0xe0, v36
	v_mad_u32_u24 v39, v59, s27, v39
	v_lshlrev_b32_e32 v66, 1, v66
	v_add_u32_e32 v68, 0x900, v65
	v_lshlrev_b32_e32 v69, 1, v69
	v_add_u32_e32 v71, 0x1200, v65
	v_lshlrev_b32_e32 v72, 1, v72
	v_add_u32_e32 v74, 0x1b00, v65
	v_lshlrev_b32_e32 v75, 1, v75
	v_add_u32_e32 v79, s60, v43
	v_mad_i32_i24 v38, v38, s27, v80
	v_mad_u32_u24 v80, v60, s27, v28
	v_lshl_add_u32 v120, v33, 2, s0
	v_lshl_add_u32 v121, v27, 2, s21
	v_mad_u32_u24 v122, v113, s27, 0
	v_or_b32_e32 v27, 32, v123
	v_or_b32_e32 v33, 64, v123
	v_or_b32_e32 v81, 0x60, v123
	v_mul_lo_u32 v41, v41, s20
	v_add_u32_e32 v124, s60, v76
	v_and_b32_e32 v28, 0x4c, v119
	v_lshlrev_b32_e32 v114, 4, v42
	v_or_b32_e32 v115, 64, v43
	v_or_b32_e32 v116, 0x80, v43
	v_or_b32_e32 v117, 0xc0, v43
	v_ashrrev_i32_e32 v59, 31, v58
	s_and_b64 s[16:17], s[40:41], vcc
	s_and_b64 s[22:23], s[48:49], vcc
	v_add_u32_e32 v125, 0x1100, v124
	v_add_u32_e32 v126, 0x2200, v124
	v_add_u32_e32 v127, 0x3300, v124
	s_lshl_b32 s79, s87, 6
	v_add_u32_e32 v128, v30, v31
	v_add_u32_e32 v129, v30, v34
	v_lshlrev_b32_e32 v60, 1, v26
	v_add_u32_e32 v130, v40, v43
	v_add_u32_e32 v131, v39, v43
	v_add_u32_e32 v132, v62, v43
	v_lshlrev_b32_e32 v62, 1, v28
	v_add_u32_e32 v133, v38, v43
	v_add_u32_e32 v134, v29, v43
	v_add_u32_e32 v135, v80, v43
	v_add_u32_e32 v136, s4, v32
	v_add_u32_e32 v137, v122, v27
	v_add_u32_e32 v138, v122, v33
	v_add_u32_e32 v139, v122, v81
	v_add_u32_e32 v140, v35, v36
	v_add_u32_e32 v141, v37, v36
	v_add_u32_e32 v142, v61, v43
	v_add_u32_e32 v143, v63, v41
	v_add_u32_e32 v144, v64, v41
	v_add_u32_e32 v145, v65, v66
	v_add_u32_e32 v146, v68, v69
	v_add_u32_e32 v147, v71, v72
	v_add_u32_e32 v148, v74, v75
	v_add_u32_e32 v149, v118, v77
	v_add_u32_e32 v150, v65, v78
	v_add_u32_e32 v151, v68, v67
	v_add_u32_e32 v152, v71, v70
	v_add_u32_e32 v153, v74, v73
	v_add_u32_e32 v154, v79, v76
	v_readlane_b32 s80, v254, 60
	s_mov_b32 s0, s2
	s_load_dwordx2 s[100:101], s[18:19], 0x48
	s_waitcnt lgkmcnt(0)
	s_add_u32 s100, s100, s28
	s_addc_u32 s101, s101, s29
	v_lshl_add_u64 v[242:243], v[58:59], 2, s[100:101]
	s_ashr_i32 s100, s0, 7
	s_mul_hi_i32 s101, s100, 0x2aaaaaab
	s_mul_i32 s101, s101, 6
	s_sub_i32 s100, s100, s101
	s_lshl_b32 s100, s100, 9
	s_mov_b32 s101, 0
	v_lshl_add_u64 v[222:223], v[52:53], 0, s[100:101]
	v_lshl_add_u64 v[224:225], v[50:51], 0, s[100:101]
	global_load_dwordx2 v[222:223], v[222:223], off
	global_load_dwordx2 v[224:225], v[224:225], off
	s_waitcnt vmcnt(0)
	s_branch .LBB0_478
; #define LAS __attribute__((address_space(3)))
; #define BAR_LDS() do { asm volatile("s_waitcnt lgkmcnt(0)" ::: "memory"); __builtin_amdgcn_s_barrier(); asm volatile("" ::: "memory"); } while (0)
; __device__ __forceinline__ float bf2f(unsigned h) { return __uint_as_float(h << 16); }
; __device__ __forceinline__ unsigned pk2(float lo, float hi) { return pg8::cvt_pk_bf16(lo, hi); }
; template <int DK, bool RET>
; __device__ __forceinline__ void gla_out_item(const Ctx& X, const bf16* H, bf16* Y, int l, int r, OutRegs<RET>& R, bool has_next) {
;     ...
;     const float rstd = __builtin_amdgcn_rsqf((red[X.wave * 16 + fr] + red[(X.wave ^ 4) * 16 + fr]) * (1.0f / 128.0f) + EPS);
;     const float* gn = X.in(RET ? 10 : 9) + l * 768 + head * 128;
; #pragma unroll
;     for (int t = 0; t < 4; ++t) { const int v = 64 * vh + 16 * t + 4 * fq; const f32x4 g4 = *(const f32x4*)(gn + v);
;         const float g0 = bf2f(gw[t].x & 0xffffu), g1 = bf2f(gw[t].x >> 16), g2 = bf2f(gw[t].y & 0xffffu), g3 = bf2f(gw[t].y >> 16);
;         const float y0 = (o[t][0] - mu) * rstd * g4.x * (g0 * __builtin_amdgcn_rcpf(1.0f + __expf(-g0))), y1 = (o[t][1] - mu) * rstd * g4.y * (g1 * __builtin_amdgcn_rcpf(1.0f + __expf(-g1)));
;         const float y2 = (o[t][2] - mu) * rstd * g4.z * (g2 * __builtin_amdgcn_rcpf(1.0f + __expf(-g2))), y3 = (o[t][3] - mu) * rstd * g4.w * (g3 * __builtin_amdgcn_rcpf(1.0f + __expf(-g3)));
;         v2u w; w.x = pk2(y0, y1); w.y = pk2(y2, y3); *(LAS v2u*)(X.lds + L::Q0 + (16 * tb + fr) * 272 + v * 2) = w; }
;     BAR_LDS();
;     { const size_t mrow = (size_t)(b * SEQ + n * CH); int t_ = X.tid; asm volatile("" : "+v"(t_));
; #pragma unroll
;         for (int p = 0; p < 2; ++p) { const int idx = t_ + NTHR * p, row = idx >> 4, c8 = idx & 15; *(v4u*)(Y + (mrow + row) * D + ycol + 8 * c8) = *(const LAS v4u*)(X.lds + L::Q0 + row * 272 + c8 * 16); } }
;     BAR_LDS();
.LBB0_477:
	s_or_b64 exec, exec, s[0:1]
	s_waitcnt lgkmcnt(0)
	s_barrier
	s_waitcnt vmcnt(0)
	ds_read_b32 v61, v120
	s_waitcnt lgkmcnt(1)
	ds_read_b32 v63, v121
	s_load_dwordx2 s[0:1], s[18:19], 0x48
	v_lshlrev_b32_e32 v80, 16, v72
	v_and_b32_e32 v81, 0xffff0000, v72
	v_lshlrev_b32_e32 v72, 16, v73
	s_waitcnt lgkmcnt(0)
	v_add_f32_e32 v61, v61, v63
	s_add_u32 s0, s0, s28
	s_addc_u32 s1, s1, s29
	s_add_u32 s0, s0, s12
	s_addc_u32 s1, s1, s13
	v_lshl_add_u64 v[74:75], v[58:59], 2, s[0:1]
	v_mov_b32_e32 v76, v226
	v_mov_b32_e32 v77, v227
	v_mov_b32_e32 v78, v228
	v_mov_b32_e32 v79, v229
	v_mov_b32_e32 v200, v230
	v_mov_b32_e32 v201, v231
	v_mov_b32_e32 v202, v232
	v_mov_b32_e32 v203, v233
	v_mov_b32_e32 v204, v234
	v_mov_b32_e32 v205, v235
	v_mov_b32_e32 v206, v236
	v_mov_b32_e32 v207, v237
	v_mov_b32_e32 v208, v238
	v_mov_b32_e32 v209, v239
	v_mov_b32_e32 v210, v240
	v_mov_b32_e32 v211, v241
	v_fmamk_f32 v61, v61, 0x3c000000, v1
	v_rsq_f32_e32 v66, v61
	v_mul_f32_e32 v61, 0xbfb8aa3b, v80
	v_exp_f32_e32 v61, v61
	v_and_b32_e32 v73, 0xffff0000, v73
	v_pk_mul_f32 v[38:39], v[38:39], v[66:67] op_sel_hi:[1,0]
	v_pk_mul_f32 v[40:41], v[40:41], v[66:67] op_sel_hi:[1,0]
	v_add_f32_e32 v61, 1.0, v61
	v_rcp_f32_e32 v82, v61
	v_mul_f32_e32 v61, 0xbfb8aa3b, v81
	v_exp_f32_e32 v61, v61
	v_pk_mul_f32 v[34:35], v[34:35], v[66:67] op_sel_hi:[1,0]
	v_pk_mul_f32 v[36:37], v[36:37], v[66:67] op_sel_hi:[1,0]
	v_pk_mul_f32 v[30:31], v[30:31], v[66:67] op_sel_hi:[1,0]
	v_add_f32_e32 v61, 1.0, v61
	v_rcp_f32_e32 v83, v61
	v_mul_f32_e32 v61, 0xbfb8aa3b, v72
	v_exp_f32_e32 v61, v61
	v_pk_mul_f32 v[32:33], v[32:33], v[66:67] op_sel_hi:[1,0]
	v_pk_mul_f32 v[26:27], v[26:27], v[66:67] op_sel_hi:[1,0]
	v_pk_mul_f32 v[28:29], v[28:29], v[66:67] op_sel_hi:[1,0]
	v_add_f32_e32 v61, 1.0, v61
	s_lshl_b64 s[0:1], s[14:15], 1
	s_add_u32 s0, s75, s0
	s_addc_u32 s1, s76, s1
	s_add_i32 s80, s80, s79
	s_and_b64 vcc, exec, s[4:5]
	s_waitcnt vmcnt(3)
	v_pk_mul_f32 v[38:39], v[76:77], v[38:39]
	v_pk_mul_f32 v[76:77], v[82:83], v[80:81]
	v_pk_mul_f32 v[40:41], v[78:79], v[40:41]
	v_pk_mul_f32 v[38:39], v[76:77], v[38:39]
	v_rcp_f32_e32 v76, v61
	v_mul_f32_e32 v61, 0xbfb8aa3b, v73
	v_exp_f32_e32 v61, v61
	v_cvt_pk_bf16_f32 v38, v38, v39
	v_add_f32_e32 v61, 1.0, v61
	v_rcp_f32_e32 v77, v61
	s_nop 0
	v_pk_mul_f32 v[72:73], v[76:77], v[72:73]
	s_nop 0
	v_pk_mul_f32 v[40:41], v[72:73], v[40:41]
	v_lshlrev_b32_e32 v72, 16, v70
	v_cvt_pk_bf16_f32 v39, v40, v41
	v_add_u32_e32 v40, v122, v123
	ds_write_b64 v40, v[38:39]
	v_and_b32_e32 v73, 0xffff0000, v70
	v_mul_f32_e32 v61, 0xbfb8aa3b, v72
	v_exp_f32_e32 v61, v61
	s_waitcnt vmcnt(2)
	v_pk_mul_f32 v[34:35], v[34:35], v[200:201]
	v_mul_f32_e32 v38, 0xbfb8aa3b, v73
	v_exp_f32_e32 v38, v38
	v_add_f32_e32 v61, 1.0, v61
	v_rcp_f32_e32 v76, v61
	v_pk_mul_f32 v[36:37], v[36:37], v[202:203]
	v_add_f32_e32 v38, 1.0, v38
	v_rcp_f32_e32 v77, v38
	s_nop 0
	v_pk_mul_f32 v[38:39], v[76:77], v[72:73]
	s_nop 0
	v_pk_mul_f32 v[34:35], v[38:39], v[34:35]
	v_lshlrev_b32_e32 v38, 16, v71
	v_and_b32_e32 v39, 0xffff0000, v71
	v_mul_f32_e32 v61, 0xbfb8aa3b, v38
	v_mul_f32_e32 v40, 0xbfb8aa3b, v39
	v_exp_f32_e32 v61, v61
	v_exp_f32_e32 v40, v40
	v_cvt_pk_bf16_f32 v34, v34, v35
	v_add_f32_e32 v61, 1.0, v61
	v_add_f32_e32 v40, 1.0, v40
	v_rcp_f32_e32 v70, v61
	v_rcp_f32_e32 v71, v40
	s_nop 0
	v_pk_mul_f32 v[38:39], v[70:71], v[38:39]
	s_nop 0
	v_pk_mul_f32 v[36:37], v[38:39], v[36:37]
	v_lshlrev_b32_e32 v38, 16, v68
	v_cvt_pk_bf16_f32 v35, v36, v37
	ds_write_b64 v137, v[34:35]
	v_and_b32_e32 v39, 0xffff0000, v68
	v_mul_f32_e32 v40, 0xbfb8aa3b, v38
	v_exp_f32_e32 v40, v40
	s_waitcnt vmcnt(1)
	v_pk_mul_f32 v[30:31], v[30:31], v[204:205]
	v_mul_f32_e32 v34, 0xbfb8aa3b, v39
	v_exp_f32_e32 v34, v34
	v_add_f32_e32 v40, 1.0, v40
	v_rcp_f32_e32 v40, v40
	v_pk_mul_f32 v[32:33], v[32:33], v[206:207]
	v_add_f32_e32 v34, 1.0, v34
	v_rcp_f32_e32 v41, v34
	s_nop 0
	v_pk_mul_f32 v[34:35], v[40:41], v[38:39]
	s_nop 0
	v_pk_mul_f32 v[30:31], v[34:35], v[30:31]
	v_lshlrev_b32_e32 v34, 16, v69
	v_and_b32_e32 v35, 0xffff0000, v69
	v_mul_f32_e32 v38, 0xbfb8aa3b, v34
	v_mul_f32_e32 v36, 0xbfb8aa3b, v35
	v_exp_f32_e32 v38, v38
	v_exp_f32_e32 v36, v36
	v_cvt_pk_bf16_f32 v30, v30, v31
	v_add_f32_e32 v38, 1.0, v38
	v_add_f32_e32 v36, 1.0, v36
	v_rcp_f32_e32 v38, v38
	v_rcp_f32_e32 v39, v36
	s_nop 0
	v_pk_mul_f32 v[34:35], v[38:39], v[34:35]
	s_nop 0
	v_pk_mul_f32 v[32:33], v[34:35], v[32:33]
	v_lshlrev_b32_e32 v34, 16, v64
	v_cvt_pk_bf16_f32 v31, v32, v33
	ds_write_b64 v138, v[30:31]
	v_and_b32_e32 v35, 0xffff0000, v64
	v_mul_f32_e32 v36, 0xbfb8aa3b, v34
	v_exp_f32_e32 v36, v36
	s_waitcnt vmcnt(0)
	v_pk_mul_f32 v[26:27], v[26:27], v[208:209]
	v_mul_f32_e32 v30, 0xbfb8aa3b, v35
	v_exp_f32_e32 v30, v30
	v_add_f32_e32 v36, 1.0, v36
	v_rcp_f32_e32 v36, v36
	v_pk_mul_f32 v[28:29], v[28:29], v[210:211]
	v_add_f32_e32 v30, 1.0, v30
	v_rcp_f32_e32 v37, v30
	s_nop 0
	v_pk_mul_f32 v[30:31], v[36:37], v[34:35]
	s_nop 0
	v_pk_mul_f32 v[26:27], v[30:31], v[26:27]
	v_lshlrev_b32_e32 v30, 16, v65
	v_and_b32_e32 v31, 0xffff0000, v65
	v_mul_f32_e32 v34, 0xbfb8aa3b, v30
	v_mul_f32_e32 v32, 0xbfb8aa3b, v31
	v_exp_f32_e32 v34, v34
	v_exp_f32_e32 v32, v32
	v_cvt_pk_bf16_f32 v26, v26, v27
	v_add_f32_e32 v34, 1.0, v34
	v_add_f32_e32 v32, 1.0, v32
	v_rcp_f32_e32 v34, v34
	v_rcp_f32_e32 v35, v32
	s_nop 0
	v_pk_mul_f32 v[30:31], v[34:35], v[30:31]
	s_nop 0
	v_pk_mul_f32 v[28:29], v[30:31], v[28:29]
	v_mov_b32_e32 v34, v42
	v_cvt_pk_bf16_f32 v27, v28, v29
	ds_write_b64 v139, v[26:27]
	s_waitcnt lgkmcnt(0)
	s_barrier
	s_nop 0
	v_lshlrev_b32_e32 v26, 4, v34
	v_ashrrev_i32_e32 v32, 4, v34
	v_and_b32_e32 v158, 0xf0, v26
	v_mul_lo_u32 v26, v32, s27
	v_add3_u32 v26, 0, v26, v158
	ds_read_b128 v[26:29], v26
	v_ashrrev_i32_e32 v33, 31, v32
	v_lshl_add_u64 v[32:33], v[32:33], 0, s[68:69]
	v_lshl_add_u64 v[30:31], s[0:1], 0, v[158:159]
	v_lshlrev_b64 v[32:33], 12, v[32:33]
	v_lshl_add_u64 v[32:33], v[30:31], 0, v[32:33]
	s_waitcnt lgkmcnt(0)
	global_store_dwordx4 v[32:33], v[26:29], off
	s_mov_b32 s0, s81
	s_nop 0
	v_add_u32_e32 v26, 0x200, v34
	v_ashrrev_i32_e32 v32, 4, v26
	v_mul_lo_u32 v26, v32, s27
	v_add3_u32 v26, 0, v26, v158
	ds_read_b128 v[26:29], v26
	v_ashrrev_i32_e32 v33, 31, v32
	v_lshl_add_u64 v[32:33], v[32:33], 0, s[68:69]
	v_lshlrev_b64 v[32:33], 12, v[32:33]
	v_lshl_add_u64 v[30:31], v[30:31], 0, v[32:33]
	s_waitcnt lgkmcnt(0)
	global_store_dwordx4 v[30:31], v[26:29], off
	s_waitcnt lgkmcnt(0)
	s_barrier
	s_cbranch_vccnz .LBB0_566
; #define SP_BEGIN() unsigned long long sp0_ = 0; if (PROBE_MASK >> 16) sp0_ = __builtin_amdgcn_s_memrealtime();
; template <int DK, bool RET>
; __device__ __forceinline__ void gla_out_item(const Ctx& X, const bf16* H, bf16* Y, int l, int r, OutRegs<RET>& R, bool has_next) {
;     typedef L3<DK, RET> L;
;     const int b = r / 768, head = (r / 128) % 6, n = r % 128;
;     const float* LB = (const float*)(X.ws + WS_TAB);
;     const unsigned char* St = (const unsigned char*)(X.ws + WS_SHG);
;     const int fr = X.lane & 15, fq = X.lane >> 4, tb = X.wave & 3, vh = X.wave >> 2;
;     const size_t m = (size_t)(b * SEQ + n * CH + 16 * tb + fr);
;     const int ycol = (RET ? 768 : 0) + head * 128;
;     SP_BEGIN()
;     const int kp = X.tid & 63; f32x2v lb0 = (f32x2v){0.f, 0.f}, lb1 = lb0;
;     v2u gw[4];
;     if (!RET) {
;         lb0 = *(const f32x2v*)(LB + (0 * 4 + l) * 768 + head * 128 + 2 * kp); lb1 = *(const f32x2v*)(LB + (1 * 4 + l) * 768 + head * 128 + 2 * kp);
;         vt_store(X, X.lds + L::VT, R.rv); raw_store<128>(X, X.lds + L::RAW, R.rzf); raw_store<128>(X, X.lds + L::RAW + 16384, R.rq);
;     } else {
;         vt_store(X, X.lds + L::VT, R.rv); raw_store<64>(X, X.lds + L::RAW, R.rq6); raw_store<64>(X, X.lds + L::RAW + 8192, R.rk6);
;     }
;     asm volatile("" : "+v"(lb0), "+v"(lb1)); __builtin_amdgcn_sched_barrier(0);
;     if (has_next) out_load<RET>(X, H, r + X.G, R);
.LBB0_478:
	s_add_i32 s81, s0, s87
	s_cmpk_gt_i32 s81, 0x5ff
	s_cselect_b64 s[4:5], -1, 0
	s_ashr_i32 s1, s0, 31
	s_lshr_b32 s1, s1, 25
	s_add_i32 s1, s0, s1
	s_ashr_i32 s83, s1, 7
	s_mul_hi_i32 s1, s83, 0x2aaaaaab
	s_lshr_b32 s12, s1, 31
	s_add_i32 s1, s1, s12
	s_mul_i32 s1, s1, 6
	s_sub_i32 s1, s83, s1
	s_lshl_b32 s14, s1, 7
	s_ashr_i32 s15, s14, 31
	s_lshl_b64 s[12:13], s[14:15], 2
	v_lshl_add_u64 v[244:245], v[242:243], 0, s[12:13]
	global_load_dwordx4 v[226:229], v[244:245], off
	global_load_dwordx4 v[230:233], v[244:245], off offset:64
	global_load_dwordx4 v[234:237], v[244:245], off offset:128
	global_load_dwordx4 v[238:241], v[244:245], off offset:192
	v_add_u32_e32 v26, 0, v114
	v_add_u32_e32 v27, 0x14c00, v26
	s_mov_b64 s[20:21], s[64:65]
	s_mov_b64 s[64:65], s[84:85]
	s_waitcnt vmcnt(6)
	ds_write_b16 v128, v22 offset:52224
	ds_write_b16_d16_hi v128, v22 offset:52368
	ds_write_b16 v128, v23 offset:52512
	ds_write_b16_d16_hi v128, v23 offset:52656
	ds_write_b16 v128, v24 offset:52800
	ds_write_b16_d16_hi v128, v24 offset:52944
	ds_write_b16 v128, v25 offset:53088
	ds_write_b16_d16_hi v128, v25 offset:53232
	ds_write_b16 v129, v18 offset:52224
	ds_write_b16_d16_hi v129, v18 offset:52368
	ds_write_b16 v129, v19 offset:52512
	ds_write_b16_d16_hi v129, v19 offset:52656
	ds_write_b16 v129, v20 offset:52800
	ds_write_b16_d16_hi v129, v20 offset:52944
	ds_write_b16 v129, v21 offset:53088
	ds_write_b16_d16_hi v129, v21 offset:53232
	ds_write_b128 v27, v[14:17]
	v_add_u32_e32 v63, 0x16c00, v26
	v_add_u32_e32 v27, 0x18c00, v26
	v_add_u32_e32 v26, 0x1ac00, v26
	ds_write_b128 v63, v[10:13]
	ds_write_b128 v27, v[6:9]
	ds_write_b128 v26, v[2:5]
	v_mov_b32_e32 v66, v222
	v_mov_b32_e32 v67, v223
	v_mov_b32_e32 v86, v224
	v_mov_b32_e32 v87, v225
	s_and_b64 vcc, exec, s[4:5]
	v_lshlrev_b32_e32 v34, 1, v46
	s_cbranch_vccnz .LBB0_480
	s_mul_hi_i32 s60, s81, 0x2aaaaaab
	s_lshr_b32 s61, s60, 31
	s_lshr_b32 s60, s60, 7
	s_add_i32 s60, s60, s61
	s_ashr_i32 s61, s81, 31
	s_lshr_b32 s61, s61, 25
	s_add_i32 s61, s81, s61
	s_ashr_i32 s61, s61, 7
	s_mul_hi_i32 s62, s61, 0x2aaaaaab
	s_lshr_b32 s63, s62, 31
	s_add_i32 s62, s62, s63
	s_mul_i32 s62, s62, 6
	s_sub_i32 s62, s61, s62
	s_lshl_b32 s60, s60, 13
	s_lshl_b32 s61, s61, 13
	s_lshl_b32 s62, s62, 7
	s_lshl_b32 s100, s62, 2
	s_mov_b32 s101, 0
	v_lshl_add_u64 v[222:223], v[52:53], 0, s[100:101]
	v_lshl_add_u64 v[224:225], v[50:51], 0, s[100:101]
	global_load_dwordx2 v[222:223], v[222:223], off
	global_load_dwordx2 v[224:225], v[224:225], off
	s_sub_i32 s60, s60, s61
	s_add_i32 s61, s79, s80
	s_add_i32 s63, s62, 0x300
	s_add_i32 s60, s61, s60
	v_add_u32_e32 v4, s63, v47
	s_ashr_i32 s61, s60, 31
	v_lshrrev_b32_e32 v158, 7, v4
	v_add_u32_e32 v8, s63, v112
	v_lshl_add_u64 v[2:3], s[60:61], 0, v[44:45]
	v_lshlrev_b64 v[4:5], 22, v[158:159]
	v_lshrrev_b32_e32 v158, 7, v8
	v_lshl_add_u64 v[4:5], s[24:25], 0, v[4:5]
	v_lshlrev_b64 v[2:3], 8, v[2:3]
	v_lshl_add_u64 v[6:7], s[60:61], 0, v[48:49]
	v_lshlrev_b64 v[8:9], 22, v[158:159]
	v_lshl_add_u64 v[4:5], v[4:5], 0, v[2:3]
	v_mov_b32_e32 v35, v159
	v_lshl_add_u64 v[8:9], s[24:25], 0, v[8:9]
	v_lshlrev_b64 v[6:7], 8, v[6:7]
	v_lshl_add_u64 v[4:5], v[4:5], 0, v[34:35]
	v_lshl_add_u64 v[8:9], v[8:9], 0, v[6:7]
	v_mov_b32_e32 v61, v159
	s_add_i32 s60, s62, 0x600
	v_lshl_add_u64 v[8:9], v[8:9], 0, v[60:61]
	global_load_dwordx4 v[22:25], v[4:5], off
	global_load_dwordx4 v[18:21], v[8:9], off
	v_add_u32_e32 v4, s60, v47
	v_lshrrev_b32_e32 v158, 7, v4
	v_add_u32_e32 v8, s60, v112
	v_lshlrev_b64 v[4:5], 22, v[158:159]
	v_lshrrev_b32_e32 v158, 7, v8
	v_lshl_add_u64 v[4:5], s[24:25], 0, v[4:5]
	v_lshlrev_b64 v[8:9], 22, v[158:159]
	v_lshl_add_u64 v[4:5], v[4:5], 0, v[2:3]
	v_lshl_add_u64 v[8:9], s[24:25], 0, v[8:9]
	v_lshl_add_u64 v[4:5], v[4:5], 0, v[34:35]
	v_lshl_add_u64 v[8:9], v[8:9], 0, v[6:7]
	v_lshl_add_u64 v[8:9], v[8:9], 0, v[60:61]
	global_load_dwordx4 v[14:17], v[4:5], off
	global_load_dwordx4 v[10:13], v[8:9], off
	v_add_u32_e32 v4, s62, v47
	v_ashrrev_i32_e32 v4, 7, v4
	v_ashrrev_i32_e32 v5, 31, v4
	v_lshlrev_b64 v[4:5], 22, v[4:5]
	v_lshl_add_u64 v[4:5], s[24:25], 0, v[4:5]
	v_lshl_add_u64 v[2:3], v[4:5], 0, v[2:3]
	v_add_u32_e32 v4, s62, v112
	v_ashrrev_i32_e32 v4, 7, v4
	v_ashrrev_i32_e32 v5, 31, v4
	v_lshlrev_b64 v[4:5], 22, v[4:5]
	v_lshl_add_u64 v[4:5], s[24:25], 0, v[4:5]
	v_lshl_add_u64 v[4:5], v[4:5], 0, v[6:7]
	v_lshl_add_u64 v[2:3], v[2:3], 0, v[34:35]
	v_lshl_add_u64 v[4:5], v[4:5], 0, v[60:61]
	global_load_dwordx4 v[6:9], v[2:3], off
	s_nop 0
	global_load_dwordx4 v[2:5], v[4:5], off

; __device__ __forceinline__ void ret_out_load(const Ctx& X, const bf16* H, int it, RetOutRegs& R) {
;     const int b = it / 384, head = (it / 64) % 6, n = it % 64; const size_t m0 = (size_t)(b * SEQ + n * RCH);
;     const int fr = X.lane & 15, fq = X.lane >> 4, tbq = X.wave & 3, vh = X.wave >> 2;
; #pragma unroll
;     for (int p = 0; p < 2; ++p) { const int idx = X.tid + NTHR * p, row = idx >> 3, c8 = idx & 7; R.q[p] = *(const v4u*)hptr(H, m0 + row, C_RQ + head * 64 + 8 * c8); R.k[p] = *(const v4u*)hptr(H, m0 + row, C_RK + head * 64 + 8 * c8); }
; #pragma unroll
;     for (int p = 0; p < 4; ++p) { const int idx = X.tid + NTHR * p, row = idx >> 4, c8 = idx & 15; R.v[p] = *(const v4u*)hptr(H, m0 + row, C_RV + head * 128 + 8 * c8); }
; }
.LBB0_566:
	v_readlane_b32 s0, v254, 22
	v_mov_b32_e32 v35, v0
	v_readlane_b32 s4, v253, 0
	v_readlane_b32 s1, v254, 23
	v_readlane_b32 s80, v252, 26
	v_readlane_b32 s82, v252, 28
	v_readlane_b32 s5, v253, 1
	s_andn2_b64 vcc, exec, s[0:1]
	v_readfirstlane_b32 s36, v35
	v_readlane_b32 s81, v252, 27
	v_readlane_b32 s83, v252, 29
	s_mov_b64 s[60:61], s[90:91]
	s_movk_i32 s20, 0x100
	s_cbranch_vccnz .LBB0_597
	s_load_dwordx2 s[0:1], s[4:5], 0x78
	s_waitcnt vmcnt(0)
	v_add_u32_e32 v2, 0x200, v35
	v_ashrrev_i32_e32 v104, 3, v2
	v_ashrrev_i32_e32 v108, 4, v2
	v_add_u32_e32 v2, 0x400, v35
	s_waitcnt lgkmcnt(0)
	s_add_u32 s28, s0, 0x21800000
	s_addc_u32 s29, s1, 0
	v_ashrrev_i32_e32 v110, 4, v2
	v_add_u32_e32 v2, 0x600, v35
	s_add_u32 s14, s0, 0x25800000
	v_ashrrev_i32_e32 v106, 4, v35
	v_ashrrev_i32_e32 v112, 4, v2
	v_readlane_b32 s18, v254, 34
	s_addc_u32 s15, s1, 0
	v_ashrrev_i32_e32 v107, 31, v106
	v_ashrrev_i32_e32 v109, 31, v108
	v_ashrrev_i32_e32 v111, 31, v110
	v_ashrrev_i32_e32 v113, 31, v112
	v_readlane_b32 s12, v254, 37
	v_readlane_b32 s19, v254, 35
	v_readlane_b32 s13, v254, 38
	s_add_u32 s12, s14, s12
	v_lshl_add_u64 v[2:3], v[112:113], 0, s[18:19]
	v_lshl_add_u64 v[4:5], v[110:111], 0, s[18:19]
	v_lshl_add_u64 v[10:11], v[108:109], 0, s[18:19]
	v_lshl_add_u64 v[12:13], v[106:107], 0, s[18:19]
	s_addc_u32 s13, s15, s13
	v_lshlrev_b64 v[2:3], 8, v[2:3]
	v_lshlrev_b64 v[4:5], 8, v[4:5]
	v_lshlrev_b64 v[10:11], 8, v[10:11]
	v_lshlrev_b64 v[12:13], 8, v[12:13]
	v_lshlrev_b32_e32 v36, 3, v35
	v_lshl_add_u64 v[2:3], s[12:13], 0, v[2:3]
	v_lshl_add_u64 v[4:5], s[12:13], 0, v[4:5]
	v_lshl_add_u64 v[10:11], s[12:13], 0, v[10:11]
	v_lshl_add_u64 v[12:13], s[12:13], 0, v[12:13]
	v_readlane_b32 s12, v254, 32
	v_ashrrev_i32_e32 v102, 3, v35
	v_and_b32_e32 v117, 56, v36
	v_readlane_b32 s13, v254, 33
	s_add_u32 s12, s14, s12
	v_readlane_b32 s16, v254, 36
	v_ashrrev_i32_e32 v103, 31, v102
	v_ashrrev_i32_e32 v105, 31, v104
	s_addc_u32 s13, s15, s13
	v_or_b32_e32 v22, s16, v117
	v_readlane_b32 s16, v254, 29
	v_and_b32_e32 v34, 0x78, v36
	v_lshl_add_u64 v[18:19], v[104:105], 0, s[18:19]
	v_readlane_b32 s17, v254, 30
	s_add_u32 s16, s14, s16
	v_lshl_add_u64 v[26:27], v[102:103], 0, s[18:19]
	v_lshlrev_b32_e32 v158, 1, v34
	v_lshlrev_b64 v[18:19], 8, v[18:19]
	s_addc_u32 s17, s15, s17
	v_lshlrev_b64 v[26:27], 8, v[26:27]
	v_lshl_add_u64 v[2:3], v[2:3], 0, v[158:159]
	v_lshl_add_u64 v[6:7], v[4:5], 0, v[158:159]
	v_lshl_add_u64 v[10:11], v[10:11], 0, v[158:159]
	v_lshl_add_u64 v[14:15], v[12:13], 0, v[158:159]
	v_lshl_add_u64 v[20:21], s[12:13], 0, v[18:19]
	v_lshlrev_b32_e32 v158, 1, v22
	v_lshl_add_u64 v[18:19], s[16:17], 0, v[18:19]
	v_lshl_add_u64 v[28:29], s[12:13], 0, v[26:27]
	v_lshl_add_u64 v[26:27], s[16:17], 0, v[26:27]
	v_lshl_add_u64 v[20:21], v[20:21], 0, v[158:159]
	v_lshl_add_u64 v[22:23], v[18:19], 0, v[158:159]
	v_lshl_add_u64 v[28:29], v[28:29], 0, v[158:159]
	v_lshl_add_u64 v[30:31], v[26:27], 0, v[158:159]
	global_load_dwordx4 v[2:5], v[2:3], off
	s_nop 0
	global_load_dwordx4 v[6:9], v[6:7], off
	s_nop 0
	global_load_dwordx4 v[10:13], v[10:11], off
	s_nop 0
	global_load_dwordx4 v[14:17], v[14:15], off
	s_nop 0
	global_load_dwordx4 v[18:21], v[20:21], off
	s_nop 0
	global_load_dwordx4 v[22:25], v[22:23], off
	s_nop 0
	global_load_dwordx4 v[26:29], v[28:29], off
	s_nop 0
	global_load_dwordx4 v[30:33], v[30:31], off
	s_movk_i32 s16, 0x90
	v_mul_lo_u32 v37, v102, s16
	v_add_u32_e32 v54, 0, v37
	v_lshlrev_b32_e32 v37, 4, v35
	v_and_b32_e32 v55, 0x70, v37
	v_mul_lo_u32 v37, v104, s16
	v_add_u32_e32 v56, 0, v37
	v_bitop3_b32 v37, v36, v106, 56 bitop3:0x6c
	s_add_u32 s30, s0, 4.0
	v_and_b32_e32 v53, 15, v35
	s_movk_i32 s12, 0x880
	v_lshlrev_b32_e32 v59, 1, v37
	v_bitop3_b32 v37, v108, v36, 56 bitop3:0x78
	s_addc_u32 s31, s1, 0
	s_ashr_i32 s0, s36, 2
	v_mad_u32_u24 v58, v53, s12, 0
	v_lshlrev_b32_e32 v60, 1, v37
	v_bitop3_b32 v37, v110, v36, 56 bitop3:0x78
	v_bitop3_b32 v36, v112, v36, 56 bitop3:0x78
	s_and_b32 s12, s0, 0xffffffc0
	v_lshlrev_b32_e32 v62, 1, v36
	v_or_b32_e32 v36, s12, v53
	v_lshlrev_b32_e32 v61, 1, v37
	v_ashrrev_i32_e32 v37, 31, v36
	v_bfe_u32 v57, v35, 4, 2
	v_lshlrev_b64 v[38:39], 6, v[36:37]
	v_or_b32_e32 v40, 16, v36
	v_or_b32_e32 v44, 32, v36
	v_or_b32_e32 v48, 48, v36
	v_mul_lo_u32 v36, v36, s27
	v_lshlrev_b32_e32 v63, 3, v57
	v_add_u32_e32 v64, 0, v36
	v_and_b32_e32 v36, 8, v35
	s_movk_i32 s13, 0x60
	v_bitop3_b32 v72, v63, v36, 32 bitop3:0x36
	v_bitop3_b32 v76, v63, v36, 64 bitop3:0x36
	v_or_b32_e32 v79, 0x60, v63
	v_bitop3_b32 v36, v63, v36, s13 bitop3:0x36
	v_lshlrev_b32_e32 v80, 1, v36
	v_bitop3_b32 v36, v40, v79, 24 bitop3:0x6c
	v_ashrrev_i32_e32 v41, 31, v40
	v_ashrrev_i32_e32 v45, 31, v44
; #define LAS __attribute__((address_space(3)))
; __device__ __forceinline__ void ret_out_item(const Ctx& X, const bf16* H, bf16* Y, int l, int it, RetOutRegs& R, bool has_next) {
;     const int b = it / 384, head = (it / 64) % 6, n = it % 64; const size_t m0 = (size_t)(b * SEQ + n * RCH);
;     const bf16* St = (const bf16*)(X.ws + WS_SRT);
;     const lptr Q = X.lds + R3_Q, K = X.lds + R3_K, VT = X.lds + R3_VT, AM = X.lds + R3_AM; LAS float* red = (LAS float*)(X.lds + R3_RED);
;     const int fr = X.lane & 15, fq = X.lane >> 4, tbq = X.wave & 3, vh = X.wave >> 2; const int ycol = 768 + head * 128;
;     const float l2f = __log2f(1.0f - exp2f(-5.0f - (float)head)), l2b = __log2f(1.0f - exp2f(-5.0f - (float)(5 - head)));
;     const int chain = (b * 6 + head) * 2;
; #pragma unroll
;     for (int p = 0; p < 2; ++p) { const int idx = X.tid + NTHR * p, row = idx >> 3, c8 = idx & 7; *(LAS v4u*)(Q + row * 144 + c8 * 16) = R.q[p]; *(LAS v4u*)(K + row * 144 + c8 * 16) = R.k[p]; }
; #pragma unroll
;     for (int p = 0; p < 4; ++p) { const int idx = X.tid + NTHR * p, row = idx >> 4, c8 = idx & 15; const v4u w = R.v[p];
;         LAS unsigned short* d = (LAS unsigned short*)(VT + (8 * c8) * 272 + (row ^ (8 * (c8 & 7))) * 2);
;         d[0] = (unsigned short)w.x; d[136] = (unsigned short)(w.x >> 16); d[272] = (unsigned short)w.y; d[408] = (unsigned short)(w.y >> 16);
;         d[544] = (unsigned short)w.z; d[680] = (unsigned short)(w.z >> 16); d[816] = (unsigned short)w.w; d[952] = (unsigned short)(w.w >> 16); }
;     __builtin_amdgcn_sched_barrier(0);
;     if (has_next) ret_out_load(X, H, it + X.G, R);
	v_ashrrev_i32_e32 v49, 31, v48
	v_lshlrev_b32_e32 v37, 2, v57
	v_and_or_b32 v116, s0, 48, v53
	v_or_b32_e32 v71, 32, v63
	v_or_b32_e32 v75, 64, v63
	v_lshlrev_b32_e32 v81, 1, v36
	v_bitop3_b32 v36, v44, v79, 40 bitop3:0x6c
	s_andn2_b32 s36, s36, 63
	v_lshlrev_b64 v[42:43], 6, v[40:41]
	v_lshlrev_b64 v[46:47], 6, v[44:45]
	v_lshlrev_b64 v[50:51], 6, v[48:49]
	v_or_b32_e32 v114, s12, v37
	v_or_b32_e32 v118, 64, v116
	s_add_i32 s12, 0, 0x1a000
	v_lshlrev_b32_e32 v49, 2, v53
	v_bitop3_b32 v66, v40, v63, 24 bitop3:0x6c
	v_bitop3_b32 v68, v44, v63, 40 bitop3:0x6c
	v_bitop3_b32 v73, v40, v71, 24 bitop3:0x6c
	v_bitop3_b32 v74, v44, v71, 40 bitop3:0x6c
	v_bitop3_b32 v77, v40, v75, 24 bitop3:0x6c
	v_bitop3_b32 v78, v44, v75, 40 bitop3:0x6c
	v_lshlrev_b32_e32 v44, 1, v36
	v_bitop3_b32 v36, v48, v79, 56 bitop3:0x6c
	s_xor_b32 s37, s36, 0x100
	v_add_u32_e32 v40, 0x41, v116
	s_and_b32 s1, s0, -16
	v_bfi_b32 v41, -16, s0, v35
	v_add_u32_e32 v174, s12, v49
	v_bitop3_b32 v70, v48, v63, 56 bitop3:0x6c
	v_lshlrev_b32_e32 v176, 1, v71
	v_bitop3_b32 v71, v48, v71, 56 bitop3:0x6c
	v_lshlrev_b32_e32 v177, 1, v75
	v_bitop3_b32 v75, v48, v75, 56 bitop3:0x6c
	v_lshlrev_b32_e32 v48, 1, v36
	v_add_u32_e32 v36, 1, v116
	s_add_i32 s13, s12, s36
	s_add_i32 s12, s12, s37
	v_cvt_f32_ubyte0_e32 v190, v40
	v_sub_u32_e32 v40, 0x80, v118
	s_lshr_b32 s0, s0, 4
	v_and_b32_e32 v52, 63, v35
	v_readlane_b32 s17, v252, 10
	v_cvt_f32_ubyte0_e32 v180, v36
	v_sub_u32_e32 v36, 0x80, v116
	v_add_u32_e32 v184, s12, v49
	v_cvt_f32_ubyte0_e32 v191, v40
	s_add_i32 s12, s36, 0
	v_mul_lo_u32 v40, v108, s27
	s_mulk_i32 s0, 0x1100
	v_lshlrev_b32_e32 v178, 1, v79
	v_cvt_f32_ubyte0_e32 v181, v36
	v_lshlrev_b32_e32 v36, 2, v52
	s_add_i32 s12, s12, 0x1aa00
	v_add_u32_e32 v79, s17, v40
	v_mul_lo_u32 v40, v110, s27
	v_mov_b32_e32 v84, s0
	v_and_b32_e32 v119, 48, v35
	v_mul_lo_u32 v45, v41, s16
	v_add_u32_e32 v161, 0x1500, v114
	v_mov_b32_e32 v57, s17
	v_bitop3_b32 v35, v63, v35, 8 bitop3:0x78
	v_mad_u32_u24 v179, v116, s16, 0
	v_add_u32_e32 v182, s13, v36
	v_add_u32_e32 v192, s12, v36
	v_mul_lo_u32 v36, v106, s27
	v_add_u32_e32 v82, s17, v40
	v_mul_lo_u32 v40, v112, s27
	v_mad_u32_u24 v84, v53, s27, v84
	v_or_b32_e32 v38, v38, v63
	v_or_b32_e32 v42, v42, v63
	v_or_b32_e32 v46, v46, v63
	v_or_b32_e32 v50, v50, v63
	v_add_u32_e32 v45, 0, v45
	v_cmp_gt_u32_e64 s[40:41], 16, v52
	v_mad_u32_u24 v175, v116, s27, v57
	v_lshlrev_b32_e32 v35, 1, v35
	v_add_u32_e32 v65, 0x1100, v64
	v_lshlrev_b32_e32 v66, 1, v66
	v_add_u32_e32 v67, 0x2200, v64
	v_lshlrev_b32_e32 v68, 1, v68
	v_add_u32_e32 v69, 0x3300, v64
	v_lshlrev_b32_e32 v70, 1, v70
	v_lshlrev_b32_e32 v72, 1, v72
	v_lshlrev_b32_e32 v73, 1, v73
	v_lshlrev_b32_e32 v74, 1, v74
	v_lshlrev_b32_e32 v71, 1, v71
	v_lshlrev_b32_e32 v76, 1, v76
	v_lshlrev_b32_e32 v77, 1, v77
	v_lshlrev_b32_e32 v78, 1, v78
	v_lshlrev_b32_e32 v75, 1, v75
	v_add_u32_e32 v183, s13, v49
	v_lshlrev_b32_e32 v185, 1, v114
	v_mad_u32_u24 v189, v118, s27, v57
	v_add_u32_e32 v49, 0x2400, v179
	v_add_u32_e32 v52, s17, v36
	v_lshlrev_b32_e32 v57, 4, v53
	v_lshlrev_b32_e32 v36, 3, v53
	v_add_u32_e32 v83, s17, v40
	v_and_b32_e32 v40, 0x4c, v161
	v_add3_u32 v193, v84, v63, s17
	v_mul_u32_u24_e32 v63, 0x90, v53
	v_readlane_b32 s0, v252, 11
	v_sub_u32_e32 v53, v37, v53
	v_ashrrev_i32_e32 v115, 31, v114
	v_or_b32_e32 v186, 32, v185
	v_or_b32_e32 v187, 64, v185
	v_or_b32_e32 v188, 0x60, v185
	v_add3_u32 v199, v63, v119, s0
	v_subrev_u32_e32 v200, s1, v53
	v_sub_u32_e32 v201, v41, v37
	v_add_u32_e32 v202, v54, v55
	v_add_u32_e32 v203, v56, v55
	v_add_u32_e32 v204, v58, v59
	v_add_u32_e32 v205, v58, v60
	v_add_u32_e32 v206, v58, v61
	v_add_u32_e32 v207, v58, v62
	v_lshlrev_b32_e32 v120, 1, v34
	v_lshlrev_b64 v[122:123], 1, v[38:39]
	v_lshlrev_b64 v[124:125], 1, v[42:43]
	v_lshlrev_b64 v[126:127], 1, v[46:47]
	v_lshlrev_b64 v[128:129], 1, v[50:51]
	v_add_u32_e32 v208, v45, v119
	v_lshlrev_b32_e32 v130, 1, v40
	s_lshl_b64 s[16:17], s[34:35], 2
	v_add_u32_e32 v209, v49, v119
	v_add_u32_e32 v210, v52, v57
	v_lshlrev_b32_e32 v158, 1, v36
	v_add_u32_e32 v211, v79, v57
	v_add_u32_e32 v212, v82, v57
	v_add_u32_e32 v213, v83, v57
	v_add_u32_e32 v214, v64, v35
	v_add_u32_e32 v215, v65, v66
	v_add_u32_e32 v216, v67, v68
	v_add_u32_e32 v217, v69, v70
	v_add_u32_e32 v218, v64, v72
	v_add_u32_e32 v219, v65, v73
	v_add_u32_e32 v220, v67, v74
	v_add_u32_e32 v221, v69, v71
	v_add_u32_e32 v222, v64, v76
	v_add_u32_e32 v223, v65, v77
	v_add_u32_e32 v224, v67, v78
	v_add_u32_e32 v225, v69, v75
	v_add_u32_e32 v226, v64, v80
	v_add_u32_e32 v227, v65, v81
	v_add_u32_e32 v228, v67, v44
	v_add_u32_e32 v229, v69, v48
	s_mov_b32 s0, s2
	s_waitcnt vmcnt(0)
	s_branch .LBB0_569

; #define LAS __attribute__((address_space(3)))
; __device__ __forceinline__ void ret_out_item(const Ctx& X, const bf16* H, bf16* Y, int l, int it, RetOutRegs& R, bool has_next) {
;     ...
; #pragma unroll
;     for (int p = 0; p < 2; ++p) { const int idx = X.tid + NTHR * p, row = idx >> 3, c8 = idx & 7; *(LAS v4u*)(Q + row * 144 + c8 * 16) = R.q[p]; *(LAS v4u*)(K + row * 144 + c8 * 16) = R.k[p]; }
; #pragma unroll
;     for (int p = 0; p < 4; ++p) { const int idx = X.tid + NTHR * p, row = idx >> 4, c8 = idx & 15; const v4u w = R.v[p];
;         LAS unsigned short* d = (LAS unsigned short*)(VT + (8 * c8) * 272 + (row ^ (8 * (c8 & 7))) * 2);
;         d[0] = (unsigned short)w.x; d[136] = (unsigned short)(w.x >> 16); d[272] = (unsigned short)w.y; d[408] = (unsigned short)(w.y >> 16);
;         d[544] = (unsigned short)w.z; d[680] = (unsigned short)(w.z >> 16); d[816] = (unsigned short)w.w; d[952] = (unsigned short)(w.w >> 16); }
;     __builtin_amdgcn_sched_barrier(0);
;     if (has_next) ret_out_load(X, H, it + X.G, R);
.LBB0_569:
	s_add_i32 s38, s0, s87
	s_cmpk_gt_i32 s38, 0x2ff
	s_cselect_b64 s[18:19], -1, 0
	s_waitcnt vmcnt(4)
	ds_write_b128 v202, v[30:33]
	ds_write_b128 v202, v[26:29] offset:18432
	ds_write_b128 v203, v[22:25]
	ds_write_b128 v203, v[18:21] offset:18432
	ds_write_b16 v204, v14 offset:36864
	ds_write_b16_d16_hi v204, v14 offset:37136
	ds_write_b16 v204, v15 offset:37408
	ds_write_b16_d16_hi v204, v15 offset:37680
	ds_write_b16 v204, v16 offset:37952
	ds_write_b16_d16_hi v204, v16 offset:38224
	ds_write_b16 v204, v17 offset:38496
	ds_write_b16_d16_hi v204, v17 offset:38768
	ds_write_b16 v205, v10 offset:36864
	ds_write_b16_d16_hi v205, v10 offset:37136
	ds_write_b16 v205, v11 offset:37408
	ds_write_b16_d16_hi v205, v11 offset:37680
	ds_write_b16 v205, v12 offset:37952
	ds_write_b16_d16_hi v205, v12 offset:38224
	ds_write_b16 v205, v13 offset:38496
	ds_write_b16_d16_hi v205, v13 offset:38768
	ds_write_b16 v206, v6 offset:36864
	ds_write_b16_d16_hi v206, v6 offset:37136
	ds_write_b16 v206, v7 offset:37408
	ds_write_b16_d16_hi v206, v7 offset:37680
	ds_write_b16 v206, v8 offset:37952
	ds_write_b16_d16_hi v206, v8 offset:38224
	ds_write_b16 v206, v9 offset:38496
	ds_write_b16_d16_hi v206, v9 offset:38768
	ds_write_b16 v207, v2 offset:36864
	ds_write_b16_d16_hi v207, v2 offset:37136
	ds_write_b16 v207, v3 offset:37408
	ds_write_b16_d16_hi v207, v3 offset:37680
	ds_write_b16 v207, v4 offset:37952
	ds_write_b16_d16_hi v207, v4 offset:38224
	ds_write_b16 v207, v5 offset:38496
	ds_write_b16_d16_hi v207, v5 offset:38768
	s_and_b64 vcc, exec, s[18:19]
	s_cbranch_vccnz .LBB0_571
	s_mul_hi_i32 s1, s38, 0x2aaaaaab
	s_lshr_b32 s12, s1, 31
	s_lshr_b32 s1, s1, 6
	s_add_i32 s1, s1, s12
	s_ashr_i32 s12, s38, 31
	s_lshr_b32 s12, s12, 26
	s_add_i32 s12, s38, s12
	s_ashr_i32 s13, s12, 6
	s_mul_hi_i32 s22, s13, 0x2aaaaaab
	s_lshr_b32 s23, s22, 31
	s_add_i32 s22, s22, s23
	s_and_b32 s12, s12, 0x1ffffc0
	s_mul_i32 s22, s22, 6
	s_sub_i32 s12, s38, s12
	s_sub_i32 s39, s13, s22
	s_lshl_b32 s1, s1, 13
	s_lshl_b32 s12, s12, 7
	s_add_i32 s12, s1, s12
	s_lshl_b32 s1, s39, 6
	s_add_i32 s22, s1, 0xf00
	s_lshr_b32 s34, s22, 7
	s_ashr_i32 s13, s12, 31
	s_lshl_b64 s[22:23], s[34:35], 22
	s_add_u32 s22, s14, s22
	s_addc_u32 s23, s15, s23
	s_add_i32 s24, s1, 0x1080
	s_lshr_b32 s34, s24, 7
	s_lshl_b64 s[24:25], s[34:35], 22
	s_add_u32 s24, s14, s24
	v_lshl_add_u64 v[2:3], s[12:13], 0, v[102:103]
	s_addc_u32 s25, s15, s25
	v_lshlrev_b64 v[2:3], 8, v[2:3]
	v_and_or_b32 v6, s1, 64, v117
	v_lshl_add_u64 v[4:5], s[22:23], 0, v[2:3]
	v_lshlrev_b32_e32 v6, 1, v6
	v_mov_b32_e32 v7, v159
	v_lshl_add_u64 v[2:3], s[24:25], 0, v[2:3]
	v_lshl_add_u64 v[4:5], v[4:5], 0, v[6:7]
	v_lshl_add_u64 v[2:3], v[2:3], 0, v[6:7]
	global_load_dwordx4 v[30:33], v[4:5], off
	global_load_dwordx4 v[26:29], v[2:3], off
	v_lshl_add_u64 v[2:3], s[12:13], 0, v[104:105]
	v_lshlrev_b64 v[2:3], 8, v[2:3]
	v_lshl_add_u64 v[4:5], s[22:23], 0, v[2:3]
	v_lshl_add_u64 v[2:3], s[24:25], 0, v[2:3]
	s_add_i32 s34, s39, 36
	v_lshl_add_u64 v[4:5], v[4:5], 0, v[6:7]
	v_lshl_add_u64 v[2:3], v[2:3], 0, v[6:7]
	s_lshl_b64 s[22:23], s[34:35], 22
	global_load_dwordx4 v[22:25], v[4:5], off
	global_load_dwordx4 v[18:21], v[2:3], off
	s_add_u32 s22, s14, s22
	v_lshl_add_u64 v[2:3], s[12:13], 0, v[106:107]
	v_lshl_add_u64 v[4:5], s[12:13], 0, v[108:109]
	s_addc_u32 s23, s15, s23
	v_lshlrev_b64 v[2:3], 8, v[2:3]
	v_lshlrev_b64 v[4:5], 8, v[4:5]
	v_lshl_add_u64 v[2:3], s[22:23], 0, v[2:3]
	v_mov_b32_e32 v121, v159
	v_lshl_add_u64 v[4:5], s[22:23], 0, v[4:5]
	v_lshl_add_u64 v[2:3], v[2:3], 0, v[120:121]
	v_lshl_add_u64 v[4:5], v[4:5], 0, v[120:121]
	global_load_dwordx4 v[14:17], v[2:3], off
	global_load_dwordx4 v[10:13], v[4:5], off
	v_lshl_add_u64 v[2:3], s[12:13], 0, v[110:111]
	v_lshl_add_u64 v[4:5], s[12:13], 0, v[112:113]
	v_lshlrev_b64 v[2:3], 8, v[2:3]
	v_lshlrev_b64 v[4:5], 8, v[4:5]
	v_lshl_add_u64 v[2:3], s[22:23], 0, v[2:3]
	v_lshl_add_u64 v[4:5], s[22:23], 0, v[4:5]
	v_lshl_add_u64 v[2:3], v[2:3], 0, v[120:121]
	v_lshl_add_u64 v[4:5], v[4:5], 0, v[120:121]
	global_load_dwordx4 v[6:9], v[2:3], off
	s_nop 0
	global_load_dwordx4 v[2:5], v[4:5], off
